# K-loop: dropped the redundant lgkmcnt(0) wait after each section barrier (40 sites), on top of ring5+DPP
# speedup vs baseline: 1.0017x; 1.0017x over previous
.LBB0_675:
	s_ashr_i32 s21, s20, 31
	s_lshl_b64 s[8:9], s[20:21], 19
	s_add_u32 s26, s36, s8
	s_addc_u32 s27, s37, s9
	s_and_b64 s[8:9], s[6:7], exec
	s_cselect_b32 s21, s27, s69
	s_cselect_b32 s31, s26, s68
	s_ashr_i32 s11, s10, 31
	s_lshl_b64 s[8:9], s[10:11], 19
	s_add_u32 s52, s40, s8
	s_addc_u32 s53, s60, s9
	s_and_b64 s[8:9], s[6:7], exec
	s_cselect_b32 s11, s53, s57
	s_cselect_b32 s82, s52, s56
	s_add_u32 s8, s68, 0x40080
	s_addc_u32 s9, s69, 0
	s_add_u32 s83, s56, 0x100
	s_addc_u32 s84, s57, 0
	s_mov_b32 s85, -2
	s_add_u32 s56, s8, 0xfffc0080
	s_addc_u32 s57, s9, -1
	s_add_i32 s64, 0, 0x10000
	s_cmp_eq_u32 s85, 12
	s_cselect_b32 s69, s21, s57
	s_cselect_b32 s68, s31, s56
	v_add_u32_e32 v160, s64, v163
	s_cselect_b32 s57, s11, s84
	s_cselect_b32 s56, s82, s83
	s_add_i32 s86, 0, 0x14000
	ds_read_b128 v[148:151], v160
	ds_read_b128 v[152:155], v160 offset:1024
	ds_read_b128 v[156:159], v160 offset:2048
	ds_read_b128 v[166:169], v160 offset:3072
	v_add_u32_e32 v160, s86, v163
	ds_read_b128 v[170:173], v160
	ds_read_b128 v[174:177], v160 offset:1024
	ds_read_b128 v[178:181], v160 offset:2048
	ds_read_b128 v[182:185], v160 offset:3072
	v_lshl_add_u64 v[160:161], s[8:9], 0, v[144:145]
	s_add_i32 m0, s72, 0xc000
	ds_read_b128 v[186:189], v165
	ds_read_b128 v[190:193], v165 offset:1024
	ds_read_b128 v[194:197], v165 offset:2048
	ds_read_b128 v[198:201], v165 offset:3072
	ds_read_b128 v[202:205], v165 offset:4096
	ds_read_b128 v[206:209], v165 offset:5120
	ds_read_b128 v[222:225], v165 offset:6144
	ds_read_b128 v[226:229], v165 offset:7168
	global_load_lds_dwordx4 v[160:161], off
	v_lshl_add_u64 v[160:161], s[8:9], 0, v[146:147]
	s_add_i32 m0, s72, 0xe000
	s_nop 0
	global_load_lds_dwordx4 v[160:161], off
	s_waitcnt vmcnt(8)
	s_waitcnt lgkmcnt(0)
	s_barrier
	s_setprio 3
	v_mfma_f32_16x16x32_bf16 v[70:73], v[148:151], v[186:189], 0
	v_mfma_f32_16x16x32_bf16 v[66:69], v[156:159], v[186:189], 0
	v_mfma_f32_16x16x32_bf16 v[54:57], v[148:151], v[194:197], 0
	v_mfma_f32_16x16x32_bf16 v[50:53], v[156:159], v[194:197], 0
	v_mfma_f32_16x16x32_bf16 v[46:49], v[148:151], v[202:205], 0
	v_mfma_f32_16x16x32_bf16 v[42:45], v[156:159], v[202:205], 0
	v_mfma_f32_16x16x32_bf16 v[38:41], v[148:151], v[222:225], 0
	v_mfma_f32_16x16x32_bf16 v[34:37], v[156:159], v[222:225], 0
	v_mfma_f32_16x16x32_bf16 v[70:73], v[152:155], v[190:193], v[70:73]
	v_mfma_f32_16x16x32_bf16 v[66:69], v[166:169], v[190:193], v[66:69]
	v_mfma_f32_16x16x32_bf16 v[54:57], v[152:155], v[198:201], v[54:57]
	v_mfma_f32_16x16x32_bf16 v[50:53], v[166:169], v[198:201], v[50:53]
	v_mfma_f32_16x16x32_bf16 v[46:49], v[152:155], v[206:209], v[46:49]
	v_mfma_f32_16x16x32_bf16 v[42:45], v[166:169], v[206:209], v[42:45]
	v_mfma_f32_16x16x32_bf16 v[38:41], v[152:155], v[226:229], v[38:41]
	v_mfma_f32_16x16x32_bf16 v[34:37], v[166:169], v[226:229], v[34:37]
	v_mfma_f32_16x16x32_bf16 v[126:129], v[170:173], v[186:189], 0
	v_mfma_f32_16x16x32_bf16 v[122:125], v[178:181], v[186:189], 0
	v_mfma_f32_16x16x32_bf16 v[118:121], v[170:173], v[194:197], 0
	v_mfma_f32_16x16x32_bf16 v[114:117], v[178:181], v[194:197], 0
	v_mfma_f32_16x16x32_bf16 v[110:113], v[170:173], v[202:205], 0
	v_mfma_f32_16x16x32_bf16 v[106:109], v[178:181], v[202:205], 0
	v_mfma_f32_16x16x32_bf16 v[102:105], v[170:173], v[222:225], 0
	v_mfma_f32_16x16x32_bf16 v[98:101], v[178:181], v[222:225], 0
	v_mfma_f32_16x16x32_bf16 v[126:129], v[174:177], v[190:193], v[126:129]
	v_mfma_f32_16x16x32_bf16 v[122:125], v[182:185], v[190:193], v[122:125]
	v_mfma_f32_16x16x32_bf16 v[118:121], v[174:177], v[198:201], v[118:121]
	v_mfma_f32_16x16x32_bf16 v[114:117], v[182:185], v[198:201], v[114:117]
	v_mfma_f32_16x16x32_bf16 v[110:113], v[174:177], v[206:209], v[110:113]
	v_mfma_f32_16x16x32_bf16 v[106:109], v[182:185], v[206:209], v[106:109]
	v_mfma_f32_16x16x32_bf16 v[102:105], v[174:177], v[226:229], v[102:105]
	v_mfma_f32_16x16x32_bf16 v[98:101], v[182:185], v[226:229], v[98:101]
	s_setprio 0
	s_barrier
	s_add_i32 s64, s64, s63
	v_lshl_add_u64 v[160:161], s[56:57], 0, v[0:1]
	s_mov_b32 m0, s64
	ds_read_b128 v[186:189], v165 offset:16384
	ds_read_b128 v[190:193], v165 offset:17408
	ds_read_b128 v[194:197], v165 offset:18432
	ds_read_b128 v[198:201], v165 offset:19456
	ds_read_b128 v[202:205], v165 offset:20480
	ds_read_b128 v[206:209], v165 offset:21504
	ds_read_b128 v[222:225], v165 offset:22528
	ds_read_b128 v[226:229], v165 offset:23552
	global_load_lds_dwordx4 v[160:161], off
	s_add_i32 m0, s64, 0x2000
	s_add_u32 s64, s56, 0x40000
	v_lshl_add_u64 v[210:211], s[56:57], 0, v[134:135]
	s_addc_u32 s65, s57, 0
	s_add_i32 s86, s86, s63
	global_load_lds_dwordx4 v[210:211], off
	v_lshl_add_u64 v[230:231], s[64:65], 0, v[0:1]
	s_mov_b32 m0, s86
	v_lshl_add_u64 v[232:233], s[68:69], 0, v[136:137]
	global_load_lds_dwordx4 v[230:231], off
	v_lshl_add_u64 v[230:231], s[64:65], 0, v[134:135]
	s_add_i32 m0, s86, 0x2000
	s_nop 0
	global_load_lds_dwordx4 v[230:231], off
	v_lshl_add_u64 v[230:231], s[68:69], 0, v[138:139]
	s_mov_b32 m0, s72
	s_nop 0
	global_load_lds_dwordx4 v[230:231], off
	s_mov_b32 m0, s73
	s_nop 0
	global_load_lds_dwordx4 v[232:233], off
	s_waitcnt vmcnt(8)
	s_waitcnt lgkmcnt(0)
	s_barrier
	s_setprio 3
	v_mfma_f32_16x16x32_bf16 v[30:33], v[148:151], v[186:189], 0
	v_mfma_f32_16x16x32_bf16 v[26:29], v[156:159], v[186:189], 0
	v_mfma_f32_16x16x32_bf16 v[22:25], v[148:151], v[194:197], 0
	v_mfma_f32_16x16x32_bf16 v[18:21], v[156:159], v[194:197], 0
	v_mfma_f32_16x16x32_bf16 v[14:17], v[148:151], v[202:205], 0
	v_mfma_f32_16x16x32_bf16 v[10:13], v[156:159], v[202:205], 0
	v_mfma_f32_16x16x32_bf16 v[6:9], v[148:151], v[222:225], 0
	v_mfma_f32_16x16x32_bf16 v[2:5], v[156:159], v[222:225], 0
	v_mfma_f32_16x16x32_bf16 v[30:33], v[152:155], v[190:193], v[30:33]
	v_mfma_f32_16x16x32_bf16 v[26:29], v[166:169], v[190:193], v[26:29]
	v_mfma_f32_16x16x32_bf16 v[22:25], v[152:155], v[198:201], v[22:25]
	v_mfma_f32_16x16x32_bf16 v[18:21], v[166:169], v[198:201], v[18:21]
	v_mfma_f32_16x16x32_bf16 v[14:17], v[152:155], v[206:209], v[14:17]
	v_mfma_f32_16x16x32_bf16 v[10:13], v[166:169], v[206:209], v[10:13]
	v_mfma_f32_16x16x32_bf16 v[6:9], v[152:155], v[226:229], v[6:9]
	v_mfma_f32_16x16x32_bf16 v[2:5], v[166:169], v[226:229], v[2:5]
	v_mfma_f32_16x16x32_bf16 v[94:97], v[170:173], v[186:189], 0
	v_mfma_f32_16x16x32_bf16 v[90:93], v[178:181], v[186:189], 0
	v_mfma_f32_16x16x32_bf16 v[86:89], v[170:173], v[194:197], 0
	v_mfma_f32_16x16x32_bf16 v[82:85], v[178:181], v[194:197], 0
	v_mfma_f32_16x16x32_bf16 v[78:81], v[170:173], v[202:205], 0
	v_mfma_f32_16x16x32_bf16 v[74:77], v[178:181], v[202:205], 0
	v_mfma_f32_16x16x32_bf16 v[62:65], v[170:173], v[222:225], 0
	v_mfma_f32_16x16x32_bf16 v[58:61], v[178:181], v[222:225], 0
	v_mfma_f32_16x16x32_bf16 v[94:97], v[174:177], v[190:193], v[94:97]
	v_mfma_f32_16x16x32_bf16 v[90:93], v[182:185], v[190:193], v[90:93]
	v_mfma_f32_16x16x32_bf16 v[86:89], v[174:177], v[198:201], v[86:89]
	v_mfma_f32_16x16x32_bf16 v[82:85], v[182:185], v[198:201], v[82:85]
	v_mfma_f32_16x16x32_bf16 v[78:81], v[174:177], v[206:209], v[78:81]
	v_mfma_f32_16x16x32_bf16 v[74:77], v[182:185], v[206:209], v[74:77]
	v_mfma_f32_16x16x32_bf16 v[62:65], v[174:177], v[226:229], v[62:65]
	v_mfma_f32_16x16x32_bf16 v[58:61], v[182:185], v[226:229], v[58:61]
	s_setprio 0
	s_barrier
	s_add_i32 s86, 0, 0x18000
	s_add_i32 s87, 0, 0x1c000
	v_add_u32_e32 v166, s86, v163
	v_add_u32_e32 v182, s87, v163
	ds_read_b128 v[148:151], v166
	ds_read_b128 v[152:155], v166 offset:1024
	ds_read_b128 v[156:159], v166 offset:2048
	ds_read_b128 v[166:169], v166 offset:3072
	ds_read_b128 v[170:173], v182
	ds_read_b128 v[174:177], v182 offset:1024
	ds_read_b128 v[178:181], v182 offset:2048
	ds_read_b128 v[182:185], v182 offset:3072
	s_add_u32 s64, s68, 0x40000
	s_addc_u32 s65, s69, 0
	s_mov_b32 m0, s74
	v_lshl_add_u64 v[234:235], s[64:65], 0, v[138:139]
	ds_read_b128 v[186:189], v165 offset:32768
	ds_read_b128 v[190:193], v165 offset:33792
	ds_read_b128 v[194:197], v165 offset:34816
	ds_read_b128 v[198:201], v165 offset:35840
	ds_read_b128 v[202:205], v165 offset:36864
	ds_read_b128 v[206:209], v165 offset:37888
	ds_read_b128 v[222:225], v165 offset:38912
	ds_read_b128 v[226:229], v165 offset:39936
	global_load_lds_dwordx4 v[234:235], off
	v_lshl_add_u64 v[234:235], s[64:65], 0, v[136:137]
	s_mov_b32 m0, s75
	s_nop 0
	global_load_lds_dwordx4 v[234:235], off
	s_waitcnt vmcnt(8)
	s_waitcnt lgkmcnt(0)
	s_barrier
	s_setprio 3
	v_mfma_f32_16x16x32_bf16 v[70:73], v[148:151], v[186:189], v[70:73]
	v_mfma_f32_16x16x32_bf16 v[66:69], v[156:159], v[186:189], v[66:69]
	v_mfma_f32_16x16x32_bf16 v[54:57], v[148:151], v[194:197], v[54:57]
	v_mfma_f32_16x16x32_bf16 v[50:53], v[156:159], v[194:197], v[50:53]
	v_mfma_f32_16x16x32_bf16 v[46:49], v[148:151], v[202:205], v[46:49]
	v_mfma_f32_16x16x32_bf16 v[42:45], v[156:159], v[202:205], v[42:45]
	v_mfma_f32_16x16x32_bf16 v[38:41], v[148:151], v[222:225], v[38:41]
	v_mfma_f32_16x16x32_bf16 v[34:37], v[156:159], v[222:225], v[34:37]
	v_mfma_f32_16x16x32_bf16 v[70:73], v[152:155], v[190:193], v[70:73]
	v_mfma_f32_16x16x32_bf16 v[66:69], v[166:169], v[190:193], v[66:69]
	v_mfma_f32_16x16x32_bf16 v[54:57], v[152:155], v[198:201], v[54:57]
	v_mfma_f32_16x16x32_bf16 v[50:53], v[166:169], v[198:201], v[50:53]
	v_mfma_f32_16x16x32_bf16 v[46:49], v[152:155], v[206:209], v[46:49]
	v_mfma_f32_16x16x32_bf16 v[42:45], v[166:169], v[206:209], v[42:45]
	v_mfma_f32_16x16x32_bf16 v[38:41], v[152:155], v[226:229], v[38:41]
	v_mfma_f32_16x16x32_bf16 v[34:37], v[166:169], v[226:229], v[34:37]
	v_mfma_f32_16x16x32_bf16 v[126:129], v[170:173], v[186:189], v[126:129]
	v_mfma_f32_16x16x32_bf16 v[122:125], v[178:181], v[186:189], v[122:125]
	v_mfma_f32_16x16x32_bf16 v[118:121], v[170:173], v[194:197], v[118:121]
	v_mfma_f32_16x16x32_bf16 v[114:117], v[178:181], v[194:197], v[114:117]
	v_mfma_f32_16x16x32_bf16 v[110:113], v[170:173], v[202:205], v[110:113]
	v_mfma_f32_16x16x32_bf16 v[106:109], v[178:181], v[202:205], v[106:109]
	v_mfma_f32_16x16x32_bf16 v[102:105], v[170:173], v[222:225], v[102:105]
	v_mfma_f32_16x16x32_bf16 v[98:101], v[178:181], v[222:225], v[98:101]
	v_mfma_f32_16x16x32_bf16 v[126:129], v[174:177], v[190:193], v[126:129]
	v_mfma_f32_16x16x32_bf16 v[122:125], v[182:185], v[190:193], v[122:125]
	v_mfma_f32_16x16x32_bf16 v[118:121], v[174:177], v[198:201], v[118:121]
	v_mfma_f32_16x16x32_bf16 v[114:117], v[182:185], v[198:201], v[114:117]
	v_mfma_f32_16x16x32_bf16 v[110:113], v[174:177], v[206:209], v[110:113]
	v_mfma_f32_16x16x32_bf16 v[106:109], v[182:185], v[206:209], v[106:109]
	v_mfma_f32_16x16x32_bf16 v[102:105], v[174:177], v[226:229], v[102:105]
	v_mfma_f32_16x16x32_bf16 v[98:101], v[182:185], v[226:229], v[98:101]
	s_setprio 0
	s_barrier
	s_add_i32 s64, s86, s63
	v_lshl_add_u64 v[160:161], v[160:161], 0, s[48:49]
	s_mov_b32 m0, s64
	ds_read_b128 v[186:189], v165 offset:49152
	ds_read_b128 v[190:193], v165 offset:50176
	ds_read_b128 v[194:197], v165 offset:51200
	ds_read_b128 v[198:201], v165 offset:52224
	ds_read_b128 v[202:205], v165 offset:53248
	ds_read_b128 v[206:209], v165 offset:54272
	ds_read_b128 v[222:225], v165 offset:55296
	ds_read_b128 v[226:229], v165 offset:56320
	global_load_lds_dwordx4 v[160:161], off
	s_add_i32 m0, s64, 0x2000
	s_add_u32 s56, s56, 0x40080
	v_lshl_add_u64 v[160:161], v[210:211], 0, s[48:49]
	s_addc_u32 s57, s57, 0
	s_add_i32 s64, s87, s63
	global_load_lds_dwordx4 v[160:161], off
	v_lshl_add_u64 v[160:161], s[56:57], 0, v[0:1]
	s_mov_b32 m0, s64
	s_nop 0
	global_load_lds_dwordx4 v[160:161], off
	v_lshl_add_u64 v[160:161], s[56:57], 0, v[134:135]
	s_add_i32 m0, s64, 0x2000
	s_nop 0
	global_load_lds_dwordx4 v[160:161], off
	v_lshl_add_u64 v[160:161], v[230:231], 0, s[48:49]
	s_mov_b32 m0, s78
	s_nop 0
	global_load_lds_dwordx4 v[160:161], off
	v_lshl_add_u64 v[160:161], v[232:233], 0, s[48:49]
	s_mov_b32 m0, s79
	s_nop 0
	global_load_lds_dwordx4 v[160:161], off
	s_waitcnt vmcnt(8)
	s_waitcnt lgkmcnt(0)
	s_barrier
	s_setprio 3
	v_mfma_f32_16x16x32_bf16 v[30:33], v[148:151], v[186:189], v[30:33]
	v_mfma_f32_16x16x32_bf16 v[26:29], v[156:159], v[186:189], v[26:29]
	v_mfma_f32_16x16x32_bf16 v[22:25], v[148:151], v[194:197], v[22:25]
	v_mfma_f32_16x16x32_bf16 v[18:21], v[156:159], v[194:197], v[18:21]
	v_mfma_f32_16x16x32_bf16 v[14:17], v[148:151], v[202:205], v[14:17]
	v_mfma_f32_16x16x32_bf16 v[10:13], v[156:159], v[202:205], v[10:13]
	v_mfma_f32_16x16x32_bf16 v[6:9], v[148:151], v[222:225], v[6:9]
	v_mfma_f32_16x16x32_bf16 v[2:5], v[156:159], v[222:225], v[2:5]
	v_mfma_f32_16x16x32_bf16 v[30:33], v[152:155], v[190:193], v[30:33]
	v_mfma_f32_16x16x32_bf16 v[26:29], v[166:169], v[190:193], v[26:29]
	v_mfma_f32_16x16x32_bf16 v[22:25], v[152:155], v[198:201], v[22:25]
	v_mfma_f32_16x16x32_bf16 v[18:21], v[166:169], v[198:201], v[18:21]
	v_mfma_f32_16x16x32_bf16 v[14:17], v[152:155], v[206:209], v[14:17]
	v_mfma_f32_16x16x32_bf16 v[10:13], v[166:169], v[206:209], v[10:13]
	v_mfma_f32_16x16x32_bf16 v[6:9], v[152:155], v[226:229], v[6:9]
	v_mfma_f32_16x16x32_bf16 v[2:5], v[166:169], v[226:229], v[2:5]
	v_mfma_f32_16x16x32_bf16 v[94:97], v[170:173], v[186:189], v[94:97]
	v_mfma_f32_16x16x32_bf16 v[90:93], v[178:181], v[186:189], v[90:93]
	v_mfma_f32_16x16x32_bf16 v[86:89], v[170:173], v[194:197], v[86:89]
	v_mfma_f32_16x16x32_bf16 v[82:85], v[178:181], v[194:197], v[82:85]
	v_mfma_f32_16x16x32_bf16 v[78:81], v[170:173], v[202:205], v[78:81]
	v_mfma_f32_16x16x32_bf16 v[74:77], v[178:181], v[202:205], v[74:77]
	v_mfma_f32_16x16x32_bf16 v[62:65], v[170:173], v[222:225], v[62:65]
	v_mfma_f32_16x16x32_bf16 v[58:61], v[178:181], v[222:225], v[58:61]
	v_mfma_f32_16x16x32_bf16 v[94:97], v[174:177], v[190:193], v[94:97]
	v_mfma_f32_16x16x32_bf16 v[90:93], v[182:185], v[190:193], v[90:93]
	v_mfma_f32_16x16x32_bf16 v[86:89], v[174:177], v[198:201], v[86:89]
	v_mfma_f32_16x16x32_bf16 v[82:85], v[182:185], v[198:201], v[82:85]
	v_mfma_f32_16x16x32_bf16 v[78:81], v[174:177], v[206:209], v[78:81]
	v_mfma_f32_16x16x32_bf16 v[74:77], v[182:185], v[206:209], v[74:77]
	v_mfma_f32_16x16x32_bf16 v[62:65], v[174:177], v[226:229], v[62:65]
	v_mfma_f32_16x16x32_bf16 v[58:61], v[182:185], v[226:229], v[58:61]
	s_setprio 0
	s_barrier
	s_add_i32 s85, s85, 2
	s_add_u32 s8, s8, 0x100
	s_addc_u32 s9, s9, 0
	s_add_u32 s83, s83, 0x100
	s_addc_u32 s84, s84, 0
.LBB0_676:
	s_add_u32 s56, s8, 0xfffc0080
	s_addc_u32 s57, s9, -1
	s_add_i32 s64, 0, 0x10000
	s_cmp_eq_u32 s85, 12
	s_cselect_b32 s69, s21, s57
	s_cselect_b32 s68, s31, s56
	v_add_u32_e32 v160, s64, v163
	s_cselect_b32 s57, s11, s84
	s_cselect_b32 s56, s82, s83
	s_add_i32 s86, 0, 0x14000
	ds_read_b128 v[148:151], v160
	ds_read_b128 v[152:155], v160 offset:1024
	ds_read_b128 v[156:159], v160 offset:2048
	ds_read_b128 v[166:169], v160 offset:3072
	v_add_u32_e32 v160, s86, v163
	ds_read_b128 v[170:173], v160
	ds_read_b128 v[174:177], v160 offset:1024
	ds_read_b128 v[178:181], v160 offset:2048
	ds_read_b128 v[182:185], v160 offset:3072
	v_lshl_add_u64 v[160:161], s[8:9], 0, v[144:145]
	s_add_i32 m0, s72, 0xc000
	ds_read_b128 v[186:189], v165
	ds_read_b128 v[190:193], v165 offset:1024
	ds_read_b128 v[194:197], v165 offset:2048
	ds_read_b128 v[198:201], v165 offset:3072
	ds_read_b128 v[202:205], v165 offset:4096
	ds_read_b128 v[206:209], v165 offset:5120
	ds_read_b128 v[222:225], v165 offset:6144
	ds_read_b128 v[226:229], v165 offset:7168
	global_load_lds_dwordx4 v[160:161], off
	v_lshl_add_u64 v[160:161], s[8:9], 0, v[146:147]
	s_add_i32 m0, s72, 0xe000
	s_nop 0
	global_load_lds_dwordx4 v[160:161], off
	s_waitcnt vmcnt(8)
	s_waitcnt lgkmcnt(0)
	s_barrier
	s_setprio 3
	v_mfma_f32_16x16x32_bf16 v[70:73], v[148:151], v[186:189], v[70:73]
	v_mfma_f32_16x16x32_bf16 v[66:69], v[156:159], v[186:189], v[66:69]
	v_mfma_f32_16x16x32_bf16 v[54:57], v[148:151], v[194:197], v[54:57]
	v_mfma_f32_16x16x32_bf16 v[50:53], v[156:159], v[194:197], v[50:53]
	v_mfma_f32_16x16x32_bf16 v[46:49], v[148:151], v[202:205], v[46:49]
	v_mfma_f32_16x16x32_bf16 v[42:45], v[156:159], v[202:205], v[42:45]
	v_mfma_f32_16x16x32_bf16 v[38:41], v[148:151], v[222:225], v[38:41]
	v_mfma_f32_16x16x32_bf16 v[34:37], v[156:159], v[222:225], v[34:37]
	v_mfma_f32_16x16x32_bf16 v[70:73], v[152:155], v[190:193], v[70:73]
	v_mfma_f32_16x16x32_bf16 v[66:69], v[166:169], v[190:193], v[66:69]
	v_mfma_f32_16x16x32_bf16 v[54:57], v[152:155], v[198:201], v[54:57]
	v_mfma_f32_16x16x32_bf16 v[50:53], v[166:169], v[198:201], v[50:53]
	v_mfma_f32_16x16x32_bf16 v[46:49], v[152:155], v[206:209], v[46:49]
	v_mfma_f32_16x16x32_bf16 v[42:45], v[166:169], v[206:209], v[42:45]
	v_mfma_f32_16x16x32_bf16 v[38:41], v[152:155], v[226:229], v[38:41]
	v_mfma_f32_16x16x32_bf16 v[34:37], v[166:169], v[226:229], v[34:37]
	v_mfma_f32_16x16x32_bf16 v[126:129], v[170:173], v[186:189], v[126:129]
	v_mfma_f32_16x16x32_bf16 v[122:125], v[178:181], v[186:189], v[122:125]
	v_mfma_f32_16x16x32_bf16 v[118:121], v[170:173], v[194:197], v[118:121]
	v_mfma_f32_16x16x32_bf16 v[114:117], v[178:181], v[194:197], v[114:117]
	v_mfma_f32_16x16x32_bf16 v[110:113], v[170:173], v[202:205], v[110:113]
	v_mfma_f32_16x16x32_bf16 v[106:109], v[178:181], v[202:205], v[106:109]
	v_mfma_f32_16x16x32_bf16 v[102:105], v[170:173], v[222:225], v[102:105]
	v_mfma_f32_16x16x32_bf16 v[98:101], v[178:181], v[222:225], v[98:101]
	v_mfma_f32_16x16x32_bf16 v[126:129], v[174:177], v[190:193], v[126:129]
	v_mfma_f32_16x16x32_bf16 v[122:125], v[182:185], v[190:193], v[122:125]
	v_mfma_f32_16x16x32_bf16 v[118:121], v[174:177], v[198:201], v[118:121]
	v_mfma_f32_16x16x32_bf16 v[114:117], v[182:185], v[198:201], v[114:117]
	v_mfma_f32_16x16x32_bf16 v[110:113], v[174:177], v[206:209], v[110:113]
	v_mfma_f32_16x16x32_bf16 v[106:109], v[182:185], v[206:209], v[106:109]
	v_mfma_f32_16x16x32_bf16 v[102:105], v[174:177], v[226:229], v[102:105]
	v_mfma_f32_16x16x32_bf16 v[98:101], v[182:185], v[226:229], v[98:101]
	s_setprio 0
	s_barrier
	s_add_i32 s64, s64, s63
	v_lshl_add_u64 v[160:161], s[56:57], 0, v[0:1]
	s_mov_b32 m0, s64
	ds_read_b128 v[186:189], v165 offset:16384
	ds_read_b128 v[190:193], v165 offset:17408
	ds_read_b128 v[194:197], v165 offset:18432
	ds_read_b128 v[198:201], v165 offset:19456
	ds_read_b128 v[202:205], v165 offset:20480
	ds_read_b128 v[206:209], v165 offset:21504
	ds_read_b128 v[222:225], v165 offset:22528
	ds_read_b128 v[226:229], v165 offset:23552
	global_load_lds_dwordx4 v[160:161], off
	s_add_i32 m0, s64, 0x2000
	s_add_u32 s64, s56, 0x40000
	v_lshl_add_u64 v[210:211], s[56:57], 0, v[134:135]
	s_addc_u32 s65, s57, 0
	s_add_i32 s86, s86, s63
	global_load_lds_dwordx4 v[210:211], off
	v_lshl_add_u64 v[230:231], s[64:65], 0, v[0:1]
	s_mov_b32 m0, s86
	v_lshl_add_u64 v[232:233], s[68:69], 0, v[136:137]
	global_load_lds_dwordx4 v[230:231], off
	v_lshl_add_u64 v[230:231], s[64:65], 0, v[134:135]
	s_add_i32 m0, s86, 0x2000
	s_nop 0
	global_load_lds_dwordx4 v[230:231], off
	v_lshl_add_u64 v[230:231], s[68:69], 0, v[138:139]
	s_mov_b32 m0, s72
	s_nop 0
	global_load_lds_dwordx4 v[230:231], off
	s_mov_b32 m0, s73
	s_nop 0
	global_load_lds_dwordx4 v[232:233], off
	s_waitcnt vmcnt(8)
	s_waitcnt lgkmcnt(0)
	s_barrier
	s_setprio 3
	v_mfma_f32_16x16x32_bf16 v[30:33], v[148:151], v[186:189], v[30:33]
	v_mfma_f32_16x16x32_bf16 v[26:29], v[156:159], v[186:189], v[26:29]
	v_mfma_f32_16x16x32_bf16 v[22:25], v[148:151], v[194:197], v[22:25]
	v_mfma_f32_16x16x32_bf16 v[18:21], v[156:159], v[194:197], v[18:21]
	v_mfma_f32_16x16x32_bf16 v[14:17], v[148:151], v[202:205], v[14:17]
	v_mfma_f32_16x16x32_bf16 v[10:13], v[156:159], v[202:205], v[10:13]
	v_mfma_f32_16x16x32_bf16 v[6:9], v[148:151], v[222:225], v[6:9]
	v_mfma_f32_16x16x32_bf16 v[2:5], v[156:159], v[222:225], v[2:5]
	v_mfma_f32_16x16x32_bf16 v[30:33], v[152:155], v[190:193], v[30:33]
	v_mfma_f32_16x16x32_bf16 v[26:29], v[166:169], v[190:193], v[26:29]
	v_mfma_f32_16x16x32_bf16 v[22:25], v[152:155], v[198:201], v[22:25]
	v_mfma_f32_16x16x32_bf16 v[18:21], v[166:169], v[198:201], v[18:21]
	v_mfma_f32_16x16x32_bf16 v[14:17], v[152:155], v[206:209], v[14:17]
	v_mfma_f32_16x16x32_bf16 v[10:13], v[166:169], v[206:209], v[10:13]
	v_mfma_f32_16x16x32_bf16 v[6:9], v[152:155], v[226:229], v[6:9]
	v_mfma_f32_16x16x32_bf16 v[2:5], v[166:169], v[226:229], v[2:5]
	v_mfma_f32_16x16x32_bf16 v[94:97], v[170:173], v[186:189], v[94:97]
	v_mfma_f32_16x16x32_bf16 v[90:93], v[178:181], v[186:189], v[90:93]
	v_mfma_f32_16x16x32_bf16 v[86:89], v[170:173], v[194:197], v[86:89]
	v_mfma_f32_16x16x32_bf16 v[82:85], v[178:181], v[194:197], v[82:85]
	v_mfma_f32_16x16x32_bf16 v[78:81], v[170:173], v[202:205], v[78:81]
	v_mfma_f32_16x16x32_bf16 v[74:77], v[178:181], v[202:205], v[74:77]
	v_mfma_f32_16x16x32_bf16 v[62:65], v[170:173], v[222:225], v[62:65]
	v_mfma_f32_16x16x32_bf16 v[58:61], v[178:181], v[222:225], v[58:61]
	v_mfma_f32_16x16x32_bf16 v[94:97], v[174:177], v[190:193], v[94:97]
	v_mfma_f32_16x16x32_bf16 v[90:93], v[182:185], v[190:193], v[90:93]
	v_mfma_f32_16x16x32_bf16 v[86:89], v[174:177], v[198:201], v[86:89]
	v_mfma_f32_16x16x32_bf16 v[82:85], v[182:185], v[198:201], v[82:85]
	v_mfma_f32_16x16x32_bf16 v[78:81], v[174:177], v[206:209], v[78:81]
	v_mfma_f32_16x16x32_bf16 v[74:77], v[182:185], v[206:209], v[74:77]
	v_mfma_f32_16x16x32_bf16 v[62:65], v[174:177], v[226:229], v[62:65]
	v_mfma_f32_16x16x32_bf16 v[58:61], v[182:185], v[226:229], v[58:61]
	s_setprio 0
	s_barrier
	s_add_i32 s86, 0, 0x18000
	s_add_i32 s87, 0, 0x1c000
	v_add_u32_e32 v166, s86, v163
	v_add_u32_e32 v182, s87, v163
	ds_read_b128 v[148:151], v166
	ds_read_b128 v[152:155], v166 offset:1024
	ds_read_b128 v[156:159], v166 offset:2048
	ds_read_b128 v[166:169], v166 offset:3072
	ds_read_b128 v[170:173], v182
	ds_read_b128 v[174:177], v182 offset:1024
	ds_read_b128 v[178:181], v182 offset:2048
	ds_read_b128 v[182:185], v182 offset:3072
	s_add_u32 s64, s68, 0x40000
	s_addc_u32 s65, s69, 0
	s_mov_b32 m0, s74
	v_lshl_add_u64 v[234:235], s[64:65], 0, v[138:139]
	ds_read_b128 v[186:189], v165 offset:32768
	ds_read_b128 v[190:193], v165 offset:33792
	ds_read_b128 v[194:197], v165 offset:34816
	ds_read_b128 v[198:201], v165 offset:35840
	ds_read_b128 v[202:205], v165 offset:36864
	ds_read_b128 v[206:209], v165 offset:37888
	ds_read_b128 v[222:225], v165 offset:38912
	ds_read_b128 v[226:229], v165 offset:39936
	global_load_lds_dwordx4 v[234:235], off
	v_lshl_add_u64 v[234:235], s[64:65], 0, v[136:137]
	s_mov_b32 m0, s75
	s_nop 0
	global_load_lds_dwordx4 v[234:235], off
	s_waitcnt vmcnt(8)
	s_waitcnt lgkmcnt(0)
	s_barrier
	s_setprio 3
	v_mfma_f32_16x16x32_bf16 v[70:73], v[148:151], v[186:189], v[70:73]
	v_mfma_f32_16x16x32_bf16 v[66:69], v[156:159], v[186:189], v[66:69]
	v_mfma_f32_16x16x32_bf16 v[54:57], v[148:151], v[194:197], v[54:57]
	v_mfma_f32_16x16x32_bf16 v[50:53], v[156:159], v[194:197], v[50:53]
	v_mfma_f32_16x16x32_bf16 v[46:49], v[148:151], v[202:205], v[46:49]
	v_mfma_f32_16x16x32_bf16 v[42:45], v[156:159], v[202:205], v[42:45]
	v_mfma_f32_16x16x32_bf16 v[38:41], v[148:151], v[222:225], v[38:41]
	v_mfma_f32_16x16x32_bf16 v[34:37], v[156:159], v[222:225], v[34:37]
	v_mfma_f32_16x16x32_bf16 v[70:73], v[152:155], v[190:193], v[70:73]
	v_mfma_f32_16x16x32_bf16 v[66:69], v[166:169], v[190:193], v[66:69]
	v_mfma_f32_16x16x32_bf16 v[54:57], v[152:155], v[198:201], v[54:57]
	v_mfma_f32_16x16x32_bf16 v[50:53], v[166:169], v[198:201], v[50:53]
	v_mfma_f32_16x16x32_bf16 v[46:49], v[152:155], v[206:209], v[46:49]
	v_mfma_f32_16x16x32_bf16 v[42:45], v[166:169], v[206:209], v[42:45]
	v_mfma_f32_16x16x32_bf16 v[38:41], v[152:155], v[226:229], v[38:41]
	v_mfma_f32_16x16x32_bf16 v[34:37], v[166:169], v[226:229], v[34:37]
	v_mfma_f32_16x16x32_bf16 v[126:129], v[170:173], v[186:189], v[126:129]
	v_mfma_f32_16x16x32_bf16 v[122:125], v[178:181], v[186:189], v[122:125]
	v_mfma_f32_16x16x32_bf16 v[118:121], v[170:173], v[194:197], v[118:121]
	v_mfma_f32_16x16x32_bf16 v[114:117], v[178:181], v[194:197], v[114:117]
	v_mfma_f32_16x16x32_bf16 v[110:113], v[170:173], v[202:205], v[110:113]
	v_mfma_f32_16x16x32_bf16 v[106:109], v[178:181], v[202:205], v[106:109]
	v_mfma_f32_16x16x32_bf16 v[102:105], v[170:173], v[222:225], v[102:105]
	v_mfma_f32_16x16x32_bf16 v[98:101], v[178:181], v[222:225], v[98:101]
	v_mfma_f32_16x16x32_bf16 v[126:129], v[174:177], v[190:193], v[126:129]
	v_mfma_f32_16x16x32_bf16 v[122:125], v[182:185], v[190:193], v[122:125]
	v_mfma_f32_16x16x32_bf16 v[118:121], v[174:177], v[198:201], v[118:121]
	v_mfma_f32_16x16x32_bf16 v[114:117], v[182:185], v[198:201], v[114:117]
	v_mfma_f32_16x16x32_bf16 v[110:113], v[174:177], v[206:209], v[110:113]
	v_mfma_f32_16x16x32_bf16 v[106:109], v[182:185], v[206:209], v[106:109]
	v_mfma_f32_16x16x32_bf16 v[102:105], v[174:177], v[226:229], v[102:105]
	v_mfma_f32_16x16x32_bf16 v[98:101], v[182:185], v[226:229], v[98:101]
	s_setprio 0
	s_barrier
	s_add_i32 s64, s86, s63
	v_lshl_add_u64 v[160:161], v[160:161], 0, s[48:49]
	s_mov_b32 m0, s64
	ds_read_b128 v[186:189], v165 offset:49152
	ds_read_b128 v[190:193], v165 offset:50176
	ds_read_b128 v[194:197], v165 offset:51200
	ds_read_b128 v[198:201], v165 offset:52224
	ds_read_b128 v[202:205], v165 offset:53248
	ds_read_b128 v[206:209], v165 offset:54272
	ds_read_b128 v[222:225], v165 offset:55296
	ds_read_b128 v[226:229], v165 offset:56320
	global_load_lds_dwordx4 v[160:161], off
	s_add_i32 m0, s64, 0x2000
	s_add_u32 s56, s56, 0x40080
	v_lshl_add_u64 v[160:161], v[210:211], 0, s[48:49]
	s_addc_u32 s57, s57, 0
	s_add_i32 s64, s87, s63
	global_load_lds_dwordx4 v[160:161], off
	v_lshl_add_u64 v[160:161], s[56:57], 0, v[0:1]
	s_mov_b32 m0, s64
	s_nop 0
	global_load_lds_dwordx4 v[160:161], off
	v_lshl_add_u64 v[160:161], s[56:57], 0, v[134:135]
	s_add_i32 m0, s64, 0x2000
	s_nop 0
	global_load_lds_dwordx4 v[160:161], off
	v_lshl_add_u64 v[160:161], v[230:231], 0, s[48:49]
	s_mov_b32 m0, s78
	s_nop 0
	global_load_lds_dwordx4 v[160:161], off
	v_lshl_add_u64 v[160:161], v[232:233], 0, s[48:49]
	s_mov_b32 m0, s79
	s_nop 0
	global_load_lds_dwordx4 v[160:161], off
	s_waitcnt vmcnt(8)
	s_waitcnt lgkmcnt(0)
	s_barrier
	s_setprio 3
	v_mfma_f32_16x16x32_bf16 v[30:33], v[148:151], v[186:189], v[30:33]
	v_mfma_f32_16x16x32_bf16 v[26:29], v[156:159], v[186:189], v[26:29]
	v_mfma_f32_16x16x32_bf16 v[22:25], v[148:151], v[194:197], v[22:25]
	v_mfma_f32_16x16x32_bf16 v[18:21], v[156:159], v[194:197], v[18:21]
	v_mfma_f32_16x16x32_bf16 v[14:17], v[148:151], v[202:205], v[14:17]
	v_mfma_f32_16x16x32_bf16 v[10:13], v[156:159], v[202:205], v[10:13]
	v_mfma_f32_16x16x32_bf16 v[6:9], v[148:151], v[222:225], v[6:9]
	v_mfma_f32_16x16x32_bf16 v[2:5], v[156:159], v[222:225], v[2:5]
	v_mfma_f32_16x16x32_bf16 v[30:33], v[152:155], v[190:193], v[30:33]
	v_mfma_f32_16x16x32_bf16 v[26:29], v[166:169], v[190:193], v[26:29]
	v_mfma_f32_16x16x32_bf16 v[22:25], v[152:155], v[198:201], v[22:25]
	v_mfma_f32_16x16x32_bf16 v[18:21], v[166:169], v[198:201], v[18:21]
	v_mfma_f32_16x16x32_bf16 v[14:17], v[152:155], v[206:209], v[14:17]
	v_mfma_f32_16x16x32_bf16 v[10:13], v[166:169], v[206:209], v[10:13]
	v_mfma_f32_16x16x32_bf16 v[6:9], v[152:155], v[226:229], v[6:9]
	v_mfma_f32_16x16x32_bf16 v[2:5], v[166:169], v[226:229], v[2:5]
	v_mfma_f32_16x16x32_bf16 v[94:97], v[170:173], v[186:189], v[94:97]
	v_mfma_f32_16x16x32_bf16 v[90:93], v[178:181], v[186:189], v[90:93]
	v_mfma_f32_16x16x32_bf16 v[86:89], v[170:173], v[194:197], v[86:89]
	v_mfma_f32_16x16x32_bf16 v[82:85], v[178:181], v[194:197], v[82:85]
	v_mfma_f32_16x16x32_bf16 v[78:81], v[170:173], v[202:205], v[78:81]
	v_mfma_f32_16x16x32_bf16 v[74:77], v[178:181], v[202:205], v[74:77]
	v_mfma_f32_16x16x32_bf16 v[62:65], v[170:173], v[222:225], v[62:65]
	v_mfma_f32_16x16x32_bf16 v[58:61], v[178:181], v[222:225], v[58:61]
	v_mfma_f32_16x16x32_bf16 v[94:97], v[174:177], v[190:193], v[94:97]
	v_mfma_f32_16x16x32_bf16 v[90:93], v[182:185], v[190:193], v[90:93]
	v_mfma_f32_16x16x32_bf16 v[86:89], v[174:177], v[198:201], v[86:89]
	v_mfma_f32_16x16x32_bf16 v[82:85], v[182:185], v[198:201], v[82:85]
	v_mfma_f32_16x16x32_bf16 v[78:81], v[174:177], v[206:209], v[78:81]
	v_mfma_f32_16x16x32_bf16 v[74:77], v[182:185], v[206:209], v[74:77]
	v_mfma_f32_16x16x32_bf16 v[62:65], v[174:177], v[226:229], v[62:65]
	v_mfma_f32_16x16x32_bf16 v[58:61], v[182:185], v[226:229], v[58:61]
	s_setprio 0
	s_barrier
	s_add_i32 s85, s85, 2
	s_add_u32 s8, s8, 0x100
	s_addc_u32 s9, s9, 0
	s_add_u32 s83, s83, 0x100
	s_addc_u32 s84, s84, 0
	s_cmp_gt_u32 s85, 13
	s_cbranch_scc0 .LBB0_676
	s_and_b64 vcc, exec, s[16:17]
	s_cbranch_vccnz .LBB0_681
	s_cmp_lt_i32 s30, 16
	s_mov_b64 s[8:9], -1
	s_cbranch_scc1 .LBB0_682

.LBB0_1458:
	s_ashr_i32 s11, s12, 3
	s_add_i32 s11, s12, s11
	s_and_b64 s[16:17], s[66:67], s[4:5]
	s_add_i32 s11, s11, 1
	s_and_b64 s[16:17], s[16:17], exec
	s_cselect_b32 s12, s11, s12
	s_ashr_i32 s13, s12, 31
	s_lshl_b64 s[16:17], s[12:13], 19
	s_add_u32 s16, s37, s16
	s_addc_u32 s17, s60, s17
	s_and_b64 s[18:19], s[4:5], exec
	s_cselect_b32 s13, s17, s53
	s_cselect_b32 s27, s16, s52
	s_ashr_i32 s11, s10, 31
	s_lshl_b64 s[18:19], s[10:11], 19
	s_add_u32 s18, s63, s18
	s_addc_u32 s19, s70, s19
	s_and_b64 s[30:31], s[4:5], exec
	s_cselect_b32 s11, s19, s57
	s_cselect_b32 s30, s18, s56
	s_add_u32 s52, s52, 0x40080
	s_addc_u32 s53, s53, 0
	s_add_u32 s31, s56, 0x100
	s_addc_u32 s84, s57, 0
	s_mov_b32 s85, -2
	s_add_u32 s56, s52, 0xfffc0080
	s_addc_u32 s57, s53, -1
	s_add_i32 s64, 0, 0x10000
	s_cmp_eq_u32 s85, 12
	s_cselect_b32 s69, s13, s57
	s_cselect_b32 s68, s27, s56
	v_add_u32_e32 v0, s64, v167
	s_cselect_b32 s57, s11, s84
	s_cselect_b32 s56, s30, s31
	s_add_i32 s86, 0, 0x14000
	ds_read_b128 v[134:137], v0
	ds_read_b128 v[150:153], v0 offset:1024
	ds_read_b128 v[154:157], v0 offset:2048
	ds_read_b128 v[158:161], v0 offset:3072
	v_add_u32_e32 v0, s86, v167
	ds_read_b128 v[162:165], v0
	ds_read_b128 v[170:173], v0 offset:1024
	ds_read_b128 v[174:177], v0 offset:2048
	ds_read_b128 v[178:181], v0 offset:3072
	v_lshl_add_u64 v[210:211], s[52:53], 0, v[146:147]
	s_add_i32 m0, s21, 0xc000
	ds_read_b128 v[182:185], v169
	ds_read_b128 v[186:189], v169 offset:1024
	ds_read_b128 v[190:193], v169 offset:2048
	ds_read_b128 v[194:197], v169 offset:3072
	ds_read_b128 v[198:201], v169 offset:4096
	ds_read_b128 v[202:205], v169 offset:5120
	ds_read_b128 v[206:209], v169 offset:6144
	ds_read_b128 v[224:227], v169 offset:7168
	global_load_lds_dwordx4 v[210:211], off
	v_lshl_add_u64 v[210:211], s[52:53], 0, v[148:149]
	s_add_i32 m0, s21, 0xe000
	s_nop 0
	global_load_lds_dwordx4 v[210:211], off
	s_waitcnt vmcnt(8)
	s_waitcnt lgkmcnt(0)
	s_barrier
	s_setprio 3
	v_mfma_f32_16x16x32_bf16 v[126:129], v[134:137], v[182:185], 0
	v_mfma_f32_16x16x32_bf16 v[122:125], v[154:157], v[182:185], 0
	v_mfma_f32_16x16x32_bf16 v[110:113], v[134:137], v[190:193], 0
	v_mfma_f32_16x16x32_bf16 v[106:109], v[154:157], v[190:193], 0
	v_mfma_f32_16x16x32_bf16 v[94:97], v[134:137], v[198:201], 0
	v_mfma_f32_16x16x32_bf16 v[90:93], v[154:157], v[198:201], 0
	v_mfma_f32_16x16x32_bf16 v[78:81], v[134:137], v[206:209], 0
	v_mfma_f32_16x16x32_bf16 v[74:77], v[154:157], v[206:209], 0
	v_mfma_f32_16x16x32_bf16 v[126:129], v[150:153], v[186:189], v[126:129]
	v_mfma_f32_16x16x32_bf16 v[122:125], v[158:161], v[186:189], v[122:125]
	v_mfma_f32_16x16x32_bf16 v[110:113], v[150:153], v[194:197], v[110:113]
	v_mfma_f32_16x16x32_bf16 v[106:109], v[158:161], v[194:197], v[106:109]
	v_mfma_f32_16x16x32_bf16 v[94:97], v[150:153], v[202:205], v[94:97]
	v_mfma_f32_16x16x32_bf16 v[90:93], v[158:161], v[202:205], v[90:93]
	v_mfma_f32_16x16x32_bf16 v[78:81], v[150:153], v[224:227], v[78:81]
	v_mfma_f32_16x16x32_bf16 v[74:77], v[158:161], v[224:227], v[74:77]
	v_mfma_f32_16x16x32_bf16 v[118:121], v[162:165], v[182:185], 0
	v_mfma_f32_16x16x32_bf16 v[114:117], v[174:177], v[182:185], 0
	v_mfma_f32_16x16x32_bf16 v[102:105], v[162:165], v[190:193], 0
	v_mfma_f32_16x16x32_bf16 v[98:101], v[174:177], v[190:193], 0
	v_mfma_f32_16x16x32_bf16 v[86:89], v[162:165], v[198:201], 0
	v_mfma_f32_16x16x32_bf16 v[82:85], v[174:177], v[198:201], 0
	v_mfma_f32_16x16x32_bf16 v[70:73], v[162:165], v[206:209], 0
	v_mfma_f32_16x16x32_bf16 v[66:69], v[174:177], v[206:209], 0
	v_mfma_f32_16x16x32_bf16 v[118:121], v[170:173], v[186:189], v[118:121]
	v_mfma_f32_16x16x32_bf16 v[114:117], v[178:181], v[186:189], v[114:117]
	v_mfma_f32_16x16x32_bf16 v[102:105], v[170:173], v[194:197], v[102:105]
	v_mfma_f32_16x16x32_bf16 v[98:101], v[178:181], v[194:197], v[98:101]
	v_mfma_f32_16x16x32_bf16 v[86:89], v[170:173], v[202:205], v[86:89]
	v_mfma_f32_16x16x32_bf16 v[82:85], v[178:181], v[202:205], v[82:85]
	v_mfma_f32_16x16x32_bf16 v[70:73], v[170:173], v[224:227], v[70:73]
	v_mfma_f32_16x16x32_bf16 v[66:69], v[178:181], v[224:227], v[66:69]
	s_setprio 0
	s_barrier
	s_add_i32 s64, s64, s71
	v_lshl_add_u64 v[210:211], s[56:57], 0, v[142:143]
	s_mov_b32 m0, s64
	ds_read_b128 v[182:185], v169 offset:16384
	ds_read_b128 v[186:189], v169 offset:17408
	ds_read_b128 v[190:193], v169 offset:18432
	ds_read_b128 v[194:197], v169 offset:19456
	ds_read_b128 v[198:201], v169 offset:20480
	ds_read_b128 v[202:205], v169 offset:21504
	ds_read_b128 v[206:209], v169 offset:22528
	ds_read_b128 v[224:227], v169 offset:23552
	global_load_lds_dwordx4 v[210:211], off
	s_add_i32 m0, s64, 0x2000
	s_add_u32 s64, s56, 0x40000
	v_lshl_add_u64 v[228:229], s[56:57], 0, v[138:139]
	s_addc_u32 s65, s57, 0
	s_add_i32 s86, s86, s71
	global_load_lds_dwordx4 v[228:229], off
	v_lshl_add_u64 v[230:231], s[64:65], 0, v[142:143]
	s_mov_b32 m0, s86
	v_lshl_add_u64 v[232:233], s[68:69], 0, v[140:141]
	global_load_lds_dwordx4 v[230:231], off
	v_lshl_add_u64 v[230:231], s[64:65], 0, v[138:139]
	s_add_i32 m0, s86, 0x2000
	s_nop 0
	global_load_lds_dwordx4 v[230:231], off
	v_lshl_add_u64 v[230:231], s[68:69], 0, v[144:145]
	s_mov_b32 m0, s21
	s_nop 0
	global_load_lds_dwordx4 v[230:231], off
	s_mov_b32 m0, s73
	s_nop 0
	global_load_lds_dwordx4 v[232:233], off
	s_waitcnt vmcnt(8)
	s_waitcnt lgkmcnt(0)
	s_barrier
	s_setprio 3
	v_mfma_f32_16x16x32_bf16 v[62:65], v[134:137], v[182:185], 0
	v_mfma_f32_16x16x32_bf16 v[58:61], v[154:157], v[182:185], 0
	v_mfma_f32_16x16x32_bf16 v[46:49], v[134:137], v[190:193], 0
	v_mfma_f32_16x16x32_bf16 v[42:45], v[154:157], v[190:193], 0
	v_mfma_f32_16x16x32_bf16 v[30:33], v[134:137], v[198:201], 0
	v_mfma_f32_16x16x32_bf16 v[26:29], v[154:157], v[198:201], 0
	v_mfma_f32_16x16x32_bf16 v[14:17], v[134:137], v[206:209], 0
	v_mfma_f32_16x16x32_bf16 v[10:13], v[154:157], v[206:209], 0
	v_mfma_f32_16x16x32_bf16 v[62:65], v[150:153], v[186:189], v[62:65]
	v_mfma_f32_16x16x32_bf16 v[58:61], v[158:161], v[186:189], v[58:61]
	v_mfma_f32_16x16x32_bf16 v[46:49], v[150:153], v[194:197], v[46:49]
	v_mfma_f32_16x16x32_bf16 v[42:45], v[158:161], v[194:197], v[42:45]
	v_mfma_f32_16x16x32_bf16 v[30:33], v[150:153], v[202:205], v[30:33]
	v_mfma_f32_16x16x32_bf16 v[26:29], v[158:161], v[202:205], v[26:29]
	v_mfma_f32_16x16x32_bf16 v[14:17], v[150:153], v[224:227], v[14:17]
	v_mfma_f32_16x16x32_bf16 v[10:13], v[158:161], v[224:227], v[10:13]
	v_mfma_f32_16x16x32_bf16 v[54:57], v[162:165], v[182:185], 0
	v_mfma_f32_16x16x32_bf16 v[50:53], v[174:177], v[182:185], 0
	v_mfma_f32_16x16x32_bf16 v[38:41], v[162:165], v[190:193], 0
	v_mfma_f32_16x16x32_bf16 v[34:37], v[174:177], v[190:193], 0
	v_mfma_f32_16x16x32_bf16 v[22:25], v[162:165], v[198:201], 0
	v_mfma_f32_16x16x32_bf16 v[18:21], v[174:177], v[198:201], 0
	v_mfma_f32_16x16x32_bf16 v[6:9], v[162:165], v[206:209], 0
	v_mfma_f32_16x16x32_bf16 v[2:5], v[174:177], v[206:209], 0
	v_mfma_f32_16x16x32_bf16 v[54:57], v[170:173], v[186:189], v[54:57]
	v_mfma_f32_16x16x32_bf16 v[50:53], v[178:181], v[186:189], v[50:53]
	v_mfma_f32_16x16x32_bf16 v[38:41], v[170:173], v[194:197], v[38:41]
	v_mfma_f32_16x16x32_bf16 v[34:37], v[178:181], v[194:197], v[34:37]
	v_mfma_f32_16x16x32_bf16 v[22:25], v[170:173], v[202:205], v[22:25]
	v_mfma_f32_16x16x32_bf16 v[18:21], v[178:181], v[202:205], v[18:21]
	v_mfma_f32_16x16x32_bf16 v[6:9], v[170:173], v[224:227], v[6:9]
	v_mfma_f32_16x16x32_bf16 v[2:5], v[178:181], v[224:227], v[2:5]
	s_setprio 0
	s_barrier
	s_add_i32 s86, 0, 0x18000
	v_add_u32_e32 v0, s86, v167
	s_add_i32 s87, 0, 0x1c000
	ds_read_b128 v[134:137], v0
	ds_read_b128 v[150:153], v0 offset:1024
	ds_read_b128 v[154:157], v0 offset:2048
	ds_read_b128 v[158:161], v0 offset:3072
	v_add_u32_e32 v0, s87, v167
	ds_read_b128 v[162:165], v0
	ds_read_b128 v[170:173], v0 offset:1024
	ds_read_b128 v[174:177], v0 offset:2048
	ds_read_b128 v[178:181], v0 offset:3072
	s_add_u32 s64, s68, 0x40000
	s_addc_u32 s65, s69, 0
	s_mov_b32 m0, s74
	v_lshl_add_u64 v[234:235], s[64:65], 0, v[144:145]
	ds_read_b128 v[182:185], v169 offset:32768
	ds_read_b128 v[186:189], v169 offset:33792
	ds_read_b128 v[190:193], v169 offset:34816
	ds_read_b128 v[194:197], v169 offset:35840
	ds_read_b128 v[198:201], v169 offset:36864
	ds_read_b128 v[202:205], v169 offset:37888
	ds_read_b128 v[206:209], v169 offset:38912
	ds_read_b128 v[224:227], v169 offset:39936
	global_load_lds_dwordx4 v[234:235], off
	v_lshl_add_u64 v[234:235], s[64:65], 0, v[140:141]
	s_mov_b32 m0, s75
	s_nop 0
	global_load_lds_dwordx4 v[234:235], off
	s_waitcnt vmcnt(8)
	s_waitcnt lgkmcnt(0)
	s_barrier
	s_setprio 3
	v_mfma_f32_16x16x32_bf16 v[126:129], v[134:137], v[182:185], v[126:129]
	v_mfma_f32_16x16x32_bf16 v[122:125], v[154:157], v[182:185], v[122:125]
	v_mfma_f32_16x16x32_bf16 v[110:113], v[134:137], v[190:193], v[110:113]
	v_mfma_f32_16x16x32_bf16 v[106:109], v[154:157], v[190:193], v[106:109]
	v_mfma_f32_16x16x32_bf16 v[94:97], v[134:137], v[198:201], v[94:97]
	v_mfma_f32_16x16x32_bf16 v[90:93], v[154:157], v[198:201], v[90:93]
	v_mfma_f32_16x16x32_bf16 v[78:81], v[134:137], v[206:209], v[78:81]
	v_mfma_f32_16x16x32_bf16 v[74:77], v[154:157], v[206:209], v[74:77]
	v_mfma_f32_16x16x32_bf16 v[126:129], v[150:153], v[186:189], v[126:129]
	v_mfma_f32_16x16x32_bf16 v[122:125], v[158:161], v[186:189], v[122:125]
	v_mfma_f32_16x16x32_bf16 v[110:113], v[150:153], v[194:197], v[110:113]
	v_mfma_f32_16x16x32_bf16 v[106:109], v[158:161], v[194:197], v[106:109]
	v_mfma_f32_16x16x32_bf16 v[94:97], v[150:153], v[202:205], v[94:97]
	v_mfma_f32_16x16x32_bf16 v[90:93], v[158:161], v[202:205], v[90:93]
	v_mfma_f32_16x16x32_bf16 v[78:81], v[150:153], v[224:227], v[78:81]
	v_mfma_f32_16x16x32_bf16 v[74:77], v[158:161], v[224:227], v[74:77]
	v_mfma_f32_16x16x32_bf16 v[118:121], v[162:165], v[182:185], v[118:121]
	v_mfma_f32_16x16x32_bf16 v[114:117], v[174:177], v[182:185], v[114:117]
	v_mfma_f32_16x16x32_bf16 v[102:105], v[162:165], v[190:193], v[102:105]
	v_mfma_f32_16x16x32_bf16 v[98:101], v[174:177], v[190:193], v[98:101]
	v_mfma_f32_16x16x32_bf16 v[86:89], v[162:165], v[198:201], v[86:89]
	v_mfma_f32_16x16x32_bf16 v[82:85], v[174:177], v[198:201], v[82:85]
	v_mfma_f32_16x16x32_bf16 v[70:73], v[162:165], v[206:209], v[70:73]
	v_mfma_f32_16x16x32_bf16 v[66:69], v[174:177], v[206:209], v[66:69]
	v_mfma_f32_16x16x32_bf16 v[118:121], v[170:173], v[186:189], v[118:121]
	v_mfma_f32_16x16x32_bf16 v[114:117], v[178:181], v[186:189], v[114:117]
	v_mfma_f32_16x16x32_bf16 v[102:105], v[170:173], v[194:197], v[102:105]
	v_mfma_f32_16x16x32_bf16 v[98:101], v[178:181], v[194:197], v[98:101]
	v_mfma_f32_16x16x32_bf16 v[86:89], v[170:173], v[202:205], v[86:89]
	v_mfma_f32_16x16x32_bf16 v[82:85], v[178:181], v[202:205], v[82:85]
	v_mfma_f32_16x16x32_bf16 v[70:73], v[170:173], v[224:227], v[70:73]
	v_mfma_f32_16x16x32_bf16 v[66:69], v[178:181], v[224:227], v[66:69]
	s_setprio 0
	s_barrier
	s_add_i32 s64, s86, s71
	v_lshl_add_u64 v[210:211], v[210:211], 0, s[48:49]
	s_mov_b32 m0, s64
	ds_read_b128 v[182:185], v169 offset:49152
	ds_read_b128 v[186:189], v169 offset:50176
	ds_read_b128 v[190:193], v169 offset:51200
	ds_read_b128 v[194:197], v169 offset:52224
	ds_read_b128 v[198:201], v169 offset:53248
	ds_read_b128 v[202:205], v169 offset:54272
	ds_read_b128 v[206:209], v169 offset:55296
	ds_read_b128 v[224:227], v169 offset:56320
	global_load_lds_dwordx4 v[210:211], off
	s_add_i32 m0, s64, 0x2000
	s_add_u32 s56, s56, 0x40080
	v_lshl_add_u64 v[210:211], v[228:229], 0, s[48:49]
	s_addc_u32 s57, s57, 0
	s_add_i32 s64, s87, s71
	global_load_lds_dwordx4 v[210:211], off
	v_lshl_add_u64 v[210:211], s[56:57], 0, v[142:143]
	s_mov_b32 m0, s64
	s_nop 0
	global_load_lds_dwordx4 v[210:211], off
	v_lshl_add_u64 v[210:211], s[56:57], 0, v[138:139]
	s_add_i32 m0, s64, 0x2000
	s_nop 0
	global_load_lds_dwordx4 v[210:211], off
	v_lshl_add_u64 v[210:211], v[230:231], 0, s[48:49]
	s_mov_b32 m0, s80
	s_nop 0
	global_load_lds_dwordx4 v[210:211], off
	v_lshl_add_u64 v[210:211], v[232:233], 0, s[48:49]
	s_mov_b32 m0, s81
	s_nop 0
	global_load_lds_dwordx4 v[210:211], off
	s_waitcnt vmcnt(8)
	s_waitcnt lgkmcnt(0)
	s_barrier
	s_setprio 3
	v_mfma_f32_16x16x32_bf16 v[62:65], v[134:137], v[182:185], v[62:65]
	v_mfma_f32_16x16x32_bf16 v[58:61], v[154:157], v[182:185], v[58:61]
	v_mfma_f32_16x16x32_bf16 v[46:49], v[134:137], v[190:193], v[46:49]
	v_mfma_f32_16x16x32_bf16 v[42:45], v[154:157], v[190:193], v[42:45]
	v_mfma_f32_16x16x32_bf16 v[30:33], v[134:137], v[198:201], v[30:33]
	v_mfma_f32_16x16x32_bf16 v[26:29], v[154:157], v[198:201], v[26:29]
	v_mfma_f32_16x16x32_bf16 v[14:17], v[134:137], v[206:209], v[14:17]
	v_mfma_f32_16x16x32_bf16 v[10:13], v[154:157], v[206:209], v[10:13]
	v_mfma_f32_16x16x32_bf16 v[62:65], v[150:153], v[186:189], v[62:65]
	v_mfma_f32_16x16x32_bf16 v[58:61], v[158:161], v[186:189], v[58:61]
	v_mfma_f32_16x16x32_bf16 v[46:49], v[150:153], v[194:197], v[46:49]
	v_mfma_f32_16x16x32_bf16 v[42:45], v[158:161], v[194:197], v[42:45]
	v_mfma_f32_16x16x32_bf16 v[30:33], v[150:153], v[202:205], v[30:33]
	v_mfma_f32_16x16x32_bf16 v[26:29], v[158:161], v[202:205], v[26:29]
	v_mfma_f32_16x16x32_bf16 v[14:17], v[150:153], v[224:227], v[14:17]
	v_mfma_f32_16x16x32_bf16 v[10:13], v[158:161], v[224:227], v[10:13]
	v_mfma_f32_16x16x32_bf16 v[54:57], v[162:165], v[182:185], v[54:57]
	v_mfma_f32_16x16x32_bf16 v[50:53], v[174:177], v[182:185], v[50:53]
	v_mfma_f32_16x16x32_bf16 v[38:41], v[162:165], v[190:193], v[38:41]
	v_mfma_f32_16x16x32_bf16 v[34:37], v[174:177], v[190:193], v[34:37]
	v_mfma_f32_16x16x32_bf16 v[22:25], v[162:165], v[198:201], v[22:25]
	v_mfma_f32_16x16x32_bf16 v[18:21], v[174:177], v[198:201], v[18:21]
	v_mfma_f32_16x16x32_bf16 v[6:9], v[162:165], v[206:209], v[6:9]
	v_mfma_f32_16x16x32_bf16 v[2:5], v[174:177], v[206:209], v[2:5]
	v_mfma_f32_16x16x32_bf16 v[54:57], v[170:173], v[186:189], v[54:57]
	v_mfma_f32_16x16x32_bf16 v[50:53], v[178:181], v[186:189], v[50:53]
	v_mfma_f32_16x16x32_bf16 v[38:41], v[170:173], v[194:197], v[38:41]
	v_mfma_f32_16x16x32_bf16 v[34:37], v[178:181], v[194:197], v[34:37]
	v_mfma_f32_16x16x32_bf16 v[22:25], v[170:173], v[202:205], v[22:25]
	v_mfma_f32_16x16x32_bf16 v[18:21], v[178:181], v[202:205], v[18:21]
	v_mfma_f32_16x16x32_bf16 v[6:9], v[170:173], v[224:227], v[6:9]
	v_mfma_f32_16x16x32_bf16 v[2:5], v[178:181], v[224:227], v[2:5]
	s_setprio 0
	s_barrier
	s_add_i32 s85, s85, 2
	s_add_u32 s52, s52, 0x100
	s_addc_u32 s53, s53, 0
	s_add_u32 s31, s31, 0x100
	s_addc_u32 s84, s84, 0
.LBB0_1459:
	s_add_u32 s56, s52, 0xfffc0080
	s_addc_u32 s57, s53, -1
	s_add_i32 s64, 0, 0x10000
	s_cmp_eq_u32 s85, 12
	s_cselect_b32 s69, s13, s57
	s_cselect_b32 s68, s27, s56
	v_add_u32_e32 v0, s64, v167
	s_cselect_b32 s57, s11, s84
	s_cselect_b32 s56, s30, s31
	s_add_i32 s86, 0, 0x14000
	ds_read_b128 v[134:137], v0
	ds_read_b128 v[150:153], v0 offset:1024
	ds_read_b128 v[154:157], v0 offset:2048
	ds_read_b128 v[158:161], v0 offset:3072
	v_add_u32_e32 v0, s86, v167
	ds_read_b128 v[162:165], v0
	ds_read_b128 v[170:173], v0 offset:1024
	ds_read_b128 v[174:177], v0 offset:2048
	ds_read_b128 v[178:181], v0 offset:3072
	v_lshl_add_u64 v[210:211], s[52:53], 0, v[146:147]
	s_add_i32 m0, s21, 0xc000
	ds_read_b128 v[182:185], v169
	ds_read_b128 v[186:189], v169 offset:1024
	ds_read_b128 v[190:193], v169 offset:2048
	ds_read_b128 v[194:197], v169 offset:3072
	ds_read_b128 v[198:201], v169 offset:4096
	ds_read_b128 v[202:205], v169 offset:5120
	ds_read_b128 v[206:209], v169 offset:6144
	ds_read_b128 v[224:227], v169 offset:7168
	global_load_lds_dwordx4 v[210:211], off
	v_lshl_add_u64 v[210:211], s[52:53], 0, v[148:149]
	s_add_i32 m0, s21, 0xe000
	s_nop 0
	global_load_lds_dwordx4 v[210:211], off
	s_waitcnt vmcnt(8)
	s_waitcnt lgkmcnt(0)
	s_barrier
	s_setprio 3
	v_mfma_f32_16x16x32_bf16 v[126:129], v[134:137], v[182:185], v[126:129]
	v_mfma_f32_16x16x32_bf16 v[122:125], v[154:157], v[182:185], v[122:125]
	v_mfma_f32_16x16x32_bf16 v[110:113], v[134:137], v[190:193], v[110:113]
	v_mfma_f32_16x16x32_bf16 v[106:109], v[154:157], v[190:193], v[106:109]
	v_mfma_f32_16x16x32_bf16 v[94:97], v[134:137], v[198:201], v[94:97]
	v_mfma_f32_16x16x32_bf16 v[90:93], v[154:157], v[198:201], v[90:93]
	v_mfma_f32_16x16x32_bf16 v[78:81], v[134:137], v[206:209], v[78:81]
	v_mfma_f32_16x16x32_bf16 v[74:77], v[154:157], v[206:209], v[74:77]
	v_mfma_f32_16x16x32_bf16 v[126:129], v[150:153], v[186:189], v[126:129]
	v_mfma_f32_16x16x32_bf16 v[122:125], v[158:161], v[186:189], v[122:125]
	v_mfma_f32_16x16x32_bf16 v[110:113], v[150:153], v[194:197], v[110:113]
	v_mfma_f32_16x16x32_bf16 v[106:109], v[158:161], v[194:197], v[106:109]
	v_mfma_f32_16x16x32_bf16 v[94:97], v[150:153], v[202:205], v[94:97]
	v_mfma_f32_16x16x32_bf16 v[90:93], v[158:161], v[202:205], v[90:93]
	v_mfma_f32_16x16x32_bf16 v[78:81], v[150:153], v[224:227], v[78:81]
	v_mfma_f32_16x16x32_bf16 v[74:77], v[158:161], v[224:227], v[74:77]
	v_mfma_f32_16x16x32_bf16 v[118:121], v[162:165], v[182:185], v[118:121]
	v_mfma_f32_16x16x32_bf16 v[114:117], v[174:177], v[182:185], v[114:117]
	v_mfma_f32_16x16x32_bf16 v[102:105], v[162:165], v[190:193], v[102:105]
	v_mfma_f32_16x16x32_bf16 v[98:101], v[174:177], v[190:193], v[98:101]
	v_mfma_f32_16x16x32_bf16 v[86:89], v[162:165], v[198:201], v[86:89]
	v_mfma_f32_16x16x32_bf16 v[82:85], v[174:177], v[198:201], v[82:85]
	v_mfma_f32_16x16x32_bf16 v[70:73], v[162:165], v[206:209], v[70:73]
	v_mfma_f32_16x16x32_bf16 v[66:69], v[174:177], v[206:209], v[66:69]
	v_mfma_f32_16x16x32_bf16 v[118:121], v[170:173], v[186:189], v[118:121]
	v_mfma_f32_16x16x32_bf16 v[114:117], v[178:181], v[186:189], v[114:117]
	v_mfma_f32_16x16x32_bf16 v[102:105], v[170:173], v[194:197], v[102:105]
	v_mfma_f32_16x16x32_bf16 v[98:101], v[178:181], v[194:197], v[98:101]
	v_mfma_f32_16x16x32_bf16 v[86:89], v[170:173], v[202:205], v[86:89]
	v_mfma_f32_16x16x32_bf16 v[82:85], v[178:181], v[202:205], v[82:85]
	v_mfma_f32_16x16x32_bf16 v[70:73], v[170:173], v[224:227], v[70:73]
	v_mfma_f32_16x16x32_bf16 v[66:69], v[178:181], v[224:227], v[66:69]
	s_setprio 0
	s_barrier
	s_add_i32 s64, s64, s71
	v_lshl_add_u64 v[210:211], s[56:57], 0, v[142:143]
	s_mov_b32 m0, s64
	ds_read_b128 v[182:185], v169 offset:16384
	ds_read_b128 v[186:189], v169 offset:17408
	ds_read_b128 v[190:193], v169 offset:18432
	ds_read_b128 v[194:197], v169 offset:19456
	ds_read_b128 v[198:201], v169 offset:20480
	ds_read_b128 v[202:205], v169 offset:21504
	ds_read_b128 v[206:209], v169 offset:22528
	ds_read_b128 v[224:227], v169 offset:23552
	global_load_lds_dwordx4 v[210:211], off
	s_add_i32 m0, s64, 0x2000
	s_add_u32 s64, s56, 0x40000
	v_lshl_add_u64 v[228:229], s[56:57], 0, v[138:139]
	s_addc_u32 s65, s57, 0
	s_add_i32 s86, s86, s71
	global_load_lds_dwordx4 v[228:229], off
	v_lshl_add_u64 v[230:231], s[64:65], 0, v[142:143]
	s_mov_b32 m0, s86
	v_lshl_add_u64 v[232:233], s[68:69], 0, v[140:141]
	global_load_lds_dwordx4 v[230:231], off
	v_lshl_add_u64 v[230:231], s[64:65], 0, v[138:139]
	s_add_i32 m0, s86, 0x2000
	s_nop 0
	global_load_lds_dwordx4 v[230:231], off
	v_lshl_add_u64 v[230:231], s[68:69], 0, v[144:145]
	s_mov_b32 m0, s21
	s_nop 0
	global_load_lds_dwordx4 v[230:231], off
	s_mov_b32 m0, s73
	s_nop 0
	global_load_lds_dwordx4 v[232:233], off
	s_waitcnt vmcnt(8)
	s_waitcnt lgkmcnt(0)
	s_barrier
	s_setprio 3
	v_mfma_f32_16x16x32_bf16 v[62:65], v[134:137], v[182:185], v[62:65]
	v_mfma_f32_16x16x32_bf16 v[58:61], v[154:157], v[182:185], v[58:61]
	v_mfma_f32_16x16x32_bf16 v[46:49], v[134:137], v[190:193], v[46:49]
	v_mfma_f32_16x16x32_bf16 v[42:45], v[154:157], v[190:193], v[42:45]
	v_mfma_f32_16x16x32_bf16 v[30:33], v[134:137], v[198:201], v[30:33]
	v_mfma_f32_16x16x32_bf16 v[26:29], v[154:157], v[198:201], v[26:29]
	v_mfma_f32_16x16x32_bf16 v[14:17], v[134:137], v[206:209], v[14:17]
	v_mfma_f32_16x16x32_bf16 v[10:13], v[154:157], v[206:209], v[10:13]
	v_mfma_f32_16x16x32_bf16 v[62:65], v[150:153], v[186:189], v[62:65]
	v_mfma_f32_16x16x32_bf16 v[58:61], v[158:161], v[186:189], v[58:61]
	v_mfma_f32_16x16x32_bf16 v[46:49], v[150:153], v[194:197], v[46:49]
	v_mfma_f32_16x16x32_bf16 v[42:45], v[158:161], v[194:197], v[42:45]
	v_mfma_f32_16x16x32_bf16 v[30:33], v[150:153], v[202:205], v[30:33]
	v_mfma_f32_16x16x32_bf16 v[26:29], v[158:161], v[202:205], v[26:29]
	v_mfma_f32_16x16x32_bf16 v[14:17], v[150:153], v[224:227], v[14:17]
	v_mfma_f32_16x16x32_bf16 v[10:13], v[158:161], v[224:227], v[10:13]
	v_mfma_f32_16x16x32_bf16 v[54:57], v[162:165], v[182:185], v[54:57]
	v_mfma_f32_16x16x32_bf16 v[50:53], v[174:177], v[182:185], v[50:53]
	v_mfma_f32_16x16x32_bf16 v[38:41], v[162:165], v[190:193], v[38:41]
	v_mfma_f32_16x16x32_bf16 v[34:37], v[174:177], v[190:193], v[34:37]
	v_mfma_f32_16x16x32_bf16 v[22:25], v[162:165], v[198:201], v[22:25]
	v_mfma_f32_16x16x32_bf16 v[18:21], v[174:177], v[198:201], v[18:21]
	v_mfma_f32_16x16x32_bf16 v[6:9], v[162:165], v[206:209], v[6:9]
	v_mfma_f32_16x16x32_bf16 v[2:5], v[174:177], v[206:209], v[2:5]
	v_mfma_f32_16x16x32_bf16 v[54:57], v[170:173], v[186:189], v[54:57]
	v_mfma_f32_16x16x32_bf16 v[50:53], v[178:181], v[186:189], v[50:53]
	v_mfma_f32_16x16x32_bf16 v[38:41], v[170:173], v[194:197], v[38:41]
	v_mfma_f32_16x16x32_bf16 v[34:37], v[178:181], v[194:197], v[34:37]
	v_mfma_f32_16x16x32_bf16 v[22:25], v[170:173], v[202:205], v[22:25]
	v_mfma_f32_16x16x32_bf16 v[18:21], v[178:181], v[202:205], v[18:21]
	v_mfma_f32_16x16x32_bf16 v[6:9], v[170:173], v[224:227], v[6:9]
	v_mfma_f32_16x16x32_bf16 v[2:5], v[178:181], v[224:227], v[2:5]
	s_setprio 0
	s_barrier
	s_add_i32 s86, 0, 0x18000
	v_add_u32_e32 v0, s86, v167
	s_add_i32 s87, 0, 0x1c000
	ds_read_b128 v[134:137], v0
	ds_read_b128 v[150:153], v0 offset:1024
	ds_read_b128 v[154:157], v0 offset:2048
	ds_read_b128 v[158:161], v0 offset:3072
	v_add_u32_e32 v0, s87, v167
	ds_read_b128 v[162:165], v0
	ds_read_b128 v[170:173], v0 offset:1024
	ds_read_b128 v[174:177], v0 offset:2048
	ds_read_b128 v[178:181], v0 offset:3072
	s_add_u32 s64, s68, 0x40000
	s_addc_u32 s65, s69, 0
	s_mov_b32 m0, s74
	v_lshl_add_u64 v[234:235], s[64:65], 0, v[144:145]
	ds_read_b128 v[182:185], v169 offset:32768
	ds_read_b128 v[186:189], v169 offset:33792
	ds_read_b128 v[190:193], v169 offset:34816
	ds_read_b128 v[194:197], v169 offset:35840
	ds_read_b128 v[198:201], v169 offset:36864
	ds_read_b128 v[202:205], v169 offset:37888
	ds_read_b128 v[206:209], v169 offset:38912
	ds_read_b128 v[224:227], v169 offset:39936
	global_load_lds_dwordx4 v[234:235], off
	v_lshl_add_u64 v[234:235], s[64:65], 0, v[140:141]
	s_mov_b32 m0, s75
	s_nop 0
	global_load_lds_dwordx4 v[234:235], off
	s_waitcnt vmcnt(8)
	s_waitcnt lgkmcnt(0)
	s_barrier
	s_setprio 3
	v_mfma_f32_16x16x32_bf16 v[126:129], v[134:137], v[182:185], v[126:129]
	v_mfma_f32_16x16x32_bf16 v[122:125], v[154:157], v[182:185], v[122:125]
	v_mfma_f32_16x16x32_bf16 v[110:113], v[134:137], v[190:193], v[110:113]
	v_mfma_f32_16x16x32_bf16 v[106:109], v[154:157], v[190:193], v[106:109]
	v_mfma_f32_16x16x32_bf16 v[94:97], v[134:137], v[198:201], v[94:97]
	v_mfma_f32_16x16x32_bf16 v[90:93], v[154:157], v[198:201], v[90:93]
	v_mfma_f32_16x16x32_bf16 v[78:81], v[134:137], v[206:209], v[78:81]
	v_mfma_f32_16x16x32_bf16 v[74:77], v[154:157], v[206:209], v[74:77]
	v_mfma_f32_16x16x32_bf16 v[126:129], v[150:153], v[186:189], v[126:129]
	v_mfma_f32_16x16x32_bf16 v[122:125], v[158:161], v[186:189], v[122:125]
	v_mfma_f32_16x16x32_bf16 v[110:113], v[150:153], v[194:197], v[110:113]
	v_mfma_f32_16x16x32_bf16 v[106:109], v[158:161], v[194:197], v[106:109]
	v_mfma_f32_16x16x32_bf16 v[94:97], v[150:153], v[202:205], v[94:97]
	v_mfma_f32_16x16x32_bf16 v[90:93], v[158:161], v[202:205], v[90:93]
	v_mfma_f32_16x16x32_bf16 v[78:81], v[150:153], v[224:227], v[78:81]
	v_mfma_f32_16x16x32_bf16 v[74:77], v[158:161], v[224:227], v[74:77]
	v_mfma_f32_16x16x32_bf16 v[118:121], v[162:165], v[182:185], v[118:121]
	v_mfma_f32_16x16x32_bf16 v[114:117], v[174:177], v[182:185], v[114:117]
	v_mfma_f32_16x16x32_bf16 v[102:105], v[162:165], v[190:193], v[102:105]
	v_mfma_f32_16x16x32_bf16 v[98:101], v[174:177], v[190:193], v[98:101]
	v_mfma_f32_16x16x32_bf16 v[86:89], v[162:165], v[198:201], v[86:89]
	v_mfma_f32_16x16x32_bf16 v[82:85], v[174:177], v[198:201], v[82:85]
	v_mfma_f32_16x16x32_bf16 v[70:73], v[162:165], v[206:209], v[70:73]
	v_mfma_f32_16x16x32_bf16 v[66:69], v[174:177], v[206:209], v[66:69]
	v_mfma_f32_16x16x32_bf16 v[118:121], v[170:173], v[186:189], v[118:121]
	v_mfma_f32_16x16x32_bf16 v[114:117], v[178:181], v[186:189], v[114:117]
	v_mfma_f32_16x16x32_bf16 v[102:105], v[170:173], v[194:197], v[102:105]
	v_mfma_f32_16x16x32_bf16 v[98:101], v[178:181], v[194:197], v[98:101]
	v_mfma_f32_16x16x32_bf16 v[86:89], v[170:173], v[202:205], v[86:89]
	v_mfma_f32_16x16x32_bf16 v[82:85], v[178:181], v[202:205], v[82:85]
	v_mfma_f32_16x16x32_bf16 v[70:73], v[170:173], v[224:227], v[70:73]
	v_mfma_f32_16x16x32_bf16 v[66:69], v[178:181], v[224:227], v[66:69]
	s_setprio 0
	s_barrier
	s_add_i32 s64, s86, s71
	v_lshl_add_u64 v[210:211], v[210:211], 0, s[48:49]
	s_mov_b32 m0, s64
	ds_read_b128 v[182:185], v169 offset:49152
	ds_read_b128 v[186:189], v169 offset:50176
	ds_read_b128 v[190:193], v169 offset:51200
	ds_read_b128 v[194:197], v169 offset:52224
	ds_read_b128 v[198:201], v169 offset:53248
	ds_read_b128 v[202:205], v169 offset:54272
	ds_read_b128 v[206:209], v169 offset:55296
	ds_read_b128 v[224:227], v169 offset:56320
	global_load_lds_dwordx4 v[210:211], off
	s_add_i32 m0, s64, 0x2000
	s_add_u32 s56, s56, 0x40080
	v_lshl_add_u64 v[210:211], v[228:229], 0, s[48:49]
	s_addc_u32 s57, s57, 0
	s_add_i32 s64, s87, s71
	global_load_lds_dwordx4 v[210:211], off
	v_lshl_add_u64 v[210:211], s[56:57], 0, v[142:143]
	s_mov_b32 m0, s64
	s_nop 0
	global_load_lds_dwordx4 v[210:211], off
	v_lshl_add_u64 v[210:211], s[56:57], 0, v[138:139]
	s_add_i32 m0, s64, 0x2000
	s_nop 0
	global_load_lds_dwordx4 v[210:211], off
	v_lshl_add_u64 v[210:211], v[230:231], 0, s[48:49]
	s_mov_b32 m0, s80
	s_nop 0
	global_load_lds_dwordx4 v[210:211], off
	v_lshl_add_u64 v[210:211], v[232:233], 0, s[48:49]
	s_mov_b32 m0, s81
	s_nop 0
	global_load_lds_dwordx4 v[210:211], off
	s_waitcnt vmcnt(8)
	s_waitcnt lgkmcnt(0)
	s_barrier
	s_setprio 3
	v_mfma_f32_16x16x32_bf16 v[62:65], v[134:137], v[182:185], v[62:65]
	v_mfma_f32_16x16x32_bf16 v[58:61], v[154:157], v[182:185], v[58:61]
	v_mfma_f32_16x16x32_bf16 v[46:49], v[134:137], v[190:193], v[46:49]
	v_mfma_f32_16x16x32_bf16 v[42:45], v[154:157], v[190:193], v[42:45]
	v_mfma_f32_16x16x32_bf16 v[30:33], v[134:137], v[198:201], v[30:33]
	v_mfma_f32_16x16x32_bf16 v[26:29], v[154:157], v[198:201], v[26:29]
	v_mfma_f32_16x16x32_bf16 v[14:17], v[134:137], v[206:209], v[14:17]
	v_mfma_f32_16x16x32_bf16 v[10:13], v[154:157], v[206:209], v[10:13]
	v_mfma_f32_16x16x32_bf16 v[62:65], v[150:153], v[186:189], v[62:65]
	v_mfma_f32_16x16x32_bf16 v[58:61], v[158:161], v[186:189], v[58:61]
	v_mfma_f32_16x16x32_bf16 v[46:49], v[150:153], v[194:197], v[46:49]
	v_mfma_f32_16x16x32_bf16 v[42:45], v[158:161], v[194:197], v[42:45]
	v_mfma_f32_16x16x32_bf16 v[30:33], v[150:153], v[202:205], v[30:33]
	v_mfma_f32_16x16x32_bf16 v[26:29], v[158:161], v[202:205], v[26:29]
	v_mfma_f32_16x16x32_bf16 v[14:17], v[150:153], v[224:227], v[14:17]
	v_mfma_f32_16x16x32_bf16 v[10:13], v[158:161], v[224:227], v[10:13]
	v_mfma_f32_16x16x32_bf16 v[54:57], v[162:165], v[182:185], v[54:57]
	v_mfma_f32_16x16x32_bf16 v[50:53], v[174:177], v[182:185], v[50:53]
	v_mfma_f32_16x16x32_bf16 v[38:41], v[162:165], v[190:193], v[38:41]
	v_mfma_f32_16x16x32_bf16 v[34:37], v[174:177], v[190:193], v[34:37]
	v_mfma_f32_16x16x32_bf16 v[22:25], v[162:165], v[198:201], v[22:25]
	v_mfma_f32_16x16x32_bf16 v[18:21], v[174:177], v[198:201], v[18:21]
	v_mfma_f32_16x16x32_bf16 v[6:9], v[162:165], v[206:209], v[6:9]
	v_mfma_f32_16x16x32_bf16 v[2:5], v[174:177], v[206:209], v[2:5]
	v_mfma_f32_16x16x32_bf16 v[54:57], v[170:173], v[186:189], v[54:57]
	v_mfma_f32_16x16x32_bf16 v[50:53], v[178:181], v[186:189], v[50:53]
	v_mfma_f32_16x16x32_bf16 v[38:41], v[170:173], v[194:197], v[38:41]
	v_mfma_f32_16x16x32_bf16 v[34:37], v[178:181], v[194:197], v[34:37]
	v_mfma_f32_16x16x32_bf16 v[22:25], v[170:173], v[202:205], v[22:25]
	v_mfma_f32_16x16x32_bf16 v[18:21], v[178:181], v[202:205], v[18:21]
	v_mfma_f32_16x16x32_bf16 v[6:9], v[170:173], v[224:227], v[6:9]
	v_mfma_f32_16x16x32_bf16 v[2:5], v[178:181], v[224:227], v[2:5]
	s_setprio 0
	s_barrier
	s_add_i32 s85, s85, 2
	s_add_u32 s52, s52, 0x100
	s_addc_u32 s53, s53, 0
	s_add_u32 s31, s31, 0x100
	s_addc_u32 s84, s84, 0
	s_cmp_gt_u32 s85, 13
	s_cbranch_scc0 .LBB0_1459
	s_and_b64 vcc, exec, s[6:7]
	s_cbranch_vccz .LBB0_1462
	s_barrier

.LBB0_1532:
	s_ashr_i32 s17, s16, 31
	s_lshl_b64 s[56:57], s[16:17], 18
	s_add_u32 s56, s37, s56
	s_addc_u32 s57, s60, s57
	s_and_b64 s[6:7], s[6:7], exec
	s_cselect_b32 s17, s57, s69
	s_cselect_b32 s19, s56, s68
	s_add_u32 s6, s70, 0x20080
	s_addc_u32 s7, s71, 0
	s_add_u32 s80, s68, 0x100
	s_addc_u32 s81, s69, 0
	s_mov_b32 s82, -2
	s_add_u32 s64, s6, 0xfffe0080
	s_addc_u32 s65, s7, -1
	s_add_i32 s83, 0, 0x10000
	s_cmp_eq_u32 s82, 4
	s_cselect_b32 s71, s53, s65
	s_cselect_b32 s70, s52, s64
	v_add_u32_e32 v144, s83, v147
	s_cselect_b32 s69, s17, s81
	s_cselect_b32 s68, s19, s80
	s_add_i32 s84, 0, 0x14000
	ds_read_b128 v[150:153], v144
	ds_read_b128 v[154:157], v144 offset:1024
	ds_read_b128 v[158:161], v144 offset:2048
	ds_read_b128 v[162:165], v144 offset:3072
	v_add_u32_e32 v144, s84, v147
	ds_read_b128 v[166:169], v144
	ds_read_b128 v[170:173], v144 offset:1024
	ds_read_b128 v[174:177], v144 offset:2048
	ds_read_b128 v[178:181], v144 offset:3072
	v_lshl_add_u64 v[144:145], s[6:7], 0, v[140:141]
	s_add_i32 m0, s21, 0xc000
	ds_read_b128 v[182:185], v149
	ds_read_b128 v[186:189], v149 offset:1024
	ds_read_b128 v[190:193], v149 offset:2048
	ds_read_b128 v[194:197], v149 offset:3072
	ds_read_b128 v[198:201], v149 offset:4096
	ds_read_b128 v[202:205], v149 offset:5120
	ds_read_b128 v[206:209], v149 offset:6144
	ds_read_b128 v[224:227], v149 offset:7168
	global_load_lds_dwordx4 v[144:145], off
	v_lshl_add_u64 v[144:145], s[6:7], 0, v[142:143]
	s_add_i32 m0, s21, 0xe000
	s_nop 0
	global_load_lds_dwordx4 v[144:145], off
	s_waitcnt vmcnt(8)
	s_waitcnt lgkmcnt(0)
	s_barrier
	s_setprio 3
	v_mfma_f32_16x16x32_bf16 v[126:129], v[150:153], v[182:185], 0
	v_mfma_f32_16x16x32_bf16 v[122:125], v[158:161], v[182:185], 0
	v_mfma_f32_16x16x32_bf16 v[118:121], v[150:153], v[190:193], 0
	v_mfma_f32_16x16x32_bf16 v[110:113], v[158:161], v[190:193], 0
	v_mfma_f32_16x16x32_bf16 v[102:105], v[150:153], v[198:201], 0
	v_mfma_f32_16x16x32_bf16 v[94:97], v[158:161], v[198:201], 0
	v_mfma_f32_16x16x32_bf16 v[86:89], v[150:153], v[206:209], 0
	v_mfma_f32_16x16x32_bf16 v[78:81], v[158:161], v[206:209], 0
	v_mfma_f32_16x16x32_bf16 v[126:129], v[154:157], v[186:189], v[126:129]
	v_mfma_f32_16x16x32_bf16 v[122:125], v[162:165], v[186:189], v[122:125]
	v_mfma_f32_16x16x32_bf16 v[118:121], v[154:157], v[194:197], v[118:121]
	v_mfma_f32_16x16x32_bf16 v[110:113], v[162:165], v[194:197], v[110:113]
	v_mfma_f32_16x16x32_bf16 v[102:105], v[154:157], v[202:205], v[102:105]
	v_mfma_f32_16x16x32_bf16 v[94:97], v[162:165], v[202:205], v[94:97]
	v_mfma_f32_16x16x32_bf16 v[86:89], v[154:157], v[224:227], v[86:89]
	v_mfma_f32_16x16x32_bf16 v[78:81], v[162:165], v[224:227], v[78:81]
	v_mfma_f32_16x16x32_bf16 v[114:117], v[166:169], v[182:185], 0
	v_mfma_f32_16x16x32_bf16 v[106:109], v[174:177], v[182:185], 0
	v_mfma_f32_16x16x32_bf16 v[98:101], v[166:169], v[190:193], 0
	v_mfma_f32_16x16x32_bf16 v[90:93], v[174:177], v[190:193], 0
	v_mfma_f32_16x16x32_bf16 v[82:85], v[166:169], v[198:201], 0
	v_mfma_f32_16x16x32_bf16 v[74:77], v[174:177], v[198:201], 0
	v_mfma_f32_16x16x32_bf16 v[70:73], v[166:169], v[206:209], 0
	v_mfma_f32_16x16x32_bf16 v[66:69], v[174:177], v[206:209], 0
	v_mfma_f32_16x16x32_bf16 v[114:117], v[170:173], v[186:189], v[114:117]
	v_mfma_f32_16x16x32_bf16 v[106:109], v[178:181], v[186:189], v[106:109]
	v_mfma_f32_16x16x32_bf16 v[98:101], v[170:173], v[194:197], v[98:101]
	v_mfma_f32_16x16x32_bf16 v[90:93], v[178:181], v[194:197], v[90:93]
	v_mfma_f32_16x16x32_bf16 v[82:85], v[170:173], v[202:205], v[82:85]
	v_mfma_f32_16x16x32_bf16 v[74:77], v[178:181], v[202:205], v[74:77]
	v_mfma_f32_16x16x32_bf16 v[70:73], v[170:173], v[224:227], v[70:73]
	v_mfma_f32_16x16x32_bf16 v[66:69], v[178:181], v[224:227], v[66:69]
	s_setprio 0
	s_barrier
	s_add_i32 s64, s83, s63
	v_lshl_add_u64 v[144:145], s[68:69], 0, v[0:1]
	s_mov_b32 m0, s64
	ds_read_b128 v[182:185], v149 offset:16384
	ds_read_b128 v[186:189], v149 offset:17408
	ds_read_b128 v[190:193], v149 offset:18432
	ds_read_b128 v[194:197], v149 offset:19456
	ds_read_b128 v[198:201], v149 offset:20480
	ds_read_b128 v[202:205], v149 offset:21504
	ds_read_b128 v[206:209], v149 offset:22528
	ds_read_b128 v[224:227], v149 offset:23552
	global_load_lds_dwordx4 v[144:145], off
	s_add_i32 m0, s64, 0x2000
	s_add_u32 s64, s68, 0x20000
	v_lshl_add_u64 v[210:211], s[68:69], 0, v[134:135]
	s_addc_u32 s65, s69, 0
	s_add_i32 s83, s84, s63
	global_load_lds_dwordx4 v[210:211], off
	v_lshl_add_u64 v[220:221], s[64:65], 0, v[0:1]
	s_mov_b32 m0, s83
	v_lshl_add_u64 v[228:229], s[70:71], 0, v[136:137]
	global_load_lds_dwordx4 v[220:221], off
	v_lshl_add_u64 v[220:221], s[64:65], 0, v[134:135]
	s_add_i32 m0, s83, 0x2000
	s_nop 0
	global_load_lds_dwordx4 v[220:221], off
	v_lshl_add_u64 v[220:221], s[70:71], 0, v[138:139]
	s_mov_b32 m0, s21
	s_nop 0
	global_load_lds_dwordx4 v[220:221], off
	s_mov_b32 m0, s27
	s_nop 0
	global_load_lds_dwordx4 v[228:229], off
	s_waitcnt vmcnt(8)
	s_waitcnt lgkmcnt(0)
	s_barrier
	s_setprio 3
	v_mfma_f32_16x16x32_bf16 v[62:65], v[150:153], v[182:185], 0
	v_mfma_f32_16x16x32_bf16 v[58:61], v[158:161], v[182:185], 0
	v_mfma_f32_16x16x32_bf16 v[54:57], v[150:153], v[190:193], 0
	v_mfma_f32_16x16x32_bf16 v[46:49], v[158:161], v[190:193], 0
	v_mfma_f32_16x16x32_bf16 v[38:41], v[150:153], v[198:201], 0
	v_mfma_f32_16x16x32_bf16 v[30:33], v[158:161], v[198:201], 0
	v_mfma_f32_16x16x32_bf16 v[22:25], v[150:153], v[206:209], 0
	v_mfma_f32_16x16x32_bf16 v[14:17], v[158:161], v[206:209], 0
	v_mfma_f32_16x16x32_bf16 v[62:65], v[154:157], v[186:189], v[62:65]
	v_mfma_f32_16x16x32_bf16 v[58:61], v[162:165], v[186:189], v[58:61]
	v_mfma_f32_16x16x32_bf16 v[54:57], v[154:157], v[194:197], v[54:57]
	v_mfma_f32_16x16x32_bf16 v[46:49], v[162:165], v[194:197], v[46:49]
	v_mfma_f32_16x16x32_bf16 v[38:41], v[154:157], v[202:205], v[38:41]
	v_mfma_f32_16x16x32_bf16 v[30:33], v[162:165], v[202:205], v[30:33]
	v_mfma_f32_16x16x32_bf16 v[22:25], v[154:157], v[224:227], v[22:25]
	v_mfma_f32_16x16x32_bf16 v[14:17], v[162:165], v[224:227], v[14:17]
	v_mfma_f32_16x16x32_bf16 v[50:53], v[166:169], v[182:185], 0
	v_mfma_f32_16x16x32_bf16 v[42:45], v[174:177], v[182:185], 0
	v_mfma_f32_16x16x32_bf16 v[34:37], v[166:169], v[190:193], 0
	v_mfma_f32_16x16x32_bf16 v[26:29], v[174:177], v[190:193], 0
	v_mfma_f32_16x16x32_bf16 v[18:21], v[166:169], v[198:201], 0
	v_mfma_f32_16x16x32_bf16 v[10:13], v[174:177], v[198:201], 0
	v_mfma_f32_16x16x32_bf16 v[6:9], v[166:169], v[206:209], 0
	v_mfma_f32_16x16x32_bf16 v[2:5], v[174:177], v[206:209], 0
	v_mfma_f32_16x16x32_bf16 v[50:53], v[170:173], v[186:189], v[50:53]
	v_mfma_f32_16x16x32_bf16 v[42:45], v[178:181], v[186:189], v[42:45]
	v_mfma_f32_16x16x32_bf16 v[34:37], v[170:173], v[194:197], v[34:37]
	v_mfma_f32_16x16x32_bf16 v[26:29], v[178:181], v[194:197], v[26:29]
	v_mfma_f32_16x16x32_bf16 v[18:21], v[170:173], v[202:205], v[18:21]
	v_mfma_f32_16x16x32_bf16 v[10:13], v[178:181], v[202:205], v[10:13]
	v_mfma_f32_16x16x32_bf16 v[6:9], v[170:173], v[224:227], v[6:9]
	v_mfma_f32_16x16x32_bf16 v[2:5], v[178:181], v[224:227], v[2:5]
	s_setprio 0
	s_barrier
	s_add_i32 s83, 0, 0x18000
	s_add_i32 s84, 0, 0x1c000
	v_add_u32_e32 v162, s83, v147
	v_add_u32_e32 v178, s84, v147
	ds_read_b128 v[150:153], v162
	ds_read_b128 v[154:157], v162 offset:1024
	ds_read_b128 v[158:161], v162 offset:2048
	ds_read_b128 v[162:165], v162 offset:3072
	ds_read_b128 v[166:169], v178
	ds_read_b128 v[170:173], v178 offset:1024
	ds_read_b128 v[174:177], v178 offset:2048
	ds_read_b128 v[178:181], v178 offset:3072
	s_add_u32 s64, s70, 0x20000
	s_addc_u32 s65, s71, 0
	s_mov_b32 m0, s72
	v_lshl_add_u64 v[230:231], s[64:65], 0, v[138:139]
	ds_read_b128 v[182:185], v149 offset:32768
	ds_read_b128 v[186:189], v149 offset:33792
	ds_read_b128 v[190:193], v149 offset:34816
	ds_read_b128 v[194:197], v149 offset:35840
	ds_read_b128 v[198:201], v149 offset:36864
	ds_read_b128 v[202:205], v149 offset:37888
	ds_read_b128 v[206:209], v149 offset:38912
	ds_read_b128 v[224:227], v149 offset:39936
	global_load_lds_dwordx4 v[230:231], off
	v_lshl_add_u64 v[230:231], s[64:65], 0, v[136:137]
	s_mov_b32 m0, s73
	s_nop 0
	global_load_lds_dwordx4 v[230:231], off
	s_waitcnt vmcnt(8)
	s_waitcnt lgkmcnt(0)
	s_barrier
	s_setprio 3
	v_mfma_f32_16x16x32_bf16 v[126:129], v[150:153], v[182:185], v[126:129]
	v_mfma_f32_16x16x32_bf16 v[122:125], v[158:161], v[182:185], v[122:125]
	v_mfma_f32_16x16x32_bf16 v[118:121], v[150:153], v[190:193], v[118:121]
	v_mfma_f32_16x16x32_bf16 v[110:113], v[158:161], v[190:193], v[110:113]
	v_mfma_f32_16x16x32_bf16 v[102:105], v[150:153], v[198:201], v[102:105]
	v_mfma_f32_16x16x32_bf16 v[94:97], v[158:161], v[198:201], v[94:97]
	v_mfma_f32_16x16x32_bf16 v[86:89], v[150:153], v[206:209], v[86:89]
	v_mfma_f32_16x16x32_bf16 v[78:81], v[158:161], v[206:209], v[78:81]
	v_mfma_f32_16x16x32_bf16 v[126:129], v[154:157], v[186:189], v[126:129]
	v_mfma_f32_16x16x32_bf16 v[122:125], v[162:165], v[186:189], v[122:125]
	v_mfma_f32_16x16x32_bf16 v[118:121], v[154:157], v[194:197], v[118:121]
	v_mfma_f32_16x16x32_bf16 v[110:113], v[162:165], v[194:197], v[110:113]
	v_mfma_f32_16x16x32_bf16 v[102:105], v[154:157], v[202:205], v[102:105]
	v_mfma_f32_16x16x32_bf16 v[94:97], v[162:165], v[202:205], v[94:97]
	v_mfma_f32_16x16x32_bf16 v[86:89], v[154:157], v[224:227], v[86:89]
	v_mfma_f32_16x16x32_bf16 v[78:81], v[162:165], v[224:227], v[78:81]
	v_mfma_f32_16x16x32_bf16 v[114:117], v[166:169], v[182:185], v[114:117]
	v_mfma_f32_16x16x32_bf16 v[106:109], v[174:177], v[182:185], v[106:109]
	v_mfma_f32_16x16x32_bf16 v[98:101], v[166:169], v[190:193], v[98:101]
	v_mfma_f32_16x16x32_bf16 v[90:93], v[174:177], v[190:193], v[90:93]
	v_mfma_f32_16x16x32_bf16 v[82:85], v[166:169], v[198:201], v[82:85]
	v_mfma_f32_16x16x32_bf16 v[74:77], v[174:177], v[198:201], v[74:77]
	v_mfma_f32_16x16x32_bf16 v[70:73], v[166:169], v[206:209], v[70:73]
	v_mfma_f32_16x16x32_bf16 v[66:69], v[174:177], v[206:209], v[66:69]
	v_mfma_f32_16x16x32_bf16 v[114:117], v[170:173], v[186:189], v[114:117]
	v_mfma_f32_16x16x32_bf16 v[106:109], v[178:181], v[186:189], v[106:109]
	v_mfma_f32_16x16x32_bf16 v[98:101], v[170:173], v[194:197], v[98:101]
	v_mfma_f32_16x16x32_bf16 v[90:93], v[178:181], v[194:197], v[90:93]
	v_mfma_f32_16x16x32_bf16 v[82:85], v[170:173], v[202:205], v[82:85]
	v_mfma_f32_16x16x32_bf16 v[74:77], v[178:181], v[202:205], v[74:77]
	v_mfma_f32_16x16x32_bf16 v[70:73], v[170:173], v[224:227], v[70:73]
	v_mfma_f32_16x16x32_bf16 v[66:69], v[178:181], v[224:227], v[66:69]
	s_setprio 0
	s_barrier
	s_add_i32 s64, s83, s63
	v_lshl_add_u64 v[144:145], v[144:145], 0, s[48:49]
	s_mov_b32 m0, s64
	ds_read_b128 v[182:185], v149 offset:49152
	ds_read_b128 v[186:189], v149 offset:50176
	ds_read_b128 v[190:193], v149 offset:51200
	ds_read_b128 v[194:197], v149 offset:52224
	ds_read_b128 v[198:201], v149 offset:53248
	ds_read_b128 v[202:205], v149 offset:54272
	ds_read_b128 v[206:209], v149 offset:55296
	ds_read_b128 v[224:227], v149 offset:56320
	global_load_lds_dwordx4 v[144:145], off
	s_add_i32 m0, s64, 0x2000
	s_add_u32 s64, s68, 0x20080
	v_lshl_add_u64 v[144:145], v[210:211], 0, s[48:49]
	s_addc_u32 s65, s69, 0
	s_add_i32 s68, s84, s63
	global_load_lds_dwordx4 v[144:145], off
	v_lshl_add_u64 v[144:145], s[64:65], 0, v[0:1]
	s_mov_b32 m0, s68
	s_nop 0
	global_load_lds_dwordx4 v[144:145], off
	v_lshl_add_u64 v[144:145], s[64:65], 0, v[134:135]
	s_add_i32 m0, s68, 0x2000
	s_nop 0
	global_load_lds_dwordx4 v[144:145], off
	v_lshl_add_u64 v[144:145], v[220:221], 0, s[48:49]
	s_mov_b32 m0, s74
	s_nop 0
	global_load_lds_dwordx4 v[144:145], off
	v_lshl_add_u64 v[144:145], v[228:229], 0, s[48:49]
	s_mov_b32 m0, s75
	s_nop 0
	global_load_lds_dwordx4 v[144:145], off
	s_waitcnt vmcnt(8)
	s_waitcnt lgkmcnt(0)
	s_barrier
	s_setprio 3
	v_mfma_f32_16x16x32_bf16 v[62:65], v[150:153], v[182:185], v[62:65]
	v_mfma_f32_16x16x32_bf16 v[58:61], v[158:161], v[182:185], v[58:61]
	v_mfma_f32_16x16x32_bf16 v[54:57], v[150:153], v[190:193], v[54:57]
	v_mfma_f32_16x16x32_bf16 v[46:49], v[158:161], v[190:193], v[46:49]
	v_mfma_f32_16x16x32_bf16 v[38:41], v[150:153], v[198:201], v[38:41]
	v_mfma_f32_16x16x32_bf16 v[30:33], v[158:161], v[198:201], v[30:33]
	v_mfma_f32_16x16x32_bf16 v[22:25], v[150:153], v[206:209], v[22:25]
	v_mfma_f32_16x16x32_bf16 v[14:17], v[158:161], v[206:209], v[14:17]
	v_mfma_f32_16x16x32_bf16 v[62:65], v[154:157], v[186:189], v[62:65]
	v_mfma_f32_16x16x32_bf16 v[58:61], v[162:165], v[186:189], v[58:61]
	v_mfma_f32_16x16x32_bf16 v[54:57], v[154:157], v[194:197], v[54:57]
	v_mfma_f32_16x16x32_bf16 v[46:49], v[162:165], v[194:197], v[46:49]
	v_mfma_f32_16x16x32_bf16 v[38:41], v[154:157], v[202:205], v[38:41]
	v_mfma_f32_16x16x32_bf16 v[30:33], v[162:165], v[202:205], v[30:33]
	v_mfma_f32_16x16x32_bf16 v[22:25], v[154:157], v[224:227], v[22:25]
	v_mfma_f32_16x16x32_bf16 v[14:17], v[162:165], v[224:227], v[14:17]
	v_mfma_f32_16x16x32_bf16 v[50:53], v[166:169], v[182:185], v[50:53]
	v_mfma_f32_16x16x32_bf16 v[42:45], v[174:177], v[182:185], v[42:45]
	v_mfma_f32_16x16x32_bf16 v[34:37], v[166:169], v[190:193], v[34:37]
	v_mfma_f32_16x16x32_bf16 v[26:29], v[174:177], v[190:193], v[26:29]
	v_mfma_f32_16x16x32_bf16 v[18:21], v[166:169], v[198:201], v[18:21]
	v_mfma_f32_16x16x32_bf16 v[10:13], v[174:177], v[198:201], v[10:13]
	v_mfma_f32_16x16x32_bf16 v[6:9], v[166:169], v[206:209], v[6:9]
	v_mfma_f32_16x16x32_bf16 v[2:5], v[174:177], v[206:209], v[2:5]
	v_mfma_f32_16x16x32_bf16 v[50:53], v[170:173], v[186:189], v[50:53]
	v_mfma_f32_16x16x32_bf16 v[42:45], v[178:181], v[186:189], v[42:45]
	v_mfma_f32_16x16x32_bf16 v[34:37], v[170:173], v[194:197], v[34:37]
	v_mfma_f32_16x16x32_bf16 v[26:29], v[178:181], v[194:197], v[26:29]
	v_mfma_f32_16x16x32_bf16 v[18:21], v[170:173], v[202:205], v[18:21]
	v_mfma_f32_16x16x32_bf16 v[10:13], v[178:181], v[202:205], v[10:13]
	v_mfma_f32_16x16x32_bf16 v[6:9], v[170:173], v[224:227], v[6:9]
	v_mfma_f32_16x16x32_bf16 v[2:5], v[178:181], v[224:227], v[2:5]
	s_setprio 0
	s_barrier
	s_add_i32 s82, s82, 2
	s_add_u32 s6, s6, 0x100
	s_addc_u32 s7, s7, 0
	s_add_u32 s80, s80, 0x100
	s_addc_u32 s81, s81, 0
.LBB0_1533:
	s_add_u32 s64, s6, 0xfffe0080
	s_addc_u32 s65, s7, -1
	s_add_i32 s83, 0, 0x10000
	s_cmp_eq_u32 s82, 4
	s_cselect_b32 s71, s53, s65
	s_cselect_b32 s70, s52, s64
	v_add_u32_e32 v144, s83, v147
	s_cselect_b32 s69, s17, s81
	s_cselect_b32 s68, s19, s80
	s_add_i32 s84, 0, 0x14000
	ds_read_b128 v[150:153], v144
	ds_read_b128 v[154:157], v144 offset:1024
	ds_read_b128 v[158:161], v144 offset:2048
	ds_read_b128 v[162:165], v144 offset:3072
	v_add_u32_e32 v144, s84, v147
	ds_read_b128 v[166:169], v144
	ds_read_b128 v[170:173], v144 offset:1024
	ds_read_b128 v[174:177], v144 offset:2048
	ds_read_b128 v[178:181], v144 offset:3072
	v_lshl_add_u64 v[144:145], s[6:7], 0, v[140:141]
	s_add_i32 m0, s21, 0xc000
	ds_read_b128 v[182:185], v149
	ds_read_b128 v[186:189], v149 offset:1024
	ds_read_b128 v[190:193], v149 offset:2048
	ds_read_b128 v[194:197], v149 offset:3072
	ds_read_b128 v[198:201], v149 offset:4096
	ds_read_b128 v[202:205], v149 offset:5120
	ds_read_b128 v[206:209], v149 offset:6144
	ds_read_b128 v[224:227], v149 offset:7168
	global_load_lds_dwordx4 v[144:145], off
	v_lshl_add_u64 v[144:145], s[6:7], 0, v[142:143]
	s_add_i32 m0, s21, 0xe000
	s_nop 0
	global_load_lds_dwordx4 v[144:145], off
	s_waitcnt vmcnt(8)
	s_waitcnt lgkmcnt(0)
	s_barrier
	s_setprio 3
	v_mfma_f32_16x16x32_bf16 v[126:129], v[150:153], v[182:185], v[126:129]
	v_mfma_f32_16x16x32_bf16 v[122:125], v[158:161], v[182:185], v[122:125]
	v_mfma_f32_16x16x32_bf16 v[118:121], v[150:153], v[190:193], v[118:121]
	v_mfma_f32_16x16x32_bf16 v[110:113], v[158:161], v[190:193], v[110:113]
	v_mfma_f32_16x16x32_bf16 v[102:105], v[150:153], v[198:201], v[102:105]
	v_mfma_f32_16x16x32_bf16 v[94:97], v[158:161], v[198:201], v[94:97]
	v_mfma_f32_16x16x32_bf16 v[86:89], v[150:153], v[206:209], v[86:89]
	v_mfma_f32_16x16x32_bf16 v[78:81], v[158:161], v[206:209], v[78:81]
	v_mfma_f32_16x16x32_bf16 v[126:129], v[154:157], v[186:189], v[126:129]
	v_mfma_f32_16x16x32_bf16 v[122:125], v[162:165], v[186:189], v[122:125]
	v_mfma_f32_16x16x32_bf16 v[118:121], v[154:157], v[194:197], v[118:121]
	v_mfma_f32_16x16x32_bf16 v[110:113], v[162:165], v[194:197], v[110:113]
	v_mfma_f32_16x16x32_bf16 v[102:105], v[154:157], v[202:205], v[102:105]
	v_mfma_f32_16x16x32_bf16 v[94:97], v[162:165], v[202:205], v[94:97]
	v_mfma_f32_16x16x32_bf16 v[86:89], v[154:157], v[224:227], v[86:89]
	v_mfma_f32_16x16x32_bf16 v[78:81], v[162:165], v[224:227], v[78:81]
	v_mfma_f32_16x16x32_bf16 v[114:117], v[166:169], v[182:185], v[114:117]
	v_mfma_f32_16x16x32_bf16 v[106:109], v[174:177], v[182:185], v[106:109]
	v_mfma_f32_16x16x32_bf16 v[98:101], v[166:169], v[190:193], v[98:101]
	v_mfma_f32_16x16x32_bf16 v[90:93], v[174:177], v[190:193], v[90:93]
	v_mfma_f32_16x16x32_bf16 v[82:85], v[166:169], v[198:201], v[82:85]
	v_mfma_f32_16x16x32_bf16 v[74:77], v[174:177], v[198:201], v[74:77]
	v_mfma_f32_16x16x32_bf16 v[70:73], v[166:169], v[206:209], v[70:73]
	v_mfma_f32_16x16x32_bf16 v[66:69], v[174:177], v[206:209], v[66:69]
	v_mfma_f32_16x16x32_bf16 v[114:117], v[170:173], v[186:189], v[114:117]
	v_mfma_f32_16x16x32_bf16 v[106:109], v[178:181], v[186:189], v[106:109]
	v_mfma_f32_16x16x32_bf16 v[98:101], v[170:173], v[194:197], v[98:101]
	v_mfma_f32_16x16x32_bf16 v[90:93], v[178:181], v[194:197], v[90:93]
	v_mfma_f32_16x16x32_bf16 v[82:85], v[170:173], v[202:205], v[82:85]
	v_mfma_f32_16x16x32_bf16 v[74:77], v[178:181], v[202:205], v[74:77]
	v_mfma_f32_16x16x32_bf16 v[70:73], v[170:173], v[224:227], v[70:73]
	v_mfma_f32_16x16x32_bf16 v[66:69], v[178:181], v[224:227], v[66:69]
	s_setprio 0
	s_barrier
	s_add_i32 s64, s83, s63
	v_lshl_add_u64 v[144:145], s[68:69], 0, v[0:1]
	s_mov_b32 m0, s64
	ds_read_b128 v[182:185], v149 offset:16384
	ds_read_b128 v[186:189], v149 offset:17408
	ds_read_b128 v[190:193], v149 offset:18432
	ds_read_b128 v[194:197], v149 offset:19456
	ds_read_b128 v[198:201], v149 offset:20480
	ds_read_b128 v[202:205], v149 offset:21504
	ds_read_b128 v[206:209], v149 offset:22528
	ds_read_b128 v[224:227], v149 offset:23552
	global_load_lds_dwordx4 v[144:145], off
	s_add_i32 m0, s64, 0x2000
	s_add_u32 s64, s68, 0x20000
	v_lshl_add_u64 v[210:211], s[68:69], 0, v[134:135]
	s_addc_u32 s65, s69, 0
	s_add_i32 s83, s84, s63
	global_load_lds_dwordx4 v[210:211], off
	v_lshl_add_u64 v[220:221], s[64:65], 0, v[0:1]
	s_mov_b32 m0, s83
	v_lshl_add_u64 v[228:229], s[70:71], 0, v[136:137]
	global_load_lds_dwordx4 v[220:221], off
	v_lshl_add_u64 v[220:221], s[64:65], 0, v[134:135]
	s_add_i32 m0, s83, 0x2000
	s_nop 0
	global_load_lds_dwordx4 v[220:221], off
	v_lshl_add_u64 v[220:221], s[70:71], 0, v[138:139]
	s_mov_b32 m0, s21
	s_nop 0
	global_load_lds_dwordx4 v[220:221], off
	s_mov_b32 m0, s27
	s_nop 0
	global_load_lds_dwordx4 v[228:229], off
	s_waitcnt vmcnt(8)
	s_waitcnt lgkmcnt(0)
	s_barrier
	s_setprio 3
	v_mfma_f32_16x16x32_bf16 v[62:65], v[150:153], v[182:185], v[62:65]
	v_mfma_f32_16x16x32_bf16 v[58:61], v[158:161], v[182:185], v[58:61]
	v_mfma_f32_16x16x32_bf16 v[54:57], v[150:153], v[190:193], v[54:57]
	v_mfma_f32_16x16x32_bf16 v[46:49], v[158:161], v[190:193], v[46:49]
	v_mfma_f32_16x16x32_bf16 v[38:41], v[150:153], v[198:201], v[38:41]
	v_mfma_f32_16x16x32_bf16 v[30:33], v[158:161], v[198:201], v[30:33]
	v_mfma_f32_16x16x32_bf16 v[22:25], v[150:153], v[206:209], v[22:25]
	v_mfma_f32_16x16x32_bf16 v[14:17], v[158:161], v[206:209], v[14:17]
	v_mfma_f32_16x16x32_bf16 v[62:65], v[154:157], v[186:189], v[62:65]
	v_mfma_f32_16x16x32_bf16 v[58:61], v[162:165], v[186:189], v[58:61]
	v_mfma_f32_16x16x32_bf16 v[54:57], v[154:157], v[194:197], v[54:57]
	v_mfma_f32_16x16x32_bf16 v[46:49], v[162:165], v[194:197], v[46:49]
	v_mfma_f32_16x16x32_bf16 v[38:41], v[154:157], v[202:205], v[38:41]
	v_mfma_f32_16x16x32_bf16 v[30:33], v[162:165], v[202:205], v[30:33]
	v_mfma_f32_16x16x32_bf16 v[22:25], v[154:157], v[224:227], v[22:25]
	v_mfma_f32_16x16x32_bf16 v[14:17], v[162:165], v[224:227], v[14:17]
	v_mfma_f32_16x16x32_bf16 v[50:53], v[166:169], v[182:185], v[50:53]
	v_mfma_f32_16x16x32_bf16 v[42:45], v[174:177], v[182:185], v[42:45]
	v_mfma_f32_16x16x32_bf16 v[34:37], v[166:169], v[190:193], v[34:37]
	v_mfma_f32_16x16x32_bf16 v[26:29], v[174:177], v[190:193], v[26:29]
	v_mfma_f32_16x16x32_bf16 v[18:21], v[166:169], v[198:201], v[18:21]
	v_mfma_f32_16x16x32_bf16 v[10:13], v[174:177], v[198:201], v[10:13]
	v_mfma_f32_16x16x32_bf16 v[6:9], v[166:169], v[206:209], v[6:9]
	v_mfma_f32_16x16x32_bf16 v[2:5], v[174:177], v[206:209], v[2:5]
	v_mfma_f32_16x16x32_bf16 v[50:53], v[170:173], v[186:189], v[50:53]
	v_mfma_f32_16x16x32_bf16 v[42:45], v[178:181], v[186:189], v[42:45]
	v_mfma_f32_16x16x32_bf16 v[34:37], v[170:173], v[194:197], v[34:37]
	v_mfma_f32_16x16x32_bf16 v[26:29], v[178:181], v[194:197], v[26:29]
	v_mfma_f32_16x16x32_bf16 v[18:21], v[170:173], v[202:205], v[18:21]
	v_mfma_f32_16x16x32_bf16 v[10:13], v[178:181], v[202:205], v[10:13]
	v_mfma_f32_16x16x32_bf16 v[6:9], v[170:173], v[224:227], v[6:9]
	v_mfma_f32_16x16x32_bf16 v[2:5], v[178:181], v[224:227], v[2:5]
	s_setprio 0
	s_barrier
	s_add_i32 s83, 0, 0x18000
	s_add_i32 s84, 0, 0x1c000
	v_add_u32_e32 v162, s83, v147
	v_add_u32_e32 v178, s84, v147
	ds_read_b128 v[150:153], v162
	ds_read_b128 v[154:157], v162 offset:1024
	ds_read_b128 v[158:161], v162 offset:2048
	ds_read_b128 v[162:165], v162 offset:3072
	ds_read_b128 v[166:169], v178
	ds_read_b128 v[170:173], v178 offset:1024
	ds_read_b128 v[174:177], v178 offset:2048
	ds_read_b128 v[178:181], v178 offset:3072
	s_add_u32 s64, s70, 0x20000
	s_addc_u32 s65, s71, 0
	s_mov_b32 m0, s72
	v_lshl_add_u64 v[230:231], s[64:65], 0, v[138:139]
	ds_read_b128 v[182:185], v149 offset:32768
	ds_read_b128 v[186:189], v149 offset:33792
	ds_read_b128 v[190:193], v149 offset:34816
	ds_read_b128 v[194:197], v149 offset:35840
	ds_read_b128 v[198:201], v149 offset:36864
	ds_read_b128 v[202:205], v149 offset:37888
	ds_read_b128 v[206:209], v149 offset:38912
	ds_read_b128 v[224:227], v149 offset:39936
	global_load_lds_dwordx4 v[230:231], off
	v_lshl_add_u64 v[230:231], s[64:65], 0, v[136:137]
	s_mov_b32 m0, s73
	s_nop 0
	global_load_lds_dwordx4 v[230:231], off
	s_waitcnt vmcnt(8)
	s_waitcnt lgkmcnt(0)
	s_barrier
	s_setprio 3
	v_mfma_f32_16x16x32_bf16 v[126:129], v[150:153], v[182:185], v[126:129]
	v_mfma_f32_16x16x32_bf16 v[122:125], v[158:161], v[182:185], v[122:125]
	v_mfma_f32_16x16x32_bf16 v[118:121], v[150:153], v[190:193], v[118:121]
	v_mfma_f32_16x16x32_bf16 v[110:113], v[158:161], v[190:193], v[110:113]
	v_mfma_f32_16x16x32_bf16 v[102:105], v[150:153], v[198:201], v[102:105]
	v_mfma_f32_16x16x32_bf16 v[94:97], v[158:161], v[198:201], v[94:97]
	v_mfma_f32_16x16x32_bf16 v[86:89], v[150:153], v[206:209], v[86:89]
	v_mfma_f32_16x16x32_bf16 v[78:81], v[158:161], v[206:209], v[78:81]
	v_mfma_f32_16x16x32_bf16 v[126:129], v[154:157], v[186:189], v[126:129]
	v_mfma_f32_16x16x32_bf16 v[122:125], v[162:165], v[186:189], v[122:125]
	v_mfma_f32_16x16x32_bf16 v[118:121], v[154:157], v[194:197], v[118:121]
	v_mfma_f32_16x16x32_bf16 v[110:113], v[162:165], v[194:197], v[110:113]
	v_mfma_f32_16x16x32_bf16 v[102:105], v[154:157], v[202:205], v[102:105]
	v_mfma_f32_16x16x32_bf16 v[94:97], v[162:165], v[202:205], v[94:97]
	v_mfma_f32_16x16x32_bf16 v[86:89], v[154:157], v[224:227], v[86:89]
	v_mfma_f32_16x16x32_bf16 v[78:81], v[162:165], v[224:227], v[78:81]
	v_mfma_f32_16x16x32_bf16 v[114:117], v[166:169], v[182:185], v[114:117]
	v_mfma_f32_16x16x32_bf16 v[106:109], v[174:177], v[182:185], v[106:109]
	v_mfma_f32_16x16x32_bf16 v[98:101], v[166:169], v[190:193], v[98:101]
	v_mfma_f32_16x16x32_bf16 v[90:93], v[174:177], v[190:193], v[90:93]
	v_mfma_f32_16x16x32_bf16 v[82:85], v[166:169], v[198:201], v[82:85]
	v_mfma_f32_16x16x32_bf16 v[74:77], v[174:177], v[198:201], v[74:77]
	v_mfma_f32_16x16x32_bf16 v[70:73], v[166:169], v[206:209], v[70:73]
	v_mfma_f32_16x16x32_bf16 v[66:69], v[174:177], v[206:209], v[66:69]
	v_mfma_f32_16x16x32_bf16 v[114:117], v[170:173], v[186:189], v[114:117]
	v_mfma_f32_16x16x32_bf16 v[106:109], v[178:181], v[186:189], v[106:109]
	v_mfma_f32_16x16x32_bf16 v[98:101], v[170:173], v[194:197], v[98:101]
	v_mfma_f32_16x16x32_bf16 v[90:93], v[178:181], v[194:197], v[90:93]
	v_mfma_f32_16x16x32_bf16 v[82:85], v[170:173], v[202:205], v[82:85]
	v_mfma_f32_16x16x32_bf16 v[74:77], v[178:181], v[202:205], v[74:77]
	v_mfma_f32_16x16x32_bf16 v[70:73], v[170:173], v[224:227], v[70:73]
	v_mfma_f32_16x16x32_bf16 v[66:69], v[178:181], v[224:227], v[66:69]
	s_setprio 0
	s_barrier
	s_add_i32 s64, s83, s63
	v_lshl_add_u64 v[144:145], v[144:145], 0, s[48:49]
	s_mov_b32 m0, s64
	ds_read_b128 v[182:185], v149 offset:49152
	ds_read_b128 v[186:189], v149 offset:50176
	ds_read_b128 v[190:193], v149 offset:51200
	ds_read_b128 v[194:197], v149 offset:52224
	ds_read_b128 v[198:201], v149 offset:53248
	ds_read_b128 v[202:205], v149 offset:54272
	ds_read_b128 v[206:209], v149 offset:55296
	ds_read_b128 v[224:227], v149 offset:56320
	global_load_lds_dwordx4 v[144:145], off
	s_add_i32 m0, s64, 0x2000
	s_add_u32 s64, s68, 0x20080
	v_lshl_add_u64 v[144:145], v[210:211], 0, s[48:49]
	s_addc_u32 s65, s69, 0
	s_add_i32 s68, s84, s63
	global_load_lds_dwordx4 v[144:145], off
	v_lshl_add_u64 v[144:145], s[64:65], 0, v[0:1]
	s_mov_b32 m0, s68
	s_nop 0
	global_load_lds_dwordx4 v[144:145], off
	v_lshl_add_u64 v[144:145], s[64:65], 0, v[134:135]
	s_add_i32 m0, s68, 0x2000
	s_nop 0
	global_load_lds_dwordx4 v[144:145], off
	v_lshl_add_u64 v[144:145], v[220:221], 0, s[48:49]
	s_mov_b32 m0, s74
	s_nop 0
	global_load_lds_dwordx4 v[144:145], off
	v_lshl_add_u64 v[144:145], v[228:229], 0, s[48:49]
	s_mov_b32 m0, s75
	s_nop 0
	global_load_lds_dwordx4 v[144:145], off
	s_waitcnt vmcnt(8)
	s_waitcnt lgkmcnt(0)
	s_barrier
	s_setprio 3
	v_mfma_f32_16x16x32_bf16 v[62:65], v[150:153], v[182:185], v[62:65]
	v_mfma_f32_16x16x32_bf16 v[58:61], v[158:161], v[182:185], v[58:61]
	v_mfma_f32_16x16x32_bf16 v[54:57], v[150:153], v[190:193], v[54:57]
	v_mfma_f32_16x16x32_bf16 v[46:49], v[158:161], v[190:193], v[46:49]
	v_mfma_f32_16x16x32_bf16 v[38:41], v[150:153], v[198:201], v[38:41]
	v_mfma_f32_16x16x32_bf16 v[30:33], v[158:161], v[198:201], v[30:33]
	v_mfma_f32_16x16x32_bf16 v[22:25], v[150:153], v[206:209], v[22:25]
	v_mfma_f32_16x16x32_bf16 v[14:17], v[158:161], v[206:209], v[14:17]
	v_mfma_f32_16x16x32_bf16 v[62:65], v[154:157], v[186:189], v[62:65]
	v_mfma_f32_16x16x32_bf16 v[58:61], v[162:165], v[186:189], v[58:61]
	v_mfma_f32_16x16x32_bf16 v[54:57], v[154:157], v[194:197], v[54:57]
	v_mfma_f32_16x16x32_bf16 v[46:49], v[162:165], v[194:197], v[46:49]
	v_mfma_f32_16x16x32_bf16 v[38:41], v[154:157], v[202:205], v[38:41]
	v_mfma_f32_16x16x32_bf16 v[30:33], v[162:165], v[202:205], v[30:33]
	v_mfma_f32_16x16x32_bf16 v[22:25], v[154:157], v[224:227], v[22:25]
	v_mfma_f32_16x16x32_bf16 v[14:17], v[162:165], v[224:227], v[14:17]
	v_mfma_f32_16x16x32_bf16 v[50:53], v[166:169], v[182:185], v[50:53]
	v_mfma_f32_16x16x32_bf16 v[42:45], v[174:177], v[182:185], v[42:45]
	v_mfma_f32_16x16x32_bf16 v[34:37], v[166:169], v[190:193], v[34:37]
	v_mfma_f32_16x16x32_bf16 v[26:29], v[174:177], v[190:193], v[26:29]
	v_mfma_f32_16x16x32_bf16 v[18:21], v[166:169], v[198:201], v[18:21]
	v_mfma_f32_16x16x32_bf16 v[10:13], v[174:177], v[198:201], v[10:13]
	v_mfma_f32_16x16x32_bf16 v[6:9], v[166:169], v[206:209], v[6:9]
	v_mfma_f32_16x16x32_bf16 v[2:5], v[174:177], v[206:209], v[2:5]
	v_mfma_f32_16x16x32_bf16 v[50:53], v[170:173], v[186:189], v[50:53]
	v_mfma_f32_16x16x32_bf16 v[42:45], v[178:181], v[186:189], v[42:45]
	v_mfma_f32_16x16x32_bf16 v[34:37], v[170:173], v[194:197], v[34:37]
	v_mfma_f32_16x16x32_bf16 v[26:29], v[178:181], v[194:197], v[26:29]
	v_mfma_f32_16x16x32_bf16 v[18:21], v[170:173], v[202:205], v[18:21]
	v_mfma_f32_16x16x32_bf16 v[10:13], v[178:181], v[202:205], v[10:13]
	v_mfma_f32_16x16x32_bf16 v[6:9], v[170:173], v[224:227], v[6:9]
	v_mfma_f32_16x16x32_bf16 v[2:5], v[178:181], v[224:227], v[2:5]
	s_setprio 0
	s_barrier
	s_add_i32 s82, s82, 2
	s_add_u32 s6, s6, 0x100
	s_addc_u32 s7, s7, 0
	s_add_u32 s80, s80, 0x100
	s_addc_u32 s81, s81, 0
	s_cmp_gt_u32 s82, 5
	s_cbranch_scc0 .LBB0_1533
	s_and_b64 vcc, exec, s[12:13]
	s_cbranch_vccnz .LBB0_1537
	s_cmp_gt_i32 s20, 15
	s_cbranch_scc0 .LBB0_1538

.LBB0_1602:
	s_ashr_i32 s13, s16, 3
	s_add_i32 s13, s16, s13
	s_and_b64 s[18:19], s[66:67], s[4:5]
	s_add_i32 s13, s13, 1
	s_and_b64 s[18:19], s[18:19], exec
	s_cselect_b32 s16, s13, s16
	s_ashr_i32 s17, s16, 31
	s_lshl_b64 s[18:19], s[16:17], 19
	s_add_u32 s18, s37, s18
	s_addc_u32 s19, s60, s19
	s_and_b64 s[20:21], s[4:5], exec
	s_cselect_b32 s17, s19, s57
	s_cselect_b32 s27, s18, s56
	s_ashr_i32 s13, s12, 31
	s_lshl_b64 s[20:21], s[12:13], 19
	s_add_u32 s20, s63, s20
	s_addc_u32 s21, s72, s21
	s_and_b64 s[30:31], s[4:5], exec
	s_cselect_b32 s13, s21, s69
	s_cselect_b32 s30, s20, s68
	s_add_u32 s56, s56, 0x40080
	s_addc_u32 s57, s57, 0
	s_add_u32 s31, s68, 0x100
	s_addc_u32 s85, s69, 0
	s_mov_b32 s86, -2
	s_add_u32 s64, s56, 0xfffc0080
	s_addc_u32 s65, s57, -1
	s_add_i32 s87, 0, 0x10000
	s_cmp_eq_u32 s86, 12
	s_cselect_b32 s71, s17, s65
	s_cselect_b32 s70, s27, s64
	v_add_u32_e32 v144, s87, v147
	s_cselect_b32 s69, s13, s85
	s_cselect_b32 s68, s30, s31
	s_add_i32 s88, 0, 0x14000
	ds_read_b128 v[140:143], v144
	ds_read_b128 v[150:153], v144 offset:1024
	ds_read_b128 v[154:157], v144 offset:2048
	ds_read_b128 v[158:161], v144 offset:3072
	v_add_u32_e32 v144, s88, v147
	ds_read_b128 v[162:165], v144
	ds_read_b128 v[166:169], v144 offset:1024
	ds_read_b128 v[170:173], v144 offset:2048
	ds_read_b128 v[174:177], v144 offset:3072
	v_lshl_add_u64 v[144:145], s[56:57], 0, v[136:137]
	s_add_i32 m0, s53, 0xc000
	ds_read_b128 v[178:181], v149
	ds_read_b128 v[182:185], v149 offset:1024
	ds_read_b128 v[186:189], v149 offset:2048
	ds_read_b128 v[190:193], v149 offset:3072
	ds_read_b128 v[194:197], v149 offset:4096
	ds_read_b128 v[198:201], v149 offset:5120
	ds_read_b128 v[202:205], v149 offset:6144
	ds_read_b128 v[206:209], v149 offset:7168
	global_load_lds_dwordx4 v[144:145], off
	v_lshl_add_u64 v[144:145], s[56:57], 0, v[138:139]
	s_add_i32 m0, s53, 0xe000
	s_nop 0
	global_load_lds_dwordx4 v[144:145], off
	s_waitcnt vmcnt(8)
	s_waitcnt lgkmcnt(0)
	s_barrier
	s_setprio 3
	v_mfma_f32_16x16x32_bf16 v[126:129], v[140:143], v[178:181], 0
	v_mfma_f32_16x16x32_bf16 v[122:125], v[154:157], v[178:181], 0
	v_mfma_f32_16x16x32_bf16 v[110:113], v[140:143], v[186:189], 0
	v_mfma_f32_16x16x32_bf16 v[106:109], v[154:157], v[186:189], 0
	v_mfma_f32_16x16x32_bf16 v[94:97], v[140:143], v[194:197], 0
	v_mfma_f32_16x16x32_bf16 v[90:93], v[154:157], v[194:197], 0
	v_mfma_f32_16x16x32_bf16 v[78:81], v[140:143], v[202:205], 0
	v_mfma_f32_16x16x32_bf16 v[74:77], v[154:157], v[202:205], 0
	v_mfma_f32_16x16x32_bf16 v[126:129], v[150:153], v[182:185], v[126:129]
	v_mfma_f32_16x16x32_bf16 v[122:125], v[158:161], v[182:185], v[122:125]
	v_mfma_f32_16x16x32_bf16 v[110:113], v[150:153], v[190:193], v[110:113]
	v_mfma_f32_16x16x32_bf16 v[106:109], v[158:161], v[190:193], v[106:109]
	v_mfma_f32_16x16x32_bf16 v[94:97], v[150:153], v[198:201], v[94:97]
	v_mfma_f32_16x16x32_bf16 v[90:93], v[158:161], v[198:201], v[90:93]
	v_mfma_f32_16x16x32_bf16 v[78:81], v[150:153], v[206:209], v[78:81]
	v_mfma_f32_16x16x32_bf16 v[74:77], v[158:161], v[206:209], v[74:77]
	v_mfma_f32_16x16x32_bf16 v[118:121], v[162:165], v[178:181], 0
	v_mfma_f32_16x16x32_bf16 v[114:117], v[170:173], v[178:181], 0
	v_mfma_f32_16x16x32_bf16 v[102:105], v[162:165], v[186:189], 0
	v_mfma_f32_16x16x32_bf16 v[98:101], v[170:173], v[186:189], 0
	v_mfma_f32_16x16x32_bf16 v[86:89], v[162:165], v[194:197], 0
	v_mfma_f32_16x16x32_bf16 v[82:85], v[170:173], v[194:197], 0
	v_mfma_f32_16x16x32_bf16 v[70:73], v[162:165], v[202:205], 0
	v_mfma_f32_16x16x32_bf16 v[66:69], v[170:173], v[202:205], 0
	v_mfma_f32_16x16x32_bf16 v[118:121], v[166:169], v[182:185], v[118:121]
	v_mfma_f32_16x16x32_bf16 v[114:117], v[174:177], v[182:185], v[114:117]
	v_mfma_f32_16x16x32_bf16 v[102:105], v[166:169], v[190:193], v[102:105]
	v_mfma_f32_16x16x32_bf16 v[98:101], v[174:177], v[190:193], v[98:101]
	v_mfma_f32_16x16x32_bf16 v[86:89], v[166:169], v[198:201], v[86:89]
	v_mfma_f32_16x16x32_bf16 v[82:85], v[174:177], v[198:201], v[82:85]
	v_mfma_f32_16x16x32_bf16 v[70:73], v[166:169], v[206:209], v[70:73]
	v_mfma_f32_16x16x32_bf16 v[66:69], v[174:177], v[206:209], v[66:69]
	s_setprio 0
	s_barrier
	s_add_i32 s64, s87, s73
	v_lshl_add_u64 v[144:145], s[68:69], 0, v[0:1]
	s_mov_b32 m0, s64
	ds_read_b128 v[178:181], v149 offset:16384
	ds_read_b128 v[182:185], v149 offset:17408
	ds_read_b128 v[186:189], v149 offset:18432
	ds_read_b128 v[190:193], v149 offset:19456
	ds_read_b128 v[194:197], v149 offset:20480
	ds_read_b128 v[198:201], v149 offset:21504
	ds_read_b128 v[202:205], v149 offset:22528
	ds_read_b128 v[206:209], v149 offset:23552
	global_load_lds_dwordx4 v[144:145], off
	s_add_i32 m0, s64, 0x2000
	s_add_u32 s64, s68, 0x40000
	v_lshl_add_u64 v[210:211], s[68:69], 0, v[134:135]
	s_addc_u32 s65, s69, 0
	s_add_i32 s87, s88, s73
	global_load_lds_dwordx4 v[210:211], off
	v_lshl_add_u64 v[220:221], s[64:65], 0, v[0:1]
	s_mov_b32 m0, s87
	v_lshl_add_u64 v[224:225], s[70:71], 0, v[134:135]
	global_load_lds_dwordx4 v[220:221], off
	v_lshl_add_u64 v[220:221], s[64:65], 0, v[134:135]
	s_add_i32 m0, s87, 0x2000
	s_nop 0
	global_load_lds_dwordx4 v[220:221], off
	v_lshl_add_u64 v[220:221], s[70:71], 0, v[0:1]
	s_mov_b32 m0, s53
	s_nop 0
	global_load_lds_dwordx4 v[220:221], off
	s_mov_b32 m0, s78
	s_nop 0
	global_load_lds_dwordx4 v[224:225], off
	s_waitcnt vmcnt(8)
	s_waitcnt lgkmcnt(0)
	s_barrier
	s_setprio 3
	v_mfma_f32_16x16x32_bf16 v[62:65], v[140:143], v[178:181], 0
	v_mfma_f32_16x16x32_bf16 v[58:61], v[154:157], v[178:181], 0
	v_mfma_f32_16x16x32_bf16 v[46:49], v[140:143], v[186:189], 0
	v_mfma_f32_16x16x32_bf16 v[42:45], v[154:157], v[186:189], 0
	v_mfma_f32_16x16x32_bf16 v[30:33], v[140:143], v[194:197], 0
	v_mfma_f32_16x16x32_bf16 v[26:29], v[154:157], v[194:197], 0
	v_mfma_f32_16x16x32_bf16 v[14:17], v[140:143], v[202:205], 0
	v_mfma_f32_16x16x32_bf16 v[10:13], v[154:157], v[202:205], 0
	v_mfma_f32_16x16x32_bf16 v[62:65], v[150:153], v[182:185], v[62:65]
	v_mfma_f32_16x16x32_bf16 v[58:61], v[158:161], v[182:185], v[58:61]
	v_mfma_f32_16x16x32_bf16 v[46:49], v[150:153], v[190:193], v[46:49]
	v_mfma_f32_16x16x32_bf16 v[42:45], v[158:161], v[190:193], v[42:45]
	v_mfma_f32_16x16x32_bf16 v[30:33], v[150:153], v[198:201], v[30:33]
	v_mfma_f32_16x16x32_bf16 v[26:29], v[158:161], v[198:201], v[26:29]
	v_mfma_f32_16x16x32_bf16 v[14:17], v[150:153], v[206:209], v[14:17]
	v_mfma_f32_16x16x32_bf16 v[10:13], v[158:161], v[206:209], v[10:13]
	v_mfma_f32_16x16x32_bf16 v[54:57], v[162:165], v[178:181], 0
	v_mfma_f32_16x16x32_bf16 v[50:53], v[170:173], v[178:181], 0
	v_mfma_f32_16x16x32_bf16 v[38:41], v[162:165], v[186:189], 0
	v_mfma_f32_16x16x32_bf16 v[34:37], v[170:173], v[186:189], 0
	v_mfma_f32_16x16x32_bf16 v[22:25], v[162:165], v[194:197], 0
	v_mfma_f32_16x16x32_bf16 v[18:21], v[170:173], v[194:197], 0
	v_mfma_f32_16x16x32_bf16 v[6:9], v[162:165], v[202:205], 0
	v_mfma_f32_16x16x32_bf16 v[2:5], v[170:173], v[202:205], 0
	v_mfma_f32_16x16x32_bf16 v[54:57], v[166:169], v[182:185], v[54:57]
	v_mfma_f32_16x16x32_bf16 v[50:53], v[174:177], v[182:185], v[50:53]
	v_mfma_f32_16x16x32_bf16 v[38:41], v[166:169], v[190:193], v[38:41]
	v_mfma_f32_16x16x32_bf16 v[34:37], v[174:177], v[190:193], v[34:37]
	v_mfma_f32_16x16x32_bf16 v[22:25], v[166:169], v[198:201], v[22:25]
	v_mfma_f32_16x16x32_bf16 v[18:21], v[174:177], v[198:201], v[18:21]
	v_mfma_f32_16x16x32_bf16 v[6:9], v[166:169], v[206:209], v[6:9]
	v_mfma_f32_16x16x32_bf16 v[2:5], v[174:177], v[206:209], v[2:5]
	s_setprio 0
	s_barrier
	s_add_i32 s87, 0, 0x18000
	s_add_i32 s88, 0, 0x1c000
	v_add_u32_e32 v158, s87, v147
	v_add_u32_e32 v174, s88, v147
	ds_read_b128 v[140:143], v158
	ds_read_b128 v[150:153], v158 offset:1024
	ds_read_b128 v[154:157], v158 offset:2048
	ds_read_b128 v[158:161], v158 offset:3072
	ds_read_b128 v[162:165], v174
	ds_read_b128 v[166:169], v174 offset:1024
	ds_read_b128 v[170:173], v174 offset:2048
	ds_read_b128 v[174:177], v174 offset:3072
	s_add_u32 s64, s70, 0x40000
	s_addc_u32 s65, s71, 0
	s_mov_b32 m0, s79
	v_lshl_add_u64 v[226:227], s[64:65], 0, v[0:1]
	ds_read_b128 v[178:181], v149 offset:32768
	ds_read_b128 v[182:185], v149 offset:33792
	ds_read_b128 v[186:189], v149 offset:34816
	ds_read_b128 v[190:193], v149 offset:35840
	ds_read_b128 v[194:197], v149 offset:36864
	ds_read_b128 v[198:201], v149 offset:37888
	ds_read_b128 v[202:205], v149 offset:38912
	ds_read_b128 v[206:209], v149 offset:39936
	global_load_lds_dwordx4 v[226:227], off
	v_lshl_add_u64 v[226:227], s[64:65], 0, v[134:135]
	s_mov_b32 m0, s80
	s_nop 0
	global_load_lds_dwordx4 v[226:227], off
	s_waitcnt vmcnt(8)
	s_waitcnt lgkmcnt(0)
	s_barrier
	s_setprio 3
	v_mfma_f32_16x16x32_bf16 v[126:129], v[140:143], v[178:181], v[126:129]
	v_mfma_f32_16x16x32_bf16 v[122:125], v[154:157], v[178:181], v[122:125]
	v_mfma_f32_16x16x32_bf16 v[110:113], v[140:143], v[186:189], v[110:113]
	v_mfma_f32_16x16x32_bf16 v[106:109], v[154:157], v[186:189], v[106:109]
	v_mfma_f32_16x16x32_bf16 v[94:97], v[140:143], v[194:197], v[94:97]
	v_mfma_f32_16x16x32_bf16 v[90:93], v[154:157], v[194:197], v[90:93]
	v_mfma_f32_16x16x32_bf16 v[78:81], v[140:143], v[202:205], v[78:81]
	v_mfma_f32_16x16x32_bf16 v[74:77], v[154:157], v[202:205], v[74:77]
	v_mfma_f32_16x16x32_bf16 v[126:129], v[150:153], v[182:185], v[126:129]
	v_mfma_f32_16x16x32_bf16 v[122:125], v[158:161], v[182:185], v[122:125]
	v_mfma_f32_16x16x32_bf16 v[110:113], v[150:153], v[190:193], v[110:113]
	v_mfma_f32_16x16x32_bf16 v[106:109], v[158:161], v[190:193], v[106:109]
	v_mfma_f32_16x16x32_bf16 v[94:97], v[150:153], v[198:201], v[94:97]
	v_mfma_f32_16x16x32_bf16 v[90:93], v[158:161], v[198:201], v[90:93]
	v_mfma_f32_16x16x32_bf16 v[78:81], v[150:153], v[206:209], v[78:81]
	v_mfma_f32_16x16x32_bf16 v[74:77], v[158:161], v[206:209], v[74:77]
	v_mfma_f32_16x16x32_bf16 v[118:121], v[162:165], v[178:181], v[118:121]
	v_mfma_f32_16x16x32_bf16 v[114:117], v[170:173], v[178:181], v[114:117]
	v_mfma_f32_16x16x32_bf16 v[102:105], v[162:165], v[186:189], v[102:105]
	v_mfma_f32_16x16x32_bf16 v[98:101], v[170:173], v[186:189], v[98:101]
	v_mfma_f32_16x16x32_bf16 v[86:89], v[162:165], v[194:197], v[86:89]
	v_mfma_f32_16x16x32_bf16 v[82:85], v[170:173], v[194:197], v[82:85]
	v_mfma_f32_16x16x32_bf16 v[70:73], v[162:165], v[202:205], v[70:73]
	v_mfma_f32_16x16x32_bf16 v[66:69], v[170:173], v[202:205], v[66:69]
	v_mfma_f32_16x16x32_bf16 v[118:121], v[166:169], v[182:185], v[118:121]
	v_mfma_f32_16x16x32_bf16 v[114:117], v[174:177], v[182:185], v[114:117]
	v_mfma_f32_16x16x32_bf16 v[102:105], v[166:169], v[190:193], v[102:105]
	v_mfma_f32_16x16x32_bf16 v[98:101], v[174:177], v[190:193], v[98:101]
	v_mfma_f32_16x16x32_bf16 v[86:89], v[166:169], v[198:201], v[86:89]
	v_mfma_f32_16x16x32_bf16 v[82:85], v[174:177], v[198:201], v[82:85]
	v_mfma_f32_16x16x32_bf16 v[70:73], v[166:169], v[206:209], v[70:73]
	v_mfma_f32_16x16x32_bf16 v[66:69], v[174:177], v[206:209], v[66:69]
	s_setprio 0
	s_barrier
	s_add_i32 s64, s87, s73
	v_lshl_add_u64 v[144:145], v[144:145], 0, s[48:49]
	s_mov_b32 m0, s64
	ds_read_b128 v[178:181], v149 offset:49152
	ds_read_b128 v[182:185], v149 offset:50176
	ds_read_b128 v[186:189], v149 offset:51200
	ds_read_b128 v[190:193], v149 offset:52224
	ds_read_b128 v[194:197], v149 offset:53248
	ds_read_b128 v[198:201], v149 offset:54272
	ds_read_b128 v[202:205], v149 offset:55296
	ds_read_b128 v[206:209], v149 offset:56320
	global_load_lds_dwordx4 v[144:145], off
	s_add_i32 m0, s64, 0x2000
	s_add_u32 s64, s68, 0x40080
	v_lshl_add_u64 v[144:145], v[210:211], 0, s[48:49]
	s_addc_u32 s65, s69, 0
	s_add_i32 s68, s88, s73
	global_load_lds_dwordx4 v[144:145], off
	v_lshl_add_u64 v[144:145], s[64:65], 0, v[0:1]
	s_mov_b32 m0, s68
	s_nop 0
	global_load_lds_dwordx4 v[144:145], off
	v_lshl_add_u64 v[144:145], s[64:65], 0, v[134:135]
	s_add_i32 m0, s68, 0x2000
	s_nop 0
	global_load_lds_dwordx4 v[144:145], off
	v_lshl_add_u64 v[144:145], v[220:221], 0, s[48:49]
	s_mov_b32 m0, s81
	s_nop 0
	global_load_lds_dwordx4 v[144:145], off
	v_lshl_add_u64 v[144:145], v[224:225], 0, s[48:49]
	s_mov_b32 m0, s82
	s_nop 0
	global_load_lds_dwordx4 v[144:145], off
	s_waitcnt vmcnt(8)
	s_waitcnt lgkmcnt(0)
	s_barrier
	s_setprio 3
	v_mfma_f32_16x16x32_bf16 v[62:65], v[140:143], v[178:181], v[62:65]
	v_mfma_f32_16x16x32_bf16 v[58:61], v[154:157], v[178:181], v[58:61]
	v_mfma_f32_16x16x32_bf16 v[46:49], v[140:143], v[186:189], v[46:49]
	v_mfma_f32_16x16x32_bf16 v[42:45], v[154:157], v[186:189], v[42:45]
	v_mfma_f32_16x16x32_bf16 v[30:33], v[140:143], v[194:197], v[30:33]
	v_mfma_f32_16x16x32_bf16 v[26:29], v[154:157], v[194:197], v[26:29]
	v_mfma_f32_16x16x32_bf16 v[14:17], v[140:143], v[202:205], v[14:17]
	v_mfma_f32_16x16x32_bf16 v[10:13], v[154:157], v[202:205], v[10:13]
	v_mfma_f32_16x16x32_bf16 v[62:65], v[150:153], v[182:185], v[62:65]
	v_mfma_f32_16x16x32_bf16 v[58:61], v[158:161], v[182:185], v[58:61]
	v_mfma_f32_16x16x32_bf16 v[46:49], v[150:153], v[190:193], v[46:49]
	v_mfma_f32_16x16x32_bf16 v[42:45], v[158:161], v[190:193], v[42:45]
	v_mfma_f32_16x16x32_bf16 v[30:33], v[150:153], v[198:201], v[30:33]
	v_mfma_f32_16x16x32_bf16 v[26:29], v[158:161], v[198:201], v[26:29]
	v_mfma_f32_16x16x32_bf16 v[14:17], v[150:153], v[206:209], v[14:17]
	v_mfma_f32_16x16x32_bf16 v[10:13], v[158:161], v[206:209], v[10:13]
	v_mfma_f32_16x16x32_bf16 v[54:57], v[162:165], v[178:181], v[54:57]
	v_mfma_f32_16x16x32_bf16 v[50:53], v[170:173], v[178:181], v[50:53]
	v_mfma_f32_16x16x32_bf16 v[38:41], v[162:165], v[186:189], v[38:41]
	v_mfma_f32_16x16x32_bf16 v[34:37], v[170:173], v[186:189], v[34:37]
	v_mfma_f32_16x16x32_bf16 v[22:25], v[162:165], v[194:197], v[22:25]
	v_mfma_f32_16x16x32_bf16 v[18:21], v[170:173], v[194:197], v[18:21]
	v_mfma_f32_16x16x32_bf16 v[6:9], v[162:165], v[202:205], v[6:9]
	v_mfma_f32_16x16x32_bf16 v[2:5], v[170:173], v[202:205], v[2:5]
	v_mfma_f32_16x16x32_bf16 v[54:57], v[166:169], v[182:185], v[54:57]
	v_mfma_f32_16x16x32_bf16 v[50:53], v[174:177], v[182:185], v[50:53]
	v_mfma_f32_16x16x32_bf16 v[38:41], v[166:169], v[190:193], v[38:41]
	v_mfma_f32_16x16x32_bf16 v[34:37], v[174:177], v[190:193], v[34:37]
	v_mfma_f32_16x16x32_bf16 v[22:25], v[166:169], v[198:201], v[22:25]
	v_mfma_f32_16x16x32_bf16 v[18:21], v[174:177], v[198:201], v[18:21]
	v_mfma_f32_16x16x32_bf16 v[6:9], v[166:169], v[206:209], v[6:9]
	v_mfma_f32_16x16x32_bf16 v[2:5], v[174:177], v[206:209], v[2:5]
	s_setprio 0
	s_barrier
	s_add_i32 s86, s86, 2
	s_add_u32 s56, s56, 0x100
	s_addc_u32 s57, s57, 0
	s_add_u32 s31, s31, 0x100
	s_addc_u32 s85, s85, 0
.LBB0_1603:
	s_add_u32 s64, s56, 0xfffc0080
	s_addc_u32 s65, s57, -1
	s_add_i32 s87, 0, 0x10000
	s_cmp_eq_u32 s86, 12
	s_cselect_b32 s71, s17, s65
	s_cselect_b32 s70, s27, s64
	v_add_u32_e32 v144, s87, v147
	s_cselect_b32 s69, s13, s85
	s_cselect_b32 s68, s30, s31
	s_add_i32 s88, 0, 0x14000
	ds_read_b128 v[140:143], v144
	ds_read_b128 v[150:153], v144 offset:1024
	ds_read_b128 v[154:157], v144 offset:2048
	ds_read_b128 v[158:161], v144 offset:3072
	v_add_u32_e32 v144, s88, v147
	ds_read_b128 v[162:165], v144
	ds_read_b128 v[166:169], v144 offset:1024
	ds_read_b128 v[170:173], v144 offset:2048
	ds_read_b128 v[174:177], v144 offset:3072
	v_lshl_add_u64 v[144:145], s[56:57], 0, v[136:137]
	s_add_i32 m0, s53, 0xc000
	ds_read_b128 v[178:181], v149
	ds_read_b128 v[182:185], v149 offset:1024
	ds_read_b128 v[186:189], v149 offset:2048
	ds_read_b128 v[190:193], v149 offset:3072
	ds_read_b128 v[194:197], v149 offset:4096
	ds_read_b128 v[198:201], v149 offset:5120
	ds_read_b128 v[202:205], v149 offset:6144
	ds_read_b128 v[206:209], v149 offset:7168
	global_load_lds_dwordx4 v[144:145], off
	v_lshl_add_u64 v[144:145], s[56:57], 0, v[138:139]
	s_add_i32 m0, s53, 0xe000
	s_nop 0
	global_load_lds_dwordx4 v[144:145], off
	s_waitcnt vmcnt(8)
	s_waitcnt lgkmcnt(0)
	s_barrier
	s_setprio 3
	v_mfma_f32_16x16x32_bf16 v[126:129], v[140:143], v[178:181], v[126:129]
	v_mfma_f32_16x16x32_bf16 v[122:125], v[154:157], v[178:181], v[122:125]
	v_mfma_f32_16x16x32_bf16 v[110:113], v[140:143], v[186:189], v[110:113]
	v_mfma_f32_16x16x32_bf16 v[106:109], v[154:157], v[186:189], v[106:109]
	v_mfma_f32_16x16x32_bf16 v[94:97], v[140:143], v[194:197], v[94:97]
	v_mfma_f32_16x16x32_bf16 v[90:93], v[154:157], v[194:197], v[90:93]
	v_mfma_f32_16x16x32_bf16 v[78:81], v[140:143], v[202:205], v[78:81]
	v_mfma_f32_16x16x32_bf16 v[74:77], v[154:157], v[202:205], v[74:77]
	v_mfma_f32_16x16x32_bf16 v[126:129], v[150:153], v[182:185], v[126:129]
	v_mfma_f32_16x16x32_bf16 v[122:125], v[158:161], v[182:185], v[122:125]
	v_mfma_f32_16x16x32_bf16 v[110:113], v[150:153], v[190:193], v[110:113]
	v_mfma_f32_16x16x32_bf16 v[106:109], v[158:161], v[190:193], v[106:109]
	v_mfma_f32_16x16x32_bf16 v[94:97], v[150:153], v[198:201], v[94:97]
	v_mfma_f32_16x16x32_bf16 v[90:93], v[158:161], v[198:201], v[90:93]
	v_mfma_f32_16x16x32_bf16 v[78:81], v[150:153], v[206:209], v[78:81]
	v_mfma_f32_16x16x32_bf16 v[74:77], v[158:161], v[206:209], v[74:77]
	v_mfma_f32_16x16x32_bf16 v[118:121], v[162:165], v[178:181], v[118:121]
	v_mfma_f32_16x16x32_bf16 v[114:117], v[170:173], v[178:181], v[114:117]
	v_mfma_f32_16x16x32_bf16 v[102:105], v[162:165], v[186:189], v[102:105]
	v_mfma_f32_16x16x32_bf16 v[98:101], v[170:173], v[186:189], v[98:101]
	v_mfma_f32_16x16x32_bf16 v[86:89], v[162:165], v[194:197], v[86:89]
	v_mfma_f32_16x16x32_bf16 v[82:85], v[170:173], v[194:197], v[82:85]
	v_mfma_f32_16x16x32_bf16 v[70:73], v[162:165], v[202:205], v[70:73]
	v_mfma_f32_16x16x32_bf16 v[66:69], v[170:173], v[202:205], v[66:69]
	v_mfma_f32_16x16x32_bf16 v[118:121], v[166:169], v[182:185], v[118:121]
	v_mfma_f32_16x16x32_bf16 v[114:117], v[174:177], v[182:185], v[114:117]
	v_mfma_f32_16x16x32_bf16 v[102:105], v[166:169], v[190:193], v[102:105]
	v_mfma_f32_16x16x32_bf16 v[98:101], v[174:177], v[190:193], v[98:101]
	v_mfma_f32_16x16x32_bf16 v[86:89], v[166:169], v[198:201], v[86:89]
	v_mfma_f32_16x16x32_bf16 v[82:85], v[174:177], v[198:201], v[82:85]
	v_mfma_f32_16x16x32_bf16 v[70:73], v[166:169], v[206:209], v[70:73]
	v_mfma_f32_16x16x32_bf16 v[66:69], v[174:177], v[206:209], v[66:69]
	s_setprio 0
	s_barrier
	s_add_i32 s64, s87, s73
	v_lshl_add_u64 v[144:145], s[68:69], 0, v[0:1]
	s_mov_b32 m0, s64
	ds_read_b128 v[178:181], v149 offset:16384
	ds_read_b128 v[182:185], v149 offset:17408
	ds_read_b128 v[186:189], v149 offset:18432
	ds_read_b128 v[190:193], v149 offset:19456
	ds_read_b128 v[194:197], v149 offset:20480
	ds_read_b128 v[198:201], v149 offset:21504
	ds_read_b128 v[202:205], v149 offset:22528
	ds_read_b128 v[206:209], v149 offset:23552
	global_load_lds_dwordx4 v[144:145], off
	s_add_i32 m0, s64, 0x2000
	s_add_u32 s64, s68, 0x40000
	v_lshl_add_u64 v[210:211], s[68:69], 0, v[134:135]
	s_addc_u32 s65, s69, 0
	s_add_i32 s87, s88, s73
	global_load_lds_dwordx4 v[210:211], off
	v_lshl_add_u64 v[220:221], s[64:65], 0, v[0:1]
	s_mov_b32 m0, s87
	v_lshl_add_u64 v[224:225], s[70:71], 0, v[134:135]
	global_load_lds_dwordx4 v[220:221], off
	v_lshl_add_u64 v[220:221], s[64:65], 0, v[134:135]
	s_add_i32 m0, s87, 0x2000
	s_nop 0
	global_load_lds_dwordx4 v[220:221], off
	v_lshl_add_u64 v[220:221], s[70:71], 0, v[0:1]
	s_mov_b32 m0, s53
	s_nop 0
	global_load_lds_dwordx4 v[220:221], off
	s_mov_b32 m0, s78
	s_nop 0
	global_load_lds_dwordx4 v[224:225], off
	s_waitcnt vmcnt(8)
	s_waitcnt lgkmcnt(0)
	s_barrier
	s_setprio 3
	v_mfma_f32_16x16x32_bf16 v[62:65], v[140:143], v[178:181], v[62:65]
	v_mfma_f32_16x16x32_bf16 v[58:61], v[154:157], v[178:181], v[58:61]
	v_mfma_f32_16x16x32_bf16 v[46:49], v[140:143], v[186:189], v[46:49]
	v_mfma_f32_16x16x32_bf16 v[42:45], v[154:157], v[186:189], v[42:45]
	v_mfma_f32_16x16x32_bf16 v[30:33], v[140:143], v[194:197], v[30:33]
	v_mfma_f32_16x16x32_bf16 v[26:29], v[154:157], v[194:197], v[26:29]
	v_mfma_f32_16x16x32_bf16 v[14:17], v[140:143], v[202:205], v[14:17]
	v_mfma_f32_16x16x32_bf16 v[10:13], v[154:157], v[202:205], v[10:13]
	v_mfma_f32_16x16x32_bf16 v[62:65], v[150:153], v[182:185], v[62:65]
	v_mfma_f32_16x16x32_bf16 v[58:61], v[158:161], v[182:185], v[58:61]
	v_mfma_f32_16x16x32_bf16 v[46:49], v[150:153], v[190:193], v[46:49]
	v_mfma_f32_16x16x32_bf16 v[42:45], v[158:161], v[190:193], v[42:45]
	v_mfma_f32_16x16x32_bf16 v[30:33], v[150:153], v[198:201], v[30:33]
	v_mfma_f32_16x16x32_bf16 v[26:29], v[158:161], v[198:201], v[26:29]
	v_mfma_f32_16x16x32_bf16 v[14:17], v[150:153], v[206:209], v[14:17]
	v_mfma_f32_16x16x32_bf16 v[10:13], v[158:161], v[206:209], v[10:13]
	v_mfma_f32_16x16x32_bf16 v[54:57], v[162:165], v[178:181], v[54:57]
	v_mfma_f32_16x16x32_bf16 v[50:53], v[170:173], v[178:181], v[50:53]
	v_mfma_f32_16x16x32_bf16 v[38:41], v[162:165], v[186:189], v[38:41]
	v_mfma_f32_16x16x32_bf16 v[34:37], v[170:173], v[186:189], v[34:37]
	v_mfma_f32_16x16x32_bf16 v[22:25], v[162:165], v[194:197], v[22:25]
	v_mfma_f32_16x16x32_bf16 v[18:21], v[170:173], v[194:197], v[18:21]
	v_mfma_f32_16x16x32_bf16 v[6:9], v[162:165], v[202:205], v[6:9]
	v_mfma_f32_16x16x32_bf16 v[2:5], v[170:173], v[202:205], v[2:5]
	v_mfma_f32_16x16x32_bf16 v[54:57], v[166:169], v[182:185], v[54:57]
	v_mfma_f32_16x16x32_bf16 v[50:53], v[174:177], v[182:185], v[50:53]
	v_mfma_f32_16x16x32_bf16 v[38:41], v[166:169], v[190:193], v[38:41]
	v_mfma_f32_16x16x32_bf16 v[34:37], v[174:177], v[190:193], v[34:37]
	v_mfma_f32_16x16x32_bf16 v[22:25], v[166:169], v[198:201], v[22:25]
	v_mfma_f32_16x16x32_bf16 v[18:21], v[174:177], v[198:201], v[18:21]
	v_mfma_f32_16x16x32_bf16 v[6:9], v[166:169], v[206:209], v[6:9]
	v_mfma_f32_16x16x32_bf16 v[2:5], v[174:177], v[206:209], v[2:5]
	s_setprio 0
	s_barrier
	s_add_i32 s87, 0, 0x18000
	s_add_i32 s88, 0, 0x1c000
	v_add_u32_e32 v158, s87, v147
	v_add_u32_e32 v174, s88, v147
	ds_read_b128 v[140:143], v158
	ds_read_b128 v[150:153], v158 offset:1024
	ds_read_b128 v[154:157], v158 offset:2048
	ds_read_b128 v[158:161], v158 offset:3072
	ds_read_b128 v[162:165], v174
	ds_read_b128 v[166:169], v174 offset:1024
	ds_read_b128 v[170:173], v174 offset:2048
	ds_read_b128 v[174:177], v174 offset:3072
	s_add_u32 s64, s70, 0x40000
	s_addc_u32 s65, s71, 0
	s_mov_b32 m0, s79
	v_lshl_add_u64 v[226:227], s[64:65], 0, v[0:1]
	ds_read_b128 v[178:181], v149 offset:32768
	ds_read_b128 v[182:185], v149 offset:33792
	ds_read_b128 v[186:189], v149 offset:34816
	ds_read_b128 v[190:193], v149 offset:35840
	ds_read_b128 v[194:197], v149 offset:36864
	ds_read_b128 v[198:201], v149 offset:37888
	ds_read_b128 v[202:205], v149 offset:38912
	ds_read_b128 v[206:209], v149 offset:39936
	global_load_lds_dwordx4 v[226:227], off
	v_lshl_add_u64 v[226:227], s[64:65], 0, v[134:135]
	s_mov_b32 m0, s80
	s_nop 0
	global_load_lds_dwordx4 v[226:227], off
	s_waitcnt vmcnt(8)
	s_waitcnt lgkmcnt(0)
	s_barrier
	s_setprio 3
	v_mfma_f32_16x16x32_bf16 v[126:129], v[140:143], v[178:181], v[126:129]
	v_mfma_f32_16x16x32_bf16 v[122:125], v[154:157], v[178:181], v[122:125]
	v_mfma_f32_16x16x32_bf16 v[110:113], v[140:143], v[186:189], v[110:113]
	v_mfma_f32_16x16x32_bf16 v[106:109], v[154:157], v[186:189], v[106:109]
	v_mfma_f32_16x16x32_bf16 v[94:97], v[140:143], v[194:197], v[94:97]
	v_mfma_f32_16x16x32_bf16 v[90:93], v[154:157], v[194:197], v[90:93]
	v_mfma_f32_16x16x32_bf16 v[78:81], v[140:143], v[202:205], v[78:81]
	v_mfma_f32_16x16x32_bf16 v[74:77], v[154:157], v[202:205], v[74:77]
	v_mfma_f32_16x16x32_bf16 v[126:129], v[150:153], v[182:185], v[126:129]
	v_mfma_f32_16x16x32_bf16 v[122:125], v[158:161], v[182:185], v[122:125]
	v_mfma_f32_16x16x32_bf16 v[110:113], v[150:153], v[190:193], v[110:113]
	v_mfma_f32_16x16x32_bf16 v[106:109], v[158:161], v[190:193], v[106:109]
	v_mfma_f32_16x16x32_bf16 v[94:97], v[150:153], v[198:201], v[94:97]
	v_mfma_f32_16x16x32_bf16 v[90:93], v[158:161], v[198:201], v[90:93]
	v_mfma_f32_16x16x32_bf16 v[78:81], v[150:153], v[206:209], v[78:81]
	v_mfma_f32_16x16x32_bf16 v[74:77], v[158:161], v[206:209], v[74:77]
	v_mfma_f32_16x16x32_bf16 v[118:121], v[162:165], v[178:181], v[118:121]
	v_mfma_f32_16x16x32_bf16 v[114:117], v[170:173], v[178:181], v[114:117]
	v_mfma_f32_16x16x32_bf16 v[102:105], v[162:165], v[186:189], v[102:105]
	v_mfma_f32_16x16x32_bf16 v[98:101], v[170:173], v[186:189], v[98:101]
	v_mfma_f32_16x16x32_bf16 v[86:89], v[162:165], v[194:197], v[86:89]
	v_mfma_f32_16x16x32_bf16 v[82:85], v[170:173], v[194:197], v[82:85]
	v_mfma_f32_16x16x32_bf16 v[70:73], v[162:165], v[202:205], v[70:73]
	v_mfma_f32_16x16x32_bf16 v[66:69], v[170:173], v[202:205], v[66:69]
	v_mfma_f32_16x16x32_bf16 v[118:121], v[166:169], v[182:185], v[118:121]
	v_mfma_f32_16x16x32_bf16 v[114:117], v[174:177], v[182:185], v[114:117]
	v_mfma_f32_16x16x32_bf16 v[102:105], v[166:169], v[190:193], v[102:105]
	v_mfma_f32_16x16x32_bf16 v[98:101], v[174:177], v[190:193], v[98:101]
	v_mfma_f32_16x16x32_bf16 v[86:89], v[166:169], v[198:201], v[86:89]
	v_mfma_f32_16x16x32_bf16 v[82:85], v[174:177], v[198:201], v[82:85]
	v_mfma_f32_16x16x32_bf16 v[70:73], v[166:169], v[206:209], v[70:73]
	v_mfma_f32_16x16x32_bf16 v[66:69], v[174:177], v[206:209], v[66:69]
	s_setprio 0
	s_barrier
	s_add_i32 s64, s87, s73
	v_lshl_add_u64 v[144:145], v[144:145], 0, s[48:49]
	s_mov_b32 m0, s64
	ds_read_b128 v[178:181], v149 offset:49152
	ds_read_b128 v[182:185], v149 offset:50176
	ds_read_b128 v[186:189], v149 offset:51200
	ds_read_b128 v[190:193], v149 offset:52224
	ds_read_b128 v[194:197], v149 offset:53248
	ds_read_b128 v[198:201], v149 offset:54272
	ds_read_b128 v[202:205], v149 offset:55296
	ds_read_b128 v[206:209], v149 offset:56320
	global_load_lds_dwordx4 v[144:145], off
	s_add_i32 m0, s64, 0x2000
	s_add_u32 s64, s68, 0x40080
	v_lshl_add_u64 v[144:145], v[210:211], 0, s[48:49]
	s_addc_u32 s65, s69, 0
	s_add_i32 s68, s88, s73
	global_load_lds_dwordx4 v[144:145], off
	v_lshl_add_u64 v[144:145], s[64:65], 0, v[0:1]
	s_mov_b32 m0, s68
	s_nop 0
	global_load_lds_dwordx4 v[144:145], off
	v_lshl_add_u64 v[144:145], s[64:65], 0, v[134:135]
	s_add_i32 m0, s68, 0x2000
	s_nop 0
	global_load_lds_dwordx4 v[144:145], off
	v_lshl_add_u64 v[144:145], v[220:221], 0, s[48:49]
	s_mov_b32 m0, s81
	s_nop 0
	global_load_lds_dwordx4 v[144:145], off
	v_lshl_add_u64 v[144:145], v[224:225], 0, s[48:49]
	s_mov_b32 m0, s82
	s_nop 0
	global_load_lds_dwordx4 v[144:145], off
	s_waitcnt vmcnt(8)
	s_waitcnt lgkmcnt(0)
	s_barrier
	s_setprio 3
	v_mfma_f32_16x16x32_bf16 v[62:65], v[140:143], v[178:181], v[62:65]
	v_mfma_f32_16x16x32_bf16 v[58:61], v[154:157], v[178:181], v[58:61]
	v_mfma_f32_16x16x32_bf16 v[46:49], v[140:143], v[186:189], v[46:49]
	v_mfma_f32_16x16x32_bf16 v[42:45], v[154:157], v[186:189], v[42:45]
	v_mfma_f32_16x16x32_bf16 v[30:33], v[140:143], v[194:197], v[30:33]
	v_mfma_f32_16x16x32_bf16 v[26:29], v[154:157], v[194:197], v[26:29]
	v_mfma_f32_16x16x32_bf16 v[14:17], v[140:143], v[202:205], v[14:17]
	v_mfma_f32_16x16x32_bf16 v[10:13], v[154:157], v[202:205], v[10:13]
	v_mfma_f32_16x16x32_bf16 v[62:65], v[150:153], v[182:185], v[62:65]
	v_mfma_f32_16x16x32_bf16 v[58:61], v[158:161], v[182:185], v[58:61]
	v_mfma_f32_16x16x32_bf16 v[46:49], v[150:153], v[190:193], v[46:49]
	v_mfma_f32_16x16x32_bf16 v[42:45], v[158:161], v[190:193], v[42:45]
	v_mfma_f32_16x16x32_bf16 v[30:33], v[150:153], v[198:201], v[30:33]
	v_mfma_f32_16x16x32_bf16 v[26:29], v[158:161], v[198:201], v[26:29]
	v_mfma_f32_16x16x32_bf16 v[14:17], v[150:153], v[206:209], v[14:17]
	v_mfma_f32_16x16x32_bf16 v[10:13], v[158:161], v[206:209], v[10:13]
	v_mfma_f32_16x16x32_bf16 v[54:57], v[162:165], v[178:181], v[54:57]
	v_mfma_f32_16x16x32_bf16 v[50:53], v[170:173], v[178:181], v[50:53]
	v_mfma_f32_16x16x32_bf16 v[38:41], v[162:165], v[186:189], v[38:41]
	v_mfma_f32_16x16x32_bf16 v[34:37], v[170:173], v[186:189], v[34:37]
	v_mfma_f32_16x16x32_bf16 v[22:25], v[162:165], v[194:197], v[22:25]
	v_mfma_f32_16x16x32_bf16 v[18:21], v[170:173], v[194:197], v[18:21]
	v_mfma_f32_16x16x32_bf16 v[6:9], v[162:165], v[202:205], v[6:9]
	v_mfma_f32_16x16x32_bf16 v[2:5], v[170:173], v[202:205], v[2:5]
	v_mfma_f32_16x16x32_bf16 v[54:57], v[166:169], v[182:185], v[54:57]
	v_mfma_f32_16x16x32_bf16 v[50:53], v[174:177], v[182:185], v[50:53]
	v_mfma_f32_16x16x32_bf16 v[38:41], v[166:169], v[190:193], v[38:41]
	v_mfma_f32_16x16x32_bf16 v[34:37], v[174:177], v[190:193], v[34:37]
	v_mfma_f32_16x16x32_bf16 v[22:25], v[166:169], v[198:201], v[22:25]
	v_mfma_f32_16x16x32_bf16 v[18:21], v[174:177], v[198:201], v[18:21]
	v_mfma_f32_16x16x32_bf16 v[6:9], v[166:169], v[206:209], v[6:9]
	v_mfma_f32_16x16x32_bf16 v[2:5], v[174:177], v[206:209], v[2:5]
	s_setprio 0
	s_barrier
	s_add_i32 s86, s86, 2
	s_add_u32 s56, s56, 0x100
	s_addc_u32 s57, s57, 0
	s_add_u32 s31, s31, 0x100
	s_addc_u32 s85, s85, 0
	s_cmp_gt_u32 s86, 13
	s_cbranch_scc0 .LBB0_1603
	s_and_b64 vcc, exec, s[10:11]
	s_cbranch_vccz .LBB0_1606
	s_barrier

.LBB0_1670:
	s_ashr_i32 s11, s12, 3
	s_add_i32 s11, s12, s11
	s_and_b64 s[16:17], s[66:67], s[4:5]
	s_add_i32 s11, s11, 1
	s_and_b64 s[16:17], s[16:17], exec
	s_cselect_b32 s12, s11, s12
	s_ashr_i32 s13, s12, 31
	s_lshl_b64 s[16:17], s[12:13], 19
	s_add_u32 s16, s31, s16
	s_addc_u32 s17, s36, s17
	s_and_b64 s[26:27], s[4:5], exec
	s_cselect_b32 s13, s17, s53
	s_cselect_b32 s79, s16, s52
	s_ashr_i32 s11, s10, 31
	s_lshl_b64 s[26:27], s[10:11], 19
	s_add_u32 s26, s37, s26
	s_addc_u32 s27, s60, s27
	s_and_b64 s[64:65], s[4:5], exec
	s_cselect_b32 s11, s27, s57
	s_cselect_b32 s80, s26, s56
	s_add_u32 s52, s52, 0x40080
	s_addc_u32 s53, s53, 0
	s_add_u32 s81, s56, 0x100
	s_addc_u32 s82, s57, 0
	s_mov_b32 s83, -2
	s_add_u32 s56, s52, 0xfffc0080
	s_addc_u32 s57, s53, -1
	s_add_i32 s64, 0, 0x10000
	s_cmp_eq_u32 s83, 12
	s_cselect_b32 s69, s13, s57
	s_cselect_b32 s68, s79, s56
	v_add_u32_e32 v144, s64, v147
	s_cselect_b32 s57, s11, s82
	s_cselect_b32 s56, s80, s81
	s_add_i32 s84, 0, 0x14000
	ds_read_b128 v[150:153], v144
	ds_read_b128 v[154:157], v144 offset:1024
	ds_read_b128 v[158:161], v144 offset:2048
	ds_read_b128 v[162:165], v144 offset:3072
	v_add_u32_e32 v144, s84, v147
	ds_read_b128 v[166:169], v144
	ds_read_b128 v[170:173], v144 offset:1024
	ds_read_b128 v[174:177], v144 offset:2048
	ds_read_b128 v[178:181], v144 offset:3072
	v_lshl_add_u64 v[144:145], s[52:53], 0, v[140:141]
	s_add_i32 m0, s19, 0xc000
	ds_read_b128 v[182:185], v149
	ds_read_b128 v[186:189], v149 offset:1024
	ds_read_b128 v[190:193], v149 offset:2048
	ds_read_b128 v[194:197], v149 offset:3072
	ds_read_b128 v[198:201], v149 offset:4096
	ds_read_b128 v[202:205], v149 offset:5120
	ds_read_b128 v[206:209], v149 offset:6144
	ds_read_b128 v[224:227], v149 offset:7168
	global_load_lds_dwordx4 v[144:145], off
	v_lshl_add_u64 v[144:145], s[52:53], 0, v[142:143]
	s_add_i32 m0, s19, 0xe000
	s_nop 0
	global_load_lds_dwordx4 v[144:145], off
	s_waitcnt vmcnt(8)
	s_waitcnt lgkmcnt(0)
	s_barrier
	s_setprio 3
	v_mfma_f32_16x16x32_bf16 v[126:129], v[150:153], v[182:185], 0
	v_mfma_f32_16x16x32_bf16 v[122:125], v[158:161], v[182:185], 0
	v_mfma_f32_16x16x32_bf16 v[118:121], v[150:153], v[190:193], 0
	v_mfma_f32_16x16x32_bf16 v[110:113], v[158:161], v[190:193], 0
	v_mfma_f32_16x16x32_bf16 v[102:105], v[150:153], v[198:201], 0
	v_mfma_f32_16x16x32_bf16 v[94:97], v[158:161], v[198:201], 0
	v_mfma_f32_16x16x32_bf16 v[86:89], v[150:153], v[206:209], 0
	v_mfma_f32_16x16x32_bf16 v[78:81], v[158:161], v[206:209], 0
	v_mfma_f32_16x16x32_bf16 v[126:129], v[154:157], v[186:189], v[126:129]
	v_mfma_f32_16x16x32_bf16 v[122:125], v[162:165], v[186:189], v[122:125]
	v_mfma_f32_16x16x32_bf16 v[118:121], v[154:157], v[194:197], v[118:121]
	v_mfma_f32_16x16x32_bf16 v[110:113], v[162:165], v[194:197], v[110:113]
	v_mfma_f32_16x16x32_bf16 v[102:105], v[154:157], v[202:205], v[102:105]
	v_mfma_f32_16x16x32_bf16 v[94:97], v[162:165], v[202:205], v[94:97]
	v_mfma_f32_16x16x32_bf16 v[86:89], v[154:157], v[224:227], v[86:89]
	v_mfma_f32_16x16x32_bf16 v[78:81], v[162:165], v[224:227], v[78:81]
	v_mfma_f32_16x16x32_bf16 v[114:117], v[166:169], v[182:185], 0
	v_mfma_f32_16x16x32_bf16 v[106:109], v[174:177], v[182:185], 0
	v_mfma_f32_16x16x32_bf16 v[98:101], v[166:169], v[190:193], 0
	v_mfma_f32_16x16x32_bf16 v[90:93], v[174:177], v[190:193], 0
	v_mfma_f32_16x16x32_bf16 v[82:85], v[166:169], v[198:201], 0
	v_mfma_f32_16x16x32_bf16 v[74:77], v[174:177], v[198:201], 0
	v_mfma_f32_16x16x32_bf16 v[70:73], v[166:169], v[206:209], 0
	v_mfma_f32_16x16x32_bf16 v[66:69], v[174:177], v[206:209], 0
	v_mfma_f32_16x16x32_bf16 v[114:117], v[170:173], v[186:189], v[114:117]
	v_mfma_f32_16x16x32_bf16 v[106:109], v[178:181], v[186:189], v[106:109]
	v_mfma_f32_16x16x32_bf16 v[98:101], v[170:173], v[194:197], v[98:101]
	v_mfma_f32_16x16x32_bf16 v[90:93], v[178:181], v[194:197], v[90:93]
	v_mfma_f32_16x16x32_bf16 v[82:85], v[170:173], v[202:205], v[82:85]
	v_mfma_f32_16x16x32_bf16 v[74:77], v[178:181], v[202:205], v[74:77]
	v_mfma_f32_16x16x32_bf16 v[70:73], v[170:173], v[224:227], v[70:73]
	v_mfma_f32_16x16x32_bf16 v[66:69], v[178:181], v[224:227], v[66:69]
	s_setprio 0
	s_barrier
	s_add_i32 s64, s64, s63
	v_lshl_add_u64 v[144:145], s[56:57], 0, v[0:1]
	s_mov_b32 m0, s64
	ds_read_b128 v[182:185], v149 offset:16384
	ds_read_b128 v[186:189], v149 offset:17408
	ds_read_b128 v[190:193], v149 offset:18432
	ds_read_b128 v[194:197], v149 offset:19456
	ds_read_b128 v[198:201], v149 offset:20480
	ds_read_b128 v[202:205], v149 offset:21504
	ds_read_b128 v[206:209], v149 offset:22528
	ds_read_b128 v[224:227], v149 offset:23552
	global_load_lds_dwordx4 v[144:145], off
	s_add_i32 m0, s64, 0x2000
	s_add_u32 s64, s56, 0x40000
	v_lshl_add_u64 v[210:211], s[56:57], 0, v[134:135]
	s_addc_u32 s65, s57, 0
	s_add_i32 s84, s84, s63
	global_load_lds_dwordx4 v[210:211], off
	v_lshl_add_u64 v[220:221], s[64:65], 0, v[0:1]
	s_mov_b32 m0, s84
	v_lshl_add_u64 v[228:229], s[68:69], 0, v[136:137]
	global_load_lds_dwordx4 v[220:221], off
	v_lshl_add_u64 v[220:221], s[64:65], 0, v[134:135]
	s_add_i32 m0, s84, 0x2000
	s_nop 0
	global_load_lds_dwordx4 v[220:221], off
	v_lshl_add_u64 v[220:221], s[68:69], 0, v[138:139]
	s_mov_b32 m0, s19
	s_nop 0
	global_load_lds_dwordx4 v[220:221], off
	s_mov_b32 m0, s21
	s_nop 0
	global_load_lds_dwordx4 v[228:229], off
	s_waitcnt vmcnt(8)
	s_waitcnt lgkmcnt(0)
	s_barrier
	s_setprio 3
	v_mfma_f32_16x16x32_bf16 v[62:65], v[150:153], v[182:185], 0
	v_mfma_f32_16x16x32_bf16 v[58:61], v[158:161], v[182:185], 0
	v_mfma_f32_16x16x32_bf16 v[54:57], v[150:153], v[190:193], 0
	v_mfma_f32_16x16x32_bf16 v[46:49], v[158:161], v[190:193], 0
	v_mfma_f32_16x16x32_bf16 v[38:41], v[150:153], v[198:201], 0
	v_mfma_f32_16x16x32_bf16 v[30:33], v[158:161], v[198:201], 0
	v_mfma_f32_16x16x32_bf16 v[22:25], v[150:153], v[206:209], 0
	v_mfma_f32_16x16x32_bf16 v[14:17], v[158:161], v[206:209], 0
	v_mfma_f32_16x16x32_bf16 v[62:65], v[154:157], v[186:189], v[62:65]
	v_mfma_f32_16x16x32_bf16 v[58:61], v[162:165], v[186:189], v[58:61]
	v_mfma_f32_16x16x32_bf16 v[54:57], v[154:157], v[194:197], v[54:57]
	v_mfma_f32_16x16x32_bf16 v[46:49], v[162:165], v[194:197], v[46:49]
	v_mfma_f32_16x16x32_bf16 v[38:41], v[154:157], v[202:205], v[38:41]
	v_mfma_f32_16x16x32_bf16 v[30:33], v[162:165], v[202:205], v[30:33]
	v_mfma_f32_16x16x32_bf16 v[22:25], v[154:157], v[224:227], v[22:25]
	v_mfma_f32_16x16x32_bf16 v[14:17], v[162:165], v[224:227], v[14:17]
	v_mfma_f32_16x16x32_bf16 v[50:53], v[166:169], v[182:185], 0
	v_mfma_f32_16x16x32_bf16 v[42:45], v[174:177], v[182:185], 0
	v_mfma_f32_16x16x32_bf16 v[34:37], v[166:169], v[190:193], 0
	v_mfma_f32_16x16x32_bf16 v[26:29], v[174:177], v[190:193], 0
	v_mfma_f32_16x16x32_bf16 v[18:21], v[166:169], v[198:201], 0
	v_mfma_f32_16x16x32_bf16 v[10:13], v[174:177], v[198:201], 0
	v_mfma_f32_16x16x32_bf16 v[6:9], v[166:169], v[206:209], 0
	v_mfma_f32_16x16x32_bf16 v[2:5], v[174:177], v[206:209], 0
	v_mfma_f32_16x16x32_bf16 v[50:53], v[170:173], v[186:189], v[50:53]
	v_mfma_f32_16x16x32_bf16 v[42:45], v[178:181], v[186:189], v[42:45]
	v_mfma_f32_16x16x32_bf16 v[34:37], v[170:173], v[194:197], v[34:37]
	v_mfma_f32_16x16x32_bf16 v[26:29], v[178:181], v[194:197], v[26:29]
	v_mfma_f32_16x16x32_bf16 v[18:21], v[170:173], v[202:205], v[18:21]
	v_mfma_f32_16x16x32_bf16 v[10:13], v[178:181], v[202:205], v[10:13]
	v_mfma_f32_16x16x32_bf16 v[6:9], v[170:173], v[224:227], v[6:9]
	v_mfma_f32_16x16x32_bf16 v[2:5], v[178:181], v[224:227], v[2:5]
	s_setprio 0
	s_barrier
	s_add_i32 s84, 0, 0x18000
	s_add_i32 s85, 0, 0x1c000
	v_add_u32_e32 v162, s84, v147
	v_add_u32_e32 v178, s85, v147
	ds_read_b128 v[150:153], v162
	ds_read_b128 v[154:157], v162 offset:1024
	ds_read_b128 v[158:161], v162 offset:2048
	ds_read_b128 v[162:165], v162 offset:3072
	ds_read_b128 v[166:169], v178
	ds_read_b128 v[170:173], v178 offset:1024
	ds_read_b128 v[174:177], v178 offset:2048
	ds_read_b128 v[178:181], v178 offset:3072
	s_add_u32 s64, s68, 0x40000
	s_addc_u32 s65, s69, 0
	s_mov_b32 m0, s71
	v_lshl_add_u64 v[230:231], s[64:65], 0, v[138:139]
	ds_read_b128 v[182:185], v149 offset:32768
	ds_read_b128 v[186:189], v149 offset:33792
	ds_read_b128 v[190:193], v149 offset:34816
	ds_read_b128 v[194:197], v149 offset:35840
	ds_read_b128 v[198:201], v149 offset:36864
	ds_read_b128 v[202:205], v149 offset:37888
	ds_read_b128 v[206:209], v149 offset:38912
	ds_read_b128 v[224:227], v149 offset:39936
	global_load_lds_dwordx4 v[230:231], off
	v_lshl_add_u64 v[230:231], s[64:65], 0, v[136:137]
	s_mov_b32 m0, s72
	s_nop 0
	global_load_lds_dwordx4 v[230:231], off
	s_waitcnt vmcnt(8)
	s_waitcnt lgkmcnt(0)
	s_barrier
	s_setprio 3
	v_mfma_f32_16x16x32_bf16 v[126:129], v[150:153], v[182:185], v[126:129]
	v_mfma_f32_16x16x32_bf16 v[122:125], v[158:161], v[182:185], v[122:125]
	v_mfma_f32_16x16x32_bf16 v[118:121], v[150:153], v[190:193], v[118:121]
	v_mfma_f32_16x16x32_bf16 v[110:113], v[158:161], v[190:193], v[110:113]
	v_mfma_f32_16x16x32_bf16 v[102:105], v[150:153], v[198:201], v[102:105]
	v_mfma_f32_16x16x32_bf16 v[94:97], v[158:161], v[198:201], v[94:97]
	v_mfma_f32_16x16x32_bf16 v[86:89], v[150:153], v[206:209], v[86:89]
	v_mfma_f32_16x16x32_bf16 v[78:81], v[158:161], v[206:209], v[78:81]
	v_mfma_f32_16x16x32_bf16 v[126:129], v[154:157], v[186:189], v[126:129]
	v_mfma_f32_16x16x32_bf16 v[122:125], v[162:165], v[186:189], v[122:125]
	v_mfma_f32_16x16x32_bf16 v[118:121], v[154:157], v[194:197], v[118:121]
	v_mfma_f32_16x16x32_bf16 v[110:113], v[162:165], v[194:197], v[110:113]
	v_mfma_f32_16x16x32_bf16 v[102:105], v[154:157], v[202:205], v[102:105]
	v_mfma_f32_16x16x32_bf16 v[94:97], v[162:165], v[202:205], v[94:97]
	v_mfma_f32_16x16x32_bf16 v[86:89], v[154:157], v[224:227], v[86:89]
	v_mfma_f32_16x16x32_bf16 v[78:81], v[162:165], v[224:227], v[78:81]
	v_mfma_f32_16x16x32_bf16 v[114:117], v[166:169], v[182:185], v[114:117]
	v_mfma_f32_16x16x32_bf16 v[106:109], v[174:177], v[182:185], v[106:109]
	v_mfma_f32_16x16x32_bf16 v[98:101], v[166:169], v[190:193], v[98:101]
	v_mfma_f32_16x16x32_bf16 v[90:93], v[174:177], v[190:193], v[90:93]
	v_mfma_f32_16x16x32_bf16 v[82:85], v[166:169], v[198:201], v[82:85]
	v_mfma_f32_16x16x32_bf16 v[74:77], v[174:177], v[198:201], v[74:77]
	v_mfma_f32_16x16x32_bf16 v[70:73], v[166:169], v[206:209], v[70:73]
	v_mfma_f32_16x16x32_bf16 v[66:69], v[174:177], v[206:209], v[66:69]
	v_mfma_f32_16x16x32_bf16 v[114:117], v[170:173], v[186:189], v[114:117]
	v_mfma_f32_16x16x32_bf16 v[106:109], v[178:181], v[186:189], v[106:109]
	v_mfma_f32_16x16x32_bf16 v[98:101], v[170:173], v[194:197], v[98:101]
	v_mfma_f32_16x16x32_bf16 v[90:93], v[178:181], v[194:197], v[90:93]
	v_mfma_f32_16x16x32_bf16 v[82:85], v[170:173], v[202:205], v[82:85]
	v_mfma_f32_16x16x32_bf16 v[74:77], v[178:181], v[202:205], v[74:77]
	v_mfma_f32_16x16x32_bf16 v[70:73], v[170:173], v[224:227], v[70:73]
	v_mfma_f32_16x16x32_bf16 v[66:69], v[178:181], v[224:227], v[66:69]
	s_setprio 0
	s_barrier
	s_add_i32 s64, s84, s63
	v_lshl_add_u64 v[144:145], v[144:145], 0, s[48:49]
	s_mov_b32 m0, s64
	ds_read_b128 v[182:185], v149 offset:49152
	ds_read_b128 v[186:189], v149 offset:50176
	ds_read_b128 v[190:193], v149 offset:51200
	ds_read_b128 v[194:197], v149 offset:52224
	ds_read_b128 v[198:201], v149 offset:53248
	ds_read_b128 v[202:205], v149 offset:54272
	ds_read_b128 v[206:209], v149 offset:55296
	ds_read_b128 v[224:227], v149 offset:56320
	global_load_lds_dwordx4 v[144:145], off
	s_add_i32 m0, s64, 0x2000
	s_add_u32 s56, s56, 0x40080
	v_lshl_add_u64 v[144:145], v[210:211], 0, s[48:49]
	s_addc_u32 s57, s57, 0
	s_add_i32 s64, s85, s63
	global_load_lds_dwordx4 v[144:145], off
	v_lshl_add_u64 v[144:145], s[56:57], 0, v[0:1]
	s_mov_b32 m0, s64
	s_nop 0
	global_load_lds_dwordx4 v[144:145], off
	v_lshl_add_u64 v[144:145], s[56:57], 0, v[134:135]
	s_add_i32 m0, s64, 0x2000
	s_nop 0
	global_load_lds_dwordx4 v[144:145], off
	v_lshl_add_u64 v[144:145], v[220:221], 0, s[48:49]
	s_mov_b32 m0, s73
	s_nop 0
	global_load_lds_dwordx4 v[144:145], off
	v_lshl_add_u64 v[144:145], v[228:229], 0, s[48:49]
	s_mov_b32 m0, s74
	s_nop 0
	global_load_lds_dwordx4 v[144:145], off
	s_waitcnt vmcnt(8)
	s_waitcnt lgkmcnt(0)
	s_barrier
	s_setprio 3
	v_mfma_f32_16x16x32_bf16 v[62:65], v[150:153], v[182:185], v[62:65]
	v_mfma_f32_16x16x32_bf16 v[58:61], v[158:161], v[182:185], v[58:61]
	v_mfma_f32_16x16x32_bf16 v[54:57], v[150:153], v[190:193], v[54:57]
	v_mfma_f32_16x16x32_bf16 v[46:49], v[158:161], v[190:193], v[46:49]
	v_mfma_f32_16x16x32_bf16 v[38:41], v[150:153], v[198:201], v[38:41]
	v_mfma_f32_16x16x32_bf16 v[30:33], v[158:161], v[198:201], v[30:33]
	v_mfma_f32_16x16x32_bf16 v[22:25], v[150:153], v[206:209], v[22:25]
	v_mfma_f32_16x16x32_bf16 v[14:17], v[158:161], v[206:209], v[14:17]
	v_mfma_f32_16x16x32_bf16 v[62:65], v[154:157], v[186:189], v[62:65]
	v_mfma_f32_16x16x32_bf16 v[58:61], v[162:165], v[186:189], v[58:61]
	v_mfma_f32_16x16x32_bf16 v[54:57], v[154:157], v[194:197], v[54:57]
	v_mfma_f32_16x16x32_bf16 v[46:49], v[162:165], v[194:197], v[46:49]
	v_mfma_f32_16x16x32_bf16 v[38:41], v[154:157], v[202:205], v[38:41]
	v_mfma_f32_16x16x32_bf16 v[30:33], v[162:165], v[202:205], v[30:33]
	v_mfma_f32_16x16x32_bf16 v[22:25], v[154:157], v[224:227], v[22:25]
	v_mfma_f32_16x16x32_bf16 v[14:17], v[162:165], v[224:227], v[14:17]
	v_mfma_f32_16x16x32_bf16 v[50:53], v[166:169], v[182:185], v[50:53]
	v_mfma_f32_16x16x32_bf16 v[42:45], v[174:177], v[182:185], v[42:45]
	v_mfma_f32_16x16x32_bf16 v[34:37], v[166:169], v[190:193], v[34:37]
	v_mfma_f32_16x16x32_bf16 v[26:29], v[174:177], v[190:193], v[26:29]
	v_mfma_f32_16x16x32_bf16 v[18:21], v[166:169], v[198:201], v[18:21]
	v_mfma_f32_16x16x32_bf16 v[10:13], v[174:177], v[198:201], v[10:13]
	v_mfma_f32_16x16x32_bf16 v[6:9], v[166:169], v[206:209], v[6:9]
	v_mfma_f32_16x16x32_bf16 v[2:5], v[174:177], v[206:209], v[2:5]
	v_mfma_f32_16x16x32_bf16 v[50:53], v[170:173], v[186:189], v[50:53]
	v_mfma_f32_16x16x32_bf16 v[42:45], v[178:181], v[186:189], v[42:45]
	v_mfma_f32_16x16x32_bf16 v[34:37], v[170:173], v[194:197], v[34:37]
	v_mfma_f32_16x16x32_bf16 v[26:29], v[178:181], v[194:197], v[26:29]
	v_mfma_f32_16x16x32_bf16 v[18:21], v[170:173], v[202:205], v[18:21]
	v_mfma_f32_16x16x32_bf16 v[10:13], v[178:181], v[202:205], v[10:13]
	v_mfma_f32_16x16x32_bf16 v[6:9], v[170:173], v[224:227], v[6:9]
	v_mfma_f32_16x16x32_bf16 v[2:5], v[178:181], v[224:227], v[2:5]
	s_setprio 0
	s_barrier
	s_add_i32 s83, s83, 2
	s_add_u32 s52, s52, 0x100
	s_addc_u32 s53, s53, 0
	s_add_u32 s81, s81, 0x100
	s_addc_u32 s82, s82, 0
.LBB0_1671:
	s_add_u32 s56, s52, 0xfffc0080
	s_addc_u32 s57, s53, -1
	s_add_i32 s64, 0, 0x10000
	s_cmp_eq_u32 s83, 12
	s_cselect_b32 s69, s13, s57
	s_cselect_b32 s68, s79, s56
	v_add_u32_e32 v144, s64, v147
	s_cselect_b32 s57, s11, s82
	s_cselect_b32 s56, s80, s81
	s_add_i32 s84, 0, 0x14000
	ds_read_b128 v[150:153], v144
	ds_read_b128 v[154:157], v144 offset:1024
	ds_read_b128 v[158:161], v144 offset:2048
	ds_read_b128 v[162:165], v144 offset:3072
	v_add_u32_e32 v144, s84, v147
	ds_read_b128 v[166:169], v144
	ds_read_b128 v[170:173], v144 offset:1024
	ds_read_b128 v[174:177], v144 offset:2048
	ds_read_b128 v[178:181], v144 offset:3072
	v_lshl_add_u64 v[144:145], s[52:53], 0, v[140:141]
	s_add_i32 m0, s19, 0xc000
	ds_read_b128 v[182:185], v149
	ds_read_b128 v[186:189], v149 offset:1024
	ds_read_b128 v[190:193], v149 offset:2048
	ds_read_b128 v[194:197], v149 offset:3072
	ds_read_b128 v[198:201], v149 offset:4096
	ds_read_b128 v[202:205], v149 offset:5120
	ds_read_b128 v[206:209], v149 offset:6144
	ds_read_b128 v[224:227], v149 offset:7168
	global_load_lds_dwordx4 v[144:145], off
	v_lshl_add_u64 v[144:145], s[52:53], 0, v[142:143]
	s_add_i32 m0, s19, 0xe000
	s_nop 0
	global_load_lds_dwordx4 v[144:145], off
	s_waitcnt vmcnt(8)
	s_waitcnt lgkmcnt(0)
	s_barrier
	s_setprio 3
	v_mfma_f32_16x16x32_bf16 v[126:129], v[150:153], v[182:185], v[126:129]
	v_mfma_f32_16x16x32_bf16 v[122:125], v[158:161], v[182:185], v[122:125]
	v_mfma_f32_16x16x32_bf16 v[118:121], v[150:153], v[190:193], v[118:121]
	v_mfma_f32_16x16x32_bf16 v[110:113], v[158:161], v[190:193], v[110:113]
	v_mfma_f32_16x16x32_bf16 v[102:105], v[150:153], v[198:201], v[102:105]
	v_mfma_f32_16x16x32_bf16 v[94:97], v[158:161], v[198:201], v[94:97]
	v_mfma_f32_16x16x32_bf16 v[86:89], v[150:153], v[206:209], v[86:89]
	v_mfma_f32_16x16x32_bf16 v[78:81], v[158:161], v[206:209], v[78:81]
	v_mfma_f32_16x16x32_bf16 v[126:129], v[154:157], v[186:189], v[126:129]
	v_mfma_f32_16x16x32_bf16 v[122:125], v[162:165], v[186:189], v[122:125]
	v_mfma_f32_16x16x32_bf16 v[118:121], v[154:157], v[194:197], v[118:121]
	v_mfma_f32_16x16x32_bf16 v[110:113], v[162:165], v[194:197], v[110:113]
	v_mfma_f32_16x16x32_bf16 v[102:105], v[154:157], v[202:205], v[102:105]
	v_mfma_f32_16x16x32_bf16 v[94:97], v[162:165], v[202:205], v[94:97]
	v_mfma_f32_16x16x32_bf16 v[86:89], v[154:157], v[224:227], v[86:89]
	v_mfma_f32_16x16x32_bf16 v[78:81], v[162:165], v[224:227], v[78:81]
	v_mfma_f32_16x16x32_bf16 v[114:117], v[166:169], v[182:185], v[114:117]
	v_mfma_f32_16x16x32_bf16 v[106:109], v[174:177], v[182:185], v[106:109]
	v_mfma_f32_16x16x32_bf16 v[98:101], v[166:169], v[190:193], v[98:101]
	v_mfma_f32_16x16x32_bf16 v[90:93], v[174:177], v[190:193], v[90:93]
	v_mfma_f32_16x16x32_bf16 v[82:85], v[166:169], v[198:201], v[82:85]
	v_mfma_f32_16x16x32_bf16 v[74:77], v[174:177], v[198:201], v[74:77]
	v_mfma_f32_16x16x32_bf16 v[70:73], v[166:169], v[206:209], v[70:73]
	v_mfma_f32_16x16x32_bf16 v[66:69], v[174:177], v[206:209], v[66:69]
	v_mfma_f32_16x16x32_bf16 v[114:117], v[170:173], v[186:189], v[114:117]
	v_mfma_f32_16x16x32_bf16 v[106:109], v[178:181], v[186:189], v[106:109]
	v_mfma_f32_16x16x32_bf16 v[98:101], v[170:173], v[194:197], v[98:101]
	v_mfma_f32_16x16x32_bf16 v[90:93], v[178:181], v[194:197], v[90:93]
	v_mfma_f32_16x16x32_bf16 v[82:85], v[170:173], v[202:205], v[82:85]
	v_mfma_f32_16x16x32_bf16 v[74:77], v[178:181], v[202:205], v[74:77]
	v_mfma_f32_16x16x32_bf16 v[70:73], v[170:173], v[224:227], v[70:73]
	v_mfma_f32_16x16x32_bf16 v[66:69], v[178:181], v[224:227], v[66:69]
	s_setprio 0
	s_barrier
	s_add_i32 s64, s64, s63
	v_lshl_add_u64 v[144:145], s[56:57], 0, v[0:1]
	s_mov_b32 m0, s64
	ds_read_b128 v[182:185], v149 offset:16384
	ds_read_b128 v[186:189], v149 offset:17408
	ds_read_b128 v[190:193], v149 offset:18432
	ds_read_b128 v[194:197], v149 offset:19456
	ds_read_b128 v[198:201], v149 offset:20480
	ds_read_b128 v[202:205], v149 offset:21504
	ds_read_b128 v[206:209], v149 offset:22528
	ds_read_b128 v[224:227], v149 offset:23552
	global_load_lds_dwordx4 v[144:145], off
	s_add_i32 m0, s64, 0x2000
	s_add_u32 s64, s56, 0x40000
	v_lshl_add_u64 v[210:211], s[56:57], 0, v[134:135]
	s_addc_u32 s65, s57, 0
	s_add_i32 s84, s84, s63
	global_load_lds_dwordx4 v[210:211], off
	v_lshl_add_u64 v[220:221], s[64:65], 0, v[0:1]
	s_mov_b32 m0, s84
	v_lshl_add_u64 v[228:229], s[68:69], 0, v[136:137]
	global_load_lds_dwordx4 v[220:221], off
	v_lshl_add_u64 v[220:221], s[64:65], 0, v[134:135]
	s_add_i32 m0, s84, 0x2000
	s_nop 0
	global_load_lds_dwordx4 v[220:221], off
	v_lshl_add_u64 v[220:221], s[68:69], 0, v[138:139]
	s_mov_b32 m0, s19
	s_nop 0
	global_load_lds_dwordx4 v[220:221], off
	s_mov_b32 m0, s21
	s_nop 0
	global_load_lds_dwordx4 v[228:229], off
	s_waitcnt vmcnt(8)
	s_waitcnt lgkmcnt(0)
	s_barrier
	s_setprio 3
	v_mfma_f32_16x16x32_bf16 v[62:65], v[150:153], v[182:185], v[62:65]
	v_mfma_f32_16x16x32_bf16 v[58:61], v[158:161], v[182:185], v[58:61]
	v_mfma_f32_16x16x32_bf16 v[54:57], v[150:153], v[190:193], v[54:57]
	v_mfma_f32_16x16x32_bf16 v[46:49], v[158:161], v[190:193], v[46:49]
	v_mfma_f32_16x16x32_bf16 v[38:41], v[150:153], v[198:201], v[38:41]
	v_mfma_f32_16x16x32_bf16 v[30:33], v[158:161], v[198:201], v[30:33]
	v_mfma_f32_16x16x32_bf16 v[22:25], v[150:153], v[206:209], v[22:25]
	v_mfma_f32_16x16x32_bf16 v[14:17], v[158:161], v[206:209], v[14:17]
	v_mfma_f32_16x16x32_bf16 v[62:65], v[154:157], v[186:189], v[62:65]
	v_mfma_f32_16x16x32_bf16 v[58:61], v[162:165], v[186:189], v[58:61]
	v_mfma_f32_16x16x32_bf16 v[54:57], v[154:157], v[194:197], v[54:57]
	v_mfma_f32_16x16x32_bf16 v[46:49], v[162:165], v[194:197], v[46:49]
	v_mfma_f32_16x16x32_bf16 v[38:41], v[154:157], v[202:205], v[38:41]
	v_mfma_f32_16x16x32_bf16 v[30:33], v[162:165], v[202:205], v[30:33]
	v_mfma_f32_16x16x32_bf16 v[22:25], v[154:157], v[224:227], v[22:25]
	v_mfma_f32_16x16x32_bf16 v[14:17], v[162:165], v[224:227], v[14:17]
	v_mfma_f32_16x16x32_bf16 v[50:53], v[166:169], v[182:185], v[50:53]
	v_mfma_f32_16x16x32_bf16 v[42:45], v[174:177], v[182:185], v[42:45]
	v_mfma_f32_16x16x32_bf16 v[34:37], v[166:169], v[190:193], v[34:37]
	v_mfma_f32_16x16x32_bf16 v[26:29], v[174:177], v[190:193], v[26:29]
	v_mfma_f32_16x16x32_bf16 v[18:21], v[166:169], v[198:201], v[18:21]
	v_mfma_f32_16x16x32_bf16 v[10:13], v[174:177], v[198:201], v[10:13]
	v_mfma_f32_16x16x32_bf16 v[6:9], v[166:169], v[206:209], v[6:9]
	v_mfma_f32_16x16x32_bf16 v[2:5], v[174:177], v[206:209], v[2:5]
	v_mfma_f32_16x16x32_bf16 v[50:53], v[170:173], v[186:189], v[50:53]
	v_mfma_f32_16x16x32_bf16 v[42:45], v[178:181], v[186:189], v[42:45]
	v_mfma_f32_16x16x32_bf16 v[34:37], v[170:173], v[194:197], v[34:37]
	v_mfma_f32_16x16x32_bf16 v[26:29], v[178:181], v[194:197], v[26:29]
	v_mfma_f32_16x16x32_bf16 v[18:21], v[170:173], v[202:205], v[18:21]
	v_mfma_f32_16x16x32_bf16 v[10:13], v[178:181], v[202:205], v[10:13]
	v_mfma_f32_16x16x32_bf16 v[6:9], v[170:173], v[224:227], v[6:9]
	v_mfma_f32_16x16x32_bf16 v[2:5], v[178:181], v[224:227], v[2:5]
	s_setprio 0
	s_barrier
	s_add_i32 s84, 0, 0x18000
	s_add_i32 s85, 0, 0x1c000
	v_add_u32_e32 v162, s84, v147
	v_add_u32_e32 v178, s85, v147
	ds_read_b128 v[150:153], v162
	ds_read_b128 v[154:157], v162 offset:1024
	ds_read_b128 v[158:161], v162 offset:2048
	ds_read_b128 v[162:165], v162 offset:3072
	ds_read_b128 v[166:169], v178
	ds_read_b128 v[170:173], v178 offset:1024
	ds_read_b128 v[174:177], v178 offset:2048
	ds_read_b128 v[178:181], v178 offset:3072
	s_add_u32 s64, s68, 0x40000
	s_addc_u32 s65, s69, 0
	s_mov_b32 m0, s71
	v_lshl_add_u64 v[230:231], s[64:65], 0, v[138:139]
	ds_read_b128 v[182:185], v149 offset:32768
	ds_read_b128 v[186:189], v149 offset:33792
	ds_read_b128 v[190:193], v149 offset:34816
	ds_read_b128 v[194:197], v149 offset:35840
	ds_read_b128 v[198:201], v149 offset:36864
	ds_read_b128 v[202:205], v149 offset:37888
	ds_read_b128 v[206:209], v149 offset:38912
	ds_read_b128 v[224:227], v149 offset:39936
	global_load_lds_dwordx4 v[230:231], off
	v_lshl_add_u64 v[230:231], s[64:65], 0, v[136:137]
	s_mov_b32 m0, s72
	s_nop 0
	global_load_lds_dwordx4 v[230:231], off
	s_waitcnt vmcnt(8)
	s_waitcnt lgkmcnt(0)
	s_barrier
	s_setprio 3
	v_mfma_f32_16x16x32_bf16 v[126:129], v[150:153], v[182:185], v[126:129]
	v_mfma_f32_16x16x32_bf16 v[122:125], v[158:161], v[182:185], v[122:125]
	v_mfma_f32_16x16x32_bf16 v[118:121], v[150:153], v[190:193], v[118:121]
	v_mfma_f32_16x16x32_bf16 v[110:113], v[158:161], v[190:193], v[110:113]
	v_mfma_f32_16x16x32_bf16 v[102:105], v[150:153], v[198:201], v[102:105]
	v_mfma_f32_16x16x32_bf16 v[94:97], v[158:161], v[198:201], v[94:97]
	v_mfma_f32_16x16x32_bf16 v[86:89], v[150:153], v[206:209], v[86:89]
	v_mfma_f32_16x16x32_bf16 v[78:81], v[158:161], v[206:209], v[78:81]
	v_mfma_f32_16x16x32_bf16 v[126:129], v[154:157], v[186:189], v[126:129]
	v_mfma_f32_16x16x32_bf16 v[122:125], v[162:165], v[186:189], v[122:125]
	v_mfma_f32_16x16x32_bf16 v[118:121], v[154:157], v[194:197], v[118:121]
	v_mfma_f32_16x16x32_bf16 v[110:113], v[162:165], v[194:197], v[110:113]
	v_mfma_f32_16x16x32_bf16 v[102:105], v[154:157], v[202:205], v[102:105]
	v_mfma_f32_16x16x32_bf16 v[94:97], v[162:165], v[202:205], v[94:97]
	v_mfma_f32_16x16x32_bf16 v[86:89], v[154:157], v[224:227], v[86:89]
	v_mfma_f32_16x16x32_bf16 v[78:81], v[162:165], v[224:227], v[78:81]
	v_mfma_f32_16x16x32_bf16 v[114:117], v[166:169], v[182:185], v[114:117]
	v_mfma_f32_16x16x32_bf16 v[106:109], v[174:177], v[182:185], v[106:109]
	v_mfma_f32_16x16x32_bf16 v[98:101], v[166:169], v[190:193], v[98:101]
	v_mfma_f32_16x16x32_bf16 v[90:93], v[174:177], v[190:193], v[90:93]
	v_mfma_f32_16x16x32_bf16 v[82:85], v[166:169], v[198:201], v[82:85]
	v_mfma_f32_16x16x32_bf16 v[74:77], v[174:177], v[198:201], v[74:77]
	v_mfma_f32_16x16x32_bf16 v[70:73], v[166:169], v[206:209], v[70:73]
	v_mfma_f32_16x16x32_bf16 v[66:69], v[174:177], v[206:209], v[66:69]
	v_mfma_f32_16x16x32_bf16 v[114:117], v[170:173], v[186:189], v[114:117]
	v_mfma_f32_16x16x32_bf16 v[106:109], v[178:181], v[186:189], v[106:109]
	v_mfma_f32_16x16x32_bf16 v[98:101], v[170:173], v[194:197], v[98:101]
	v_mfma_f32_16x16x32_bf16 v[90:93], v[178:181], v[194:197], v[90:93]
	v_mfma_f32_16x16x32_bf16 v[82:85], v[170:173], v[202:205], v[82:85]
	v_mfma_f32_16x16x32_bf16 v[74:77], v[178:181], v[202:205], v[74:77]
	v_mfma_f32_16x16x32_bf16 v[70:73], v[170:173], v[224:227], v[70:73]
	v_mfma_f32_16x16x32_bf16 v[66:69], v[178:181], v[224:227], v[66:69]
	s_setprio 0
	s_barrier
	s_add_i32 s64, s84, s63
	v_lshl_add_u64 v[144:145], v[144:145], 0, s[48:49]
	s_mov_b32 m0, s64
	ds_read_b128 v[182:185], v149 offset:49152
	ds_read_b128 v[186:189], v149 offset:50176
	ds_read_b128 v[190:193], v149 offset:51200
	ds_read_b128 v[194:197], v149 offset:52224
	ds_read_b128 v[198:201], v149 offset:53248
	ds_read_b128 v[202:205], v149 offset:54272
	ds_read_b128 v[206:209], v149 offset:55296
	ds_read_b128 v[224:227], v149 offset:56320
	global_load_lds_dwordx4 v[144:145], off
	s_add_i32 m0, s64, 0x2000
	s_add_u32 s56, s56, 0x40080
	v_lshl_add_u64 v[144:145], v[210:211], 0, s[48:49]
	s_addc_u32 s57, s57, 0
	s_add_i32 s64, s85, s63
	global_load_lds_dwordx4 v[144:145], off
	v_lshl_add_u64 v[144:145], s[56:57], 0, v[0:1]
	s_mov_b32 m0, s64
	s_nop 0
	global_load_lds_dwordx4 v[144:145], off
	v_lshl_add_u64 v[144:145], s[56:57], 0, v[134:135]
	s_add_i32 m0, s64, 0x2000
	s_nop 0
	global_load_lds_dwordx4 v[144:145], off
	v_lshl_add_u64 v[144:145], v[220:221], 0, s[48:49]
	s_mov_b32 m0, s73
	s_nop 0
	global_load_lds_dwordx4 v[144:145], off
	v_lshl_add_u64 v[144:145], v[228:229], 0, s[48:49]
	s_mov_b32 m0, s74
	s_nop 0
	global_load_lds_dwordx4 v[144:145], off
	s_waitcnt vmcnt(8)
	s_waitcnt lgkmcnt(0)
	s_barrier
	s_setprio 3
	v_mfma_f32_16x16x32_bf16 v[62:65], v[150:153], v[182:185], v[62:65]
	v_mfma_f32_16x16x32_bf16 v[58:61], v[158:161], v[182:185], v[58:61]
	v_mfma_f32_16x16x32_bf16 v[54:57], v[150:153], v[190:193], v[54:57]
	v_mfma_f32_16x16x32_bf16 v[46:49], v[158:161], v[190:193], v[46:49]
	v_mfma_f32_16x16x32_bf16 v[38:41], v[150:153], v[198:201], v[38:41]
	v_mfma_f32_16x16x32_bf16 v[30:33], v[158:161], v[198:201], v[30:33]
	v_mfma_f32_16x16x32_bf16 v[22:25], v[150:153], v[206:209], v[22:25]
	v_mfma_f32_16x16x32_bf16 v[14:17], v[158:161], v[206:209], v[14:17]
	v_mfma_f32_16x16x32_bf16 v[62:65], v[154:157], v[186:189], v[62:65]
	v_mfma_f32_16x16x32_bf16 v[58:61], v[162:165], v[186:189], v[58:61]
	v_mfma_f32_16x16x32_bf16 v[54:57], v[154:157], v[194:197], v[54:57]
	v_mfma_f32_16x16x32_bf16 v[46:49], v[162:165], v[194:197], v[46:49]
	v_mfma_f32_16x16x32_bf16 v[38:41], v[154:157], v[202:205], v[38:41]
	v_mfma_f32_16x16x32_bf16 v[30:33], v[162:165], v[202:205], v[30:33]
	v_mfma_f32_16x16x32_bf16 v[22:25], v[154:157], v[224:227], v[22:25]
	v_mfma_f32_16x16x32_bf16 v[14:17], v[162:165], v[224:227], v[14:17]
	v_mfma_f32_16x16x32_bf16 v[50:53], v[166:169], v[182:185], v[50:53]
	v_mfma_f32_16x16x32_bf16 v[42:45], v[174:177], v[182:185], v[42:45]
	v_mfma_f32_16x16x32_bf16 v[34:37], v[166:169], v[190:193], v[34:37]
	v_mfma_f32_16x16x32_bf16 v[26:29], v[174:177], v[190:193], v[26:29]
	v_mfma_f32_16x16x32_bf16 v[18:21], v[166:169], v[198:201], v[18:21]
	v_mfma_f32_16x16x32_bf16 v[10:13], v[174:177], v[198:201], v[10:13]
	v_mfma_f32_16x16x32_bf16 v[6:9], v[166:169], v[206:209], v[6:9]
	v_mfma_f32_16x16x32_bf16 v[2:5], v[174:177], v[206:209], v[2:5]
	v_mfma_f32_16x16x32_bf16 v[50:53], v[170:173], v[186:189], v[50:53]
	v_mfma_f32_16x16x32_bf16 v[42:45], v[178:181], v[186:189], v[42:45]
	v_mfma_f32_16x16x32_bf16 v[34:37], v[170:173], v[194:197], v[34:37]
	v_mfma_f32_16x16x32_bf16 v[26:29], v[178:181], v[194:197], v[26:29]
	v_mfma_f32_16x16x32_bf16 v[18:21], v[170:173], v[202:205], v[18:21]
	v_mfma_f32_16x16x32_bf16 v[10:13], v[178:181], v[202:205], v[10:13]
	v_mfma_f32_16x16x32_bf16 v[6:9], v[170:173], v[224:227], v[6:9]
	v_mfma_f32_16x16x32_bf16 v[2:5], v[178:181], v[224:227], v[2:5]
	s_setprio 0
	s_barrier
	s_add_i32 s83, s83, 2
	s_add_u32 s52, s52, 0x100
	s_addc_u32 s53, s53, 0
	s_add_u32 s81, s81, 0x100
	s_addc_u32 s82, s82, 0
	s_cmp_gt_u32 s83, 13
	s_cbranch_scc0 .LBB0_1671
	s_and_b64 vcc, exec, s[8:9]
	s_cbranch_vccnz .LBB0_1675
	s_cmp_gt_i32 s18, 15
	s_cbranch_scc0 .LBB0_1676
